# v037 + the 54 s_nop 0 pads in the K-loop load segments replaced by moving each LDS-DMA address VALU between the M0 write and the DMA
# baseline (speedup 1.0000x reference)
; #define PG8_STAGE(bufoff, gbase, voff) do { _Pragma("unroll") for (int _i = 0; _i < 2; ++_i) \
;         __builtin_amdgcn_global_load_lds((const unsigned*)((const char*)(gbase) + (voff)[_i]), (LAS unsigned*)(lds + (bufoff) + ldsw + _i * 8192), 16, 0, 0); } while (0)
; #define PG8_LDA(dst, b, h) do { _Pragma("unroll") for (int m = 0; m < 4; ++m) _Pragma("unroll") for (int k = 0; k < 2; ++k) dst[m][k] = *(const LAS bf16x8*)(lds + PG8_SA(b, h) + aoff + m * 2048 + k * 1024); } while (0)
; #define PG8_LDB(dst, b, h) do { _Pragma("unroll") for (int n = 0; n < 2; ++n) _Pragma("unroll") for (int k = 0; k < 2; ++k) dst[n][k] = *(const LAS bf16x8*)(lds + PG8_SB(b, h) + boff + n * 2048 + k * 1024); } while (0)
; #define PG8_MMA(ai, bj, At, Bt) do { __builtin_amdgcn_s_setprio(1); _Pragma("unroll") for (int m = 0; m < 4; ++m) _Pragma("unroll") for (int n = 0; n < 2; ++n) _Pragma("unroll") for (int k = 0; k < 2; ++k) \
;         acc[ai][bj][m][n] = __builtin_amdgcn_mfma_f32_16x16x32_bf16(Bt[n][k], At[m][k], acc[ai][bj][m][n], 0, 0, 0); __builtin_amdgcn_s_setprio(0); } while (0)
; #define PG8_WAIT_V(n) asm volatile("s_waitcnt vmcnt(" #n ")" ::: "memory")
; #define PG8_WAIT_L(n) asm volatile("s_waitcnt lgkmcnt(" #n ")" ::: "memory")
; template <int MODE, class EpiT, class Sched>
; __device__ __forceinline__ void gemm_phase(LAS unsigned char* lds, const Gemm g, const Sched& S, const EpiT& E) {
;     ...
;         for (int t = 0; t < nt; t += 2) {
;             const bool last = (t == nt - 2);
;             const char* a1 = cA + (size_t)(t + 1) * kstep;
;             const char* a2 = last ? nA : cA + (size_t)(t + 2) * kstep; const char* b2 = last ? nB : cB + (size_t)(t + 2) * kstep;
;             const char* a3 = a2 + kstep; const char* b3 = b2 + kstep;
;             PG8_LDB(B0, 0, 0); PG8_SCHED; PG8_LDA(At, 0, 0); PG8_STAGE(PG8_SA(1, 1), a1 + hstep, voffA);
;             PG8_WAIT_L(8); PG8_BAR; PG8_WAIT_L(0); PG8_MMA(0, 0, At, B0); PG8_BAR; PG8_SCHED;
;             PG8_LDB(B1, 0, 1); PG8_STAGE(PG8_SB(0, 0), b2, voffB);
;             PG8_BAR; PG8_WAIT_L(0); PG8_MMA(0, 1, At, B1); PG8_BAR;
;             PG8_LDA(At, 0, 1); PG8_STAGE(PG8_SA(0, 0), a2, voffA);
;             PG8_BAR; PG8_WAIT_L(0); PG8_MMA(1, 0, At, B0); PG8_BAR; PG8_SCHED;
;             PG8_STAGE(PG8_SB(0, 1), b2 + hstep, voffB);
;             PG8_WAIT_V(6); PG8_BAR; PG8_MMA(1, 1, At, B1); PG8_BAR;
.LBB0_115:
	s_add_i32 s58, s52, 2
	s_add_u32 s59, s44, 0x80
	s_addc_u32 s53, s45, 0
	s_add_i32 s91, 0, 0x10000
	v_add_u32_e32 v86, s91, v192
	ds_read_b128 v[70:73], v86
	ds_read_b128 v[74:77], v86 offset:1024
	ds_read_b128 v[82:85], v86 offset:2048
	ds_read_b128 v[86:89], v86 offset:3072
	s_cmp_eq_u32 s57, s52
	s_cselect_b32 s52, s4, s59
	s_cselect_b32 s53, s5, s53
	s_cselect_b32 s75, s47, vcc_hi
	s_cselect_b32 s74, s46, vcc_lo
	v_lshl_add_u64 v[188:189], s[44:45], 0, v[176:177]
	s_add_i32 m0, s20, 0xc000
	ds_read_b128 v[138:141], v194
	ds_read_b128 v[142:145], v194 offset:1024
	ds_read_b128 v[146:149], v194 offset:2048
	ds_read_b128 v[154:157], v194 offset:3072
	ds_read_b128 v[162:165], v194 offset:4096
	ds_read_b128 v[166:169], v194 offset:5120
	ds_read_b128 v[170:173], v194 offset:6144
	ds_read_b128 v[184:187], v194 offset:7168
	global_load_lds_dwordx4 v[188:189], off
	s_add_i32 m0, s20, 0xe000
	v_lshl_add_u64 v[188:189], s[44:45], 0, v[182:183]
	global_load_lds_dwordx4 v[188:189], off
	s_waitcnt lgkmcnt(8)
	s_barrier
	s_waitcnt lgkmcnt(0)
	v_mfma_f32_16x16x32_bf16 v[158:161], v[70:73], v[138:141], v[158:161]
	v_mfma_f32_16x16x32_bf16 v[150:153], v[82:85], v[138:141], v[150:153]
	v_mfma_f32_16x16x32_bf16 v[126:129], v[70:73], v[146:149], v[126:129]
	v_mfma_f32_16x16x32_bf16 v[122:125], v[82:85], v[146:149], v[122:125]
	v_mfma_f32_16x16x32_bf16 v[110:113], v[70:73], v[162:165], v[110:113]
	v_mfma_f32_16x16x32_bf16 v[106:109], v[82:85], v[162:165], v[106:109]
	v_mfma_f32_16x16x32_bf16 v[94:97], v[70:73], v[170:173], v[94:97]
	v_mfma_f32_16x16x32_bf16 v[90:93], v[82:85], v[170:173], v[90:93]
	v_mfma_f32_16x16x32_bf16 v[158:161], v[74:77], v[142:145], v[158:161]
	v_mfma_f32_16x16x32_bf16 v[150:153], v[86:89], v[142:145], v[150:153]
	v_mfma_f32_16x16x32_bf16 v[126:129], v[74:77], v[154:157], v[126:129]
	v_mfma_f32_16x16x32_bf16 v[122:125], v[86:89], v[154:157], v[122:125]
	v_mfma_f32_16x16x32_bf16 v[110:113], v[74:77], v[166:169], v[110:113]
	v_mfma_f32_16x16x32_bf16 v[106:109], v[86:89], v[166:169], v[106:109]
	v_mfma_f32_16x16x32_bf16 v[94:97], v[74:77], v[184:187], v[94:97]
	v_mfma_f32_16x16x32_bf16 v[90:93], v[86:89], v[184:187], v[90:93]
	s_barrier
	s_add_i32 s59, 0, 0x14000
	s_add_i32 s91, s91, s9
	v_add_u32_e32 v195, s59, v192
	v_lshl_add_u64 v[228:229], s[74:75], 0, v[0:1]
	s_mov_b32 m0, s91
	ds_read_b128 v[188:191], v195
	ds_read_b128 v[196:199], v195 offset:1024
	ds_read_b128 v[220:223], v195 offset:2048
	ds_read_b128 v[224:227], v195 offset:3072
	global_load_lds_dwordx4 v[228:229], off
	s_add_i32 m0, s91, 0x2000
	v_lshl_add_u64 v[230:231], s[74:75], 0, v[174:175]
	global_load_lds_dwordx4 v[230:231], off
	s_barrier
	s_waitcnt lgkmcnt(0)
	v_mfma_f32_16x16x32_bf16 v[134:137], v[188:191], v[138:141], v[134:137]
	v_mfma_f32_16x16x32_bf16 v[130:133], v[220:223], v[138:141], v[130:133]
	v_mfma_f32_16x16x32_bf16 v[118:121], v[188:191], v[146:149], v[118:121]
	v_mfma_f32_16x16x32_bf16 v[114:117], v[220:223], v[146:149], v[114:117]
	v_mfma_f32_16x16x32_bf16 v[102:105], v[188:191], v[162:165], v[102:105]
	v_mfma_f32_16x16x32_bf16 v[98:101], v[220:223], v[162:165], v[98:101]
	v_mfma_f32_16x16x32_bf16 v[78:81], v[188:191], v[170:173], v[78:81]
	v_mfma_f32_16x16x32_bf16 v[66:69], v[220:223], v[170:173], v[66:69]
	v_mfma_f32_16x16x32_bf16 v[134:137], v[196:199], v[142:145], v[134:137]
	v_mfma_f32_16x16x32_bf16 v[130:133], v[224:227], v[142:145], v[130:133]
	v_mfma_f32_16x16x32_bf16 v[118:121], v[196:199], v[154:157], v[118:121]
	v_mfma_f32_16x16x32_bf16 v[114:117], v[224:227], v[154:157], v[114:117]
	v_mfma_f32_16x16x32_bf16 v[102:105], v[196:199], v[166:169], v[102:105]
	v_mfma_f32_16x16x32_bf16 v[98:101], v[224:227], v[166:169], v[98:101]
	v_mfma_f32_16x16x32_bf16 v[78:81], v[196:199], v[184:187], v[78:81]
	v_mfma_f32_16x16x32_bf16 v[66:69], v[224:227], v[184:187], v[66:69]
	s_barrier
	s_mov_b32 m0, s20
	v_lshl_add_u64 v[232:233], s[52:53], 0, v[0:1]
	ds_read_b128 v[138:141], v194 offset:16384
	ds_read_b128 v[142:145], v194 offset:17408
	ds_read_b128 v[146:149], v194 offset:18432
	ds_read_b128 v[154:157], v194 offset:19456
	ds_read_b128 v[162:165], v194 offset:20480
	ds_read_b128 v[166:169], v194 offset:21504
	ds_read_b128 v[170:173], v194 offset:22528
	ds_read_b128 v[184:187], v194 offset:23552
	global_load_lds_dwordx4 v[232:233], off
	s_mov_b32 m0, s21
	v_lshl_add_u64 v[234:235], s[52:53], 0, v[174:175]
	global_load_lds_dwordx4 v[234:235], off
	s_barrier
	s_waitcnt lgkmcnt(0)
	v_mfma_f32_16x16x32_bf16 v[62:65], v[70:73], v[138:141], v[62:65]
	v_mfma_f32_16x16x32_bf16 v[58:61], v[82:85], v[138:141], v[58:61]
	v_mfma_f32_16x16x32_bf16 v[46:49], v[70:73], v[146:149], v[46:49]
	v_mfma_f32_16x16x32_bf16 v[42:45], v[82:85], v[146:149], v[42:45]
	v_mfma_f32_16x16x32_bf16 v[30:33], v[70:73], v[162:165], v[30:33]
	v_mfma_f32_16x16x32_bf16 v[26:29], v[82:85], v[162:165], v[26:29]
	v_mfma_f32_16x16x32_bf16 v[14:17], v[70:73], v[170:173], v[14:17]
	v_mfma_f32_16x16x32_bf16 v[10:13], v[82:85], v[170:173], v[10:13]
	v_mfma_f32_16x16x32_bf16 v[62:65], v[74:77], v[142:145], v[62:65]
	v_mfma_f32_16x16x32_bf16 v[58:61], v[86:89], v[142:145], v[58:61]
	v_mfma_f32_16x16x32_bf16 v[46:49], v[74:77], v[154:157], v[46:49]
	v_mfma_f32_16x16x32_bf16 v[42:45], v[86:89], v[154:157], v[42:45]
	v_mfma_f32_16x16x32_bf16 v[30:33], v[74:77], v[166:169], v[30:33]
	v_mfma_f32_16x16x32_bf16 v[26:29], v[86:89], v[166:169], v[26:29]
	v_mfma_f32_16x16x32_bf16 v[14:17], v[74:77], v[184:187], v[14:17]
	v_mfma_f32_16x16x32_bf16 v[10:13], v[86:89], v[184:187], v[10:13]
	s_barrier
; #define PG8_STAGE(bufoff, gbase, voff) do { _Pragma("unroll") for (int _i = 0; _i < 2; ++_i) \
;         __builtin_amdgcn_global_load_lds((const unsigned*)((const char*)(gbase) + (voff)[_i]), (LAS unsigned*)(lds + (bufoff) + ldsw + _i * 8192), 16, 0, 0); } while (0)
; #define PG8_LDA(dst, b, h) do { _Pragma("unroll") for (int m = 0; m < 4; ++m) _Pragma("unroll") for (int k = 0; k < 2; ++k) dst[m][k] = *(const LAS bf16x8*)(lds + PG8_SA(b, h) + aoff + m * 2048 + k * 1024); } while (0)
; #define PG8_LDB(dst, b, h) do { _Pragma("unroll") for (int n = 0; n < 2; ++n) _Pragma("unroll") for (int k = 0; k < 2; ++k) dst[n][k] = *(const LAS bf16x8*)(lds + PG8_SB(b, h) + boff + n * 2048 + k * 1024); } while (0)
; #define PG8_MMA(ai, bj, At, Bt) do { __builtin_amdgcn_s_setprio(1); _Pragma("unroll") for (int m = 0; m < 4; ++m) _Pragma("unroll") for (int n = 0; n < 2; ++n) _Pragma("unroll") for (int k = 0; k < 2; ++k) \
;         acc[ai][bj][m][n] = __builtin_amdgcn_mfma_f32_16x16x32_bf16(Bt[n][k], At[m][k], acc[ai][bj][m][n], 0, 0, 0); __builtin_amdgcn_s_setprio(0); } while (0)
; #define PG8_WAIT_V(n) asm volatile("s_waitcnt vmcnt(" #n ")" ::: "memory")
; #define PG8_WAIT_L(n) asm volatile("s_waitcnt lgkmcnt(" #n ")" ::: "memory")
; #define PG8_BAR __builtin_amdgcn_s_barrier()
; #define PG8_SCHED __builtin_amdgcn_sched_barrier(0)
; template <int MODE, class EpiT, class Sched>
; __device__ __forceinline__ void gemm_phase(LAS unsigned char* lds, const Gemm g, const Sched& S, const EpiT& E) {
;     ...
;             PG8_STAGE(PG8_SB(0, 1), b2 + hstep, voffB);
;             PG8_WAIT_V(6); PG8_BAR; PG8_MMA(1, 1, At, B1); PG8_BAR;
;             PG8_LDB(B0, 1, 0); PG8_SCHED; PG8_LDA(At, 1, 0); PG8_STAGE(PG8_SA(0, 1), a2 + hstep, voffA);
;             PG8_WAIT_L(8); PG8_BAR; PG8_WAIT_L(0); PG8_MMA(0, 0, At, B0); PG8_BAR; PG8_SCHED;
;             PG8_LDB(B1, 1, 1); PG8_STAGE(PG8_SB(1, 0), b3, voffB);
	s_add_u32 s74, s74, s78
	s_addc_u32 s75, s75, 0
	s_add_i32 s59, s59, s9
	v_lshl_add_u64 v[236:237], s[74:75], 0, v[0:1]
	s_mov_b32 m0, s59
	global_load_lds_dwordx4 v[236:237], off
	s_add_i32 m0, s59, 0x2000
	v_lshl_add_u64 v[238:239], s[74:75], 0, v[174:175]
	global_load_lds_dwordx4 v[238:239], off
	s_waitcnt vmcnt(6)
	s_barrier
	v_mfma_f32_16x16x32_bf16 v[54:57], v[188:191], v[138:141], v[54:57]
	v_mfma_f32_16x16x32_bf16 v[50:53], v[220:223], v[138:141], v[50:53]
	v_mfma_f32_16x16x32_bf16 v[38:41], v[188:191], v[146:149], v[38:41]
	v_mfma_f32_16x16x32_bf16 v[34:37], v[220:223], v[146:149], v[34:37]
	v_mfma_f32_16x16x32_bf16 v[22:25], v[188:191], v[162:165], v[22:25]
	v_mfma_f32_16x16x32_bf16 v[18:21], v[220:223], v[162:165], v[18:21]
	v_mfma_f32_16x16x32_bf16 v[6:9], v[188:191], v[170:173], v[6:9]
	v_mfma_f32_16x16x32_bf16 v[2:5], v[220:223], v[170:173], v[2:5]
	v_mfma_f32_16x16x32_bf16 v[54:57], v[196:199], v[142:145], v[54:57]
	v_mfma_f32_16x16x32_bf16 v[50:53], v[224:227], v[142:145], v[50:53]
	v_mfma_f32_16x16x32_bf16 v[38:41], v[196:199], v[154:157], v[38:41]
	v_mfma_f32_16x16x32_bf16 v[34:37], v[224:227], v[154:157], v[34:37]
	v_mfma_f32_16x16x32_bf16 v[22:25], v[196:199], v[166:169], v[22:25]
	v_mfma_f32_16x16x32_bf16 v[18:21], v[224:227], v[166:169], v[18:21]
	v_mfma_f32_16x16x32_bf16 v[6:9], v[196:199], v[184:187], v[6:9]
	v_mfma_f32_16x16x32_bf16 v[2:5], v[224:227], v[184:187], v[2:5]
	s_barrier
	s_add_i32 s59, 0, 0x18000
	v_add_u32_e32 v86, s59, v192
	ds_read_b128 v[70:73], v86
	ds_read_b128 v[74:77], v86 offset:1024
	ds_read_b128 v[82:85], v86 offset:2048
	ds_read_b128 v[86:89], v86 offset:3072
	s_add_u32 s52, s52, s78
	s_addc_u32 s53, s53, 0
	s_mov_b32 m0, s22
	v_lshl_add_u64 v[188:189], s[52:53], 0, v[0:1]
	ds_read_b128 v[138:141], v194 offset:32768
	ds_read_b128 v[142:145], v194 offset:33792
	ds_read_b128 v[146:149], v194 offset:34816
	ds_read_b128 v[154:157], v194 offset:35840
	ds_read_b128 v[162:165], v194 offset:36864
	ds_read_b128 v[166:169], v194 offset:37888
	ds_read_b128 v[170:173], v194 offset:38912
	ds_read_b128 v[184:187], v194 offset:39936
	global_load_lds_dwordx4 v[188:189], off
	s_mov_b32 m0, s23
	v_lshl_add_u64 v[188:189], s[52:53], 0, v[174:175]
	global_load_lds_dwordx4 v[188:189], off
	s_waitcnt lgkmcnt(8)
	s_barrier
	s_waitcnt lgkmcnt(0)
	v_mfma_f32_16x16x32_bf16 v[158:161], v[70:73], v[138:141], v[158:161]
	v_mfma_f32_16x16x32_bf16 v[150:153], v[82:85], v[138:141], v[150:153]
	v_mfma_f32_16x16x32_bf16 v[126:129], v[70:73], v[146:149], v[126:129]
	v_mfma_f32_16x16x32_bf16 v[122:125], v[82:85], v[146:149], v[122:125]
	v_mfma_f32_16x16x32_bf16 v[110:113], v[70:73], v[162:165], v[110:113]
	v_mfma_f32_16x16x32_bf16 v[106:109], v[82:85], v[162:165], v[106:109]
	v_mfma_f32_16x16x32_bf16 v[94:97], v[70:73], v[170:173], v[94:97]
	v_mfma_f32_16x16x32_bf16 v[90:93], v[82:85], v[170:173], v[90:93]
	v_mfma_f32_16x16x32_bf16 v[158:161], v[74:77], v[142:145], v[158:161]
	v_mfma_f32_16x16x32_bf16 v[150:153], v[86:89], v[142:145], v[150:153]
	v_mfma_f32_16x16x32_bf16 v[126:129], v[74:77], v[154:157], v[126:129]
	v_mfma_f32_16x16x32_bf16 v[122:125], v[86:89], v[154:157], v[122:125]
	v_mfma_f32_16x16x32_bf16 v[110:113], v[74:77], v[166:169], v[110:113]
	v_mfma_f32_16x16x32_bf16 v[106:109], v[86:89], v[166:169], v[106:109]
	v_mfma_f32_16x16x32_bf16 v[94:97], v[74:77], v[184:187], v[94:97]
	v_mfma_f32_16x16x32_bf16 v[90:93], v[86:89], v[184:187], v[90:93]
	s_barrier
	s_add_i32 s52, 0, 0x1c000
	s_add_i32 s53, s59, s9
	v_add_u32_e32 v195, s52, v192
	v_lshl_add_u64 v[228:229], v[228:229], 0, s[76:77]
	s_mov_b32 m0, s53
	ds_read_b128 v[188:191], v195
	ds_read_b128 v[196:199], v195 offset:1024
	ds_read_b128 v[220:223], v195 offset:2048
	ds_read_b128 v[224:227], v195 offset:3072
	global_load_lds_dwordx4 v[228:229], off
	s_add_i32 m0, s53, 0x2000
	v_lshl_add_u64 v[228:229], v[230:231], 0, s[76:77]
	global_load_lds_dwordx4 v[228:229], off
	s_barrier
; #define PG8_STAGE(bufoff, gbase, voff) do { _Pragma("unroll") for (int _i = 0; _i < 2; ++_i) \
;         __builtin_amdgcn_global_load_lds((const unsigned*)((const char*)(gbase) + (voff)[_i]), (LAS unsigned*)(lds + (bufoff) + ldsw + _i * 8192), 16, 0, 0); } while (0)
; #define PG8_LDA(dst, b, h) do { _Pragma("unroll") for (int m = 0; m < 4; ++m) _Pragma("unroll") for (int k = 0; k < 2; ++k) dst[m][k] = *(const LAS bf16x8*)(lds + PG8_SA(b, h) + aoff + m * 2048 + k * 1024); } while (0)
; #define PG8_MMA(ai, bj, At, Bt) do { __builtin_amdgcn_s_setprio(1); _Pragma("unroll") for (int m = 0; m < 4; ++m) _Pragma("unroll") for (int n = 0; n < 2; ++n) _Pragma("unroll") for (int k = 0; k < 2; ++k) \
;         acc[ai][bj][m][n] = __builtin_amdgcn_mfma_f32_16x16x32_bf16(Bt[n][k], At[m][k], acc[ai][bj][m][n], 0, 0, 0); __builtin_amdgcn_s_setprio(0); } while (0)
; #define PG8_WAIT_V(n) asm volatile("s_waitcnt vmcnt(" #n ")" ::: "memory")
; #define PG8_WAIT_L(n) asm volatile("s_waitcnt lgkmcnt(" #n ")" ::: "memory")
; #define PG8_BAR __builtin_amdgcn_s_barrier()
; #define PG8_SCHED __builtin_amdgcn_sched_barrier(0)
; template <int MODE, class EpiT, class Sched>
; __device__ __forceinline__ void gemm_phase(LAS unsigned char* lds, const Gemm g, const Sched& S, const EpiT& E) {
;     ...
;             PG8_BAR; PG8_WAIT_L(0); PG8_MMA(0, 1, At, B1); PG8_BAR;
;             PG8_LDA(At, 1, 1); PG8_STAGE(PG8_SA(1, 0), a3, voffA);
;             PG8_BAR; PG8_WAIT_L(0); PG8_MMA(1, 0, At, B0); PG8_BAR; PG8_SCHED;
;             PG8_STAGE(PG8_SB(1, 1), b3 + hstep, voffB);
;             PG8_WAIT_V(6); PG8_BAR; PG8_MMA(1, 1, At, B1); PG8_BAR;
;         }
;         E.template run<MODE>(acc, cur, wr, wc, fr, fq, SC + ui * 256);
;         if (!has_next) break;
	s_waitcnt lgkmcnt(0)
	v_mfma_f32_16x16x32_bf16 v[134:137], v[188:191], v[138:141], v[134:137]
	v_mfma_f32_16x16x32_bf16 v[130:133], v[220:223], v[138:141], v[130:133]
	v_mfma_f32_16x16x32_bf16 v[118:121], v[188:191], v[146:149], v[118:121]
	v_mfma_f32_16x16x32_bf16 v[114:117], v[220:223], v[146:149], v[114:117]
	v_mfma_f32_16x16x32_bf16 v[102:105], v[188:191], v[162:165], v[102:105]
	v_mfma_f32_16x16x32_bf16 v[98:101], v[220:223], v[162:165], v[98:101]
	v_mfma_f32_16x16x32_bf16 v[78:81], v[188:191], v[170:173], v[78:81]
	v_mfma_f32_16x16x32_bf16 v[66:69], v[220:223], v[170:173], v[66:69]
	v_mfma_f32_16x16x32_bf16 v[134:137], v[196:199], v[142:145], v[134:137]
	v_mfma_f32_16x16x32_bf16 v[130:133], v[224:227], v[142:145], v[130:133]
	v_mfma_f32_16x16x32_bf16 v[118:121], v[196:199], v[154:157], v[118:121]
	v_mfma_f32_16x16x32_bf16 v[114:117], v[224:227], v[154:157], v[114:117]
	v_mfma_f32_16x16x32_bf16 v[102:105], v[196:199], v[166:169], v[102:105]
	v_mfma_f32_16x16x32_bf16 v[98:101], v[224:227], v[166:169], v[98:101]
	v_mfma_f32_16x16x32_bf16 v[78:81], v[196:199], v[184:187], v[78:81]
	v_mfma_f32_16x16x32_bf16 v[66:69], v[224:227], v[184:187], v[66:69]
	s_barrier
	s_mov_b32 m0, s51
	v_lshl_add_u64 v[228:229], v[232:233], 0, s[76:77]
	ds_read_b128 v[138:141], v194 offset:49152
	ds_read_b128 v[142:145], v194 offset:50176
	ds_read_b128 v[146:149], v194 offset:51200
	ds_read_b128 v[154:157], v194 offset:52224
	ds_read_b128 v[162:165], v194 offset:53248
	ds_read_b128 v[166:169], v194 offset:54272
	ds_read_b128 v[170:173], v194 offset:55296
	ds_read_b128 v[184:187], v194 offset:56320
	global_load_lds_dwordx4 v[228:229], off
	s_mov_b32 m0, s56
	v_lshl_add_u64 v[228:229], v[234:235], 0, s[76:77]
	global_load_lds_dwordx4 v[228:229], off
	s_barrier
	s_waitcnt lgkmcnt(0)
	v_mfma_f32_16x16x32_bf16 v[62:65], v[70:73], v[138:141], v[62:65]
	v_mfma_f32_16x16x32_bf16 v[58:61], v[82:85], v[138:141], v[58:61]
	v_mfma_f32_16x16x32_bf16 v[46:49], v[70:73], v[146:149], v[46:49]
	v_mfma_f32_16x16x32_bf16 v[42:45], v[82:85], v[146:149], v[42:45]
	v_mfma_f32_16x16x32_bf16 v[30:33], v[70:73], v[162:165], v[30:33]
	v_mfma_f32_16x16x32_bf16 v[26:29], v[82:85], v[162:165], v[26:29]
	v_mfma_f32_16x16x32_bf16 v[14:17], v[70:73], v[170:173], v[14:17]
	v_mfma_f32_16x16x32_bf16 v[10:13], v[82:85], v[170:173], v[10:13]
	v_mfma_f32_16x16x32_bf16 v[62:65], v[74:77], v[142:145], v[62:65]
	v_mfma_f32_16x16x32_bf16 v[58:61], v[86:89], v[142:145], v[58:61]
	v_mfma_f32_16x16x32_bf16 v[46:49], v[74:77], v[154:157], v[46:49]
	v_mfma_f32_16x16x32_bf16 v[42:45], v[86:89], v[154:157], v[42:45]
	v_mfma_f32_16x16x32_bf16 v[30:33], v[74:77], v[166:169], v[30:33]
	v_mfma_f32_16x16x32_bf16 v[26:29], v[86:89], v[166:169], v[26:29]
	v_mfma_f32_16x16x32_bf16 v[14:17], v[74:77], v[184:187], v[14:17]
	v_mfma_f32_16x16x32_bf16 v[10:13], v[86:89], v[184:187], v[10:13]
	s_barrier
	s_add_i32 s52, s52, s9
	s_mov_b32 m0, s52
	v_lshl_add_u64 v[70:71], v[236:237], 0, s[76:77]
	global_load_lds_dwordx4 v[70:71], off
	s_add_i32 m0, s52, 0x2000
	v_lshl_add_u64 v[70:71], v[238:239], 0, s[76:77]
	global_load_lds_dwordx4 v[70:71], off
	s_waitcnt vmcnt(6)
	s_barrier
	v_mfma_f32_16x16x32_bf16 v[54:57], v[188:191], v[138:141], v[54:57]
	v_mfma_f32_16x16x32_bf16 v[50:53], v[220:223], v[138:141], v[50:53]
	v_mfma_f32_16x16x32_bf16 v[38:41], v[188:191], v[146:149], v[38:41]
	v_mfma_f32_16x16x32_bf16 v[34:37], v[220:223], v[146:149], v[34:37]
	v_mfma_f32_16x16x32_bf16 v[22:25], v[188:191], v[162:165], v[22:25]
	v_mfma_f32_16x16x32_bf16 v[18:21], v[220:223], v[162:165], v[18:21]
	v_mfma_f32_16x16x32_bf16 v[6:9], v[188:191], v[170:173], v[6:9]
	v_mfma_f32_16x16x32_bf16 v[2:5], v[220:223], v[170:173], v[2:5]
	v_mfma_f32_16x16x32_bf16 v[54:57], v[196:199], v[142:145], v[54:57]
	v_mfma_f32_16x16x32_bf16 v[50:53], v[224:227], v[142:145], v[50:53]
	v_mfma_f32_16x16x32_bf16 v[38:41], v[196:199], v[154:157], v[38:41]
	v_mfma_f32_16x16x32_bf16 v[34:37], v[224:227], v[154:157], v[34:37]
	v_mfma_f32_16x16x32_bf16 v[22:25], v[196:199], v[166:169], v[22:25]
	v_mfma_f32_16x16x32_bf16 v[18:21], v[224:227], v[166:169], v[18:21]
	v_mfma_f32_16x16x32_bf16 v[6:9], v[196:199], v[184:187], v[6:9]
	v_mfma_f32_16x16x32_bf16 v[2:5], v[224:227], v[184:187], v[2:5]
	s_barrier
	s_add_u32 s44, s44, 0x100
	s_addc_u32 s45, s45, 0
	s_add_u32 vcc_lo, vcc_lo, 0x100
	s_addc_u32 vcc_hi, vcc_hi, 0
	s_cmp_ge_u32 s58, s50
	s_mov_b32 s52, s58
	s_cbranch_scc0 .LBB0_115
	v_lshl_or_b32 v184, s24, 8, v193
	v_ashrrev_i32_e32 v185, 31, v184
	v_mov_b32_e32 v74, 0
	v_cndmask_b32_e64 v70, 0, 1, s[68:69]
	v_lshl_add_u64 v[138:139], v[184:185], 2, s[12:13]
	v_cmp_ne_u32_e64 s[44:45], 1, v70
	s_andn2_b64 vcc, exec, s[68:69]
	v_mov_b32_e32 v86, 0
	v_mov_b32_e32 v87, v74
	v_mov_b32_e32 v186, 0
	v_mov_b32_e32 v187, v74
	s_cbranch_vccnz .LBB0_118
	global_load_dwordx4 v[86:89], v[138:139], off
	s_waitcnt vmcnt(0)
	v_mov_b32_e32 v186, v88
	v_mov_b32_e32 v187, v89

; #define PG8_STAGE(bufoff, gbase, voff) do { _Pragma("unroll") for (int _i = 0; _i < 2; ++_i) \
;         __builtin_amdgcn_global_load_lds((const unsigned*)((const char*)(gbase) + (voff)[_i]), (LAS unsigned*)(lds + (bufoff) + ldsw + _i * 8192), 16, 0, 0); } while (0)
; #define PG8_LDA(dst, b, h) do { _Pragma("unroll") for (int m = 0; m < 4; ++m) _Pragma("unroll") for (int k = 0; k < 2; ++k) dst[m][k] = *(const LAS bf16x8*)(lds + PG8_SA(b, h) + aoff + m * 2048 + k * 1024); } while (0)
; #define PG8_LDB(dst, b, h) do { _Pragma("unroll") for (int n = 0; n < 2; ++n) _Pragma("unroll") for (int k = 0; k < 2; ++k) dst[n][k] = *(const LAS bf16x8*)(lds + PG8_SB(b, h) + boff + n * 2048 + k * 1024); } while (0)
; #define PG8_MMA(ai, bj, At, Bt) do { __builtin_amdgcn_s_setprio(1); _Pragma("unroll") for (int m = 0; m < 4; ++m) _Pragma("unroll") for (int n = 0; n < 2; ++n) _Pragma("unroll") for (int k = 0; k < 2; ++k) \
;         acc[ai][bj][m][n] = __builtin_amdgcn_mfma_f32_16x16x32_bf16(Bt[n][k], At[m][k], acc[ai][bj][m][n], 0, 0, 0); __builtin_amdgcn_s_setprio(0); } while (0)
; #define PG8_WAIT_L(n) asm volatile("s_waitcnt lgkmcnt(" #n ")" ::: "memory")
; #define PG8_BAR __builtin_amdgcn_s_barrier()
; #define PG8_SCHED __builtin_amdgcn_sched_barrier(0)
; template <int MODE, class EpiT, class Sched>
; __device__ __forceinline__ void gemm_phase(LAS unsigned char* lds, const Gemm g, const Sched& S, const EpiT& E) {
;     ...
;             PG8_LDB(B0, 0, 0); PG8_SCHED; PG8_LDA(At, 0, 0); PG8_STAGE(PG8_SA(1, 1), a1 + hstep, voffA);
;             PG8_WAIT_L(8); PG8_BAR; PG8_WAIT_L(0); PG8_MMA(0, 0, At, B0); PG8_BAR; PG8_SCHED;
;             PG8_LDB(B1, 0, 1); PG8_STAGE(PG8_SB(0, 0), b2, voffB);
;             PG8_BAR; PG8_WAIT_L(0); PG8_MMA(0, 1, At, B1); PG8_BAR;
;             PG8_LDA(At, 0, 1); PG8_STAGE(PG8_SA(0, 0), a2, voffA);
;             PG8_BAR; PG8_WAIT_L(0); PG8_MMA(1, 0, At, B0); PG8_BAR; PG8_SCHED;
.LBB0_159:
	s_add_i32 s89, s30, 2
	s_add_u32 s44, s4, 0x80
	s_addc_u32 s45, s5, 0
	s_add_i32 s58, 0, 0x10000
	v_add_u32_e32 v142, s58, v220
	ds_read_b128 v[130:133], v142
	ds_read_b128 v[134:137], v142 offset:1024
	ds_read_b128 v[138:141], v142 offset:2048
	ds_read_b128 v[142:145], v142 offset:3072
	s_cmp_eq_u32 s61, s30
	s_cselect_b32 s45, s79, s45
	s_cselect_b32 s44, s78, s44
	s_cselect_b32 s53, s47, s24
	s_cselect_b32 s52, s46, s23
	v_lshl_add_u64 v[188:189], s[4:5], 0, v[184:185]
	s_add_i32 m0, s69, 0xc000
	ds_read_b128 v[146:149], v223
	ds_read_b128 v[150:153], v223 offset:1024
	ds_read_b128 v[154:157], v223 offset:2048
	ds_read_b128 v[158:161], v223 offset:3072
	ds_read_b128 v[162:165], v223 offset:4096
	ds_read_b128 v[166:169], v223 offset:5120
	ds_read_b128 v[170:173], v223 offset:6144
	ds_read_b128 v[174:177], v223 offset:7168
	global_load_lds_dwordx4 v[188:189], off
	s_add_i32 m0, s69, 0xe000
	v_lshl_add_u64 v[188:189], s[4:5], 0, v[186:187]
	global_load_lds_dwordx4 v[188:189], off
	s_waitcnt lgkmcnt(8)
	s_barrier
	s_waitcnt lgkmcnt(0)
	v_mfma_f32_16x16x32_bf16 v[126:129], v[130:133], v[146:149], v[126:129]
	v_mfma_f32_16x16x32_bf16 v[122:125], v[138:141], v[146:149], v[122:125]
	v_mfma_f32_16x16x32_bf16 v[110:113], v[130:133], v[154:157], v[110:113]
	v_mfma_f32_16x16x32_bf16 v[106:109], v[138:141], v[154:157], v[106:109]
	v_mfma_f32_16x16x32_bf16 v[94:97], v[130:133], v[162:165], v[94:97]
	v_mfma_f32_16x16x32_bf16 v[90:93], v[138:141], v[162:165], v[90:93]
	v_mfma_f32_16x16x32_bf16 v[78:81], v[130:133], v[170:173], v[78:81]
	v_mfma_f32_16x16x32_bf16 v[74:77], v[138:141], v[170:173], v[74:77]
	v_mfma_f32_16x16x32_bf16 v[126:129], v[134:137], v[150:153], v[126:129]
	v_mfma_f32_16x16x32_bf16 v[122:125], v[142:145], v[150:153], v[122:125]
	v_mfma_f32_16x16x32_bf16 v[110:113], v[134:137], v[158:161], v[110:113]
	v_mfma_f32_16x16x32_bf16 v[106:109], v[142:145], v[158:161], v[106:109]
	v_mfma_f32_16x16x32_bf16 v[94:97], v[134:137], v[166:169], v[94:97]
	v_mfma_f32_16x16x32_bf16 v[90:93], v[142:145], v[166:169], v[90:93]
	v_mfma_f32_16x16x32_bf16 v[78:81], v[134:137], v[174:177], v[78:81]
	v_mfma_f32_16x16x32_bf16 v[74:77], v[142:145], v[174:177], v[74:77]
	s_barrier
	s_add_i32 s30, 0, 0x14000
	s_add_i32 s58, s58, s68
	v_add_u32_e32 v200, s30, v220
	v_lshl_add_u64 v[228:229], s[52:53], 0, v[0:1]
	s_mov_b32 m0, s58
	ds_read_b128 v[188:191], v200
	ds_read_b128 v[192:195], v200 offset:1024
	ds_read_b128 v[196:199], v200 offset:2048
	ds_read_b128 v[224:227], v200 offset:3072
	global_load_lds_dwordx4 v[228:229], off
	s_add_i32 m0, s58, 0x2000
	v_lshl_add_u64 v[230:231], s[52:53], 0, v[182:183]
	global_load_lds_dwordx4 v[230:231], off
	s_barrier
	s_waitcnt lgkmcnt(0)
	v_mfma_f32_16x16x32_bf16 v[118:121], v[188:191], v[146:149], v[118:121]
	v_mfma_f32_16x16x32_bf16 v[114:117], v[196:199], v[146:149], v[114:117]
	v_mfma_f32_16x16x32_bf16 v[102:105], v[188:191], v[154:157], v[102:105]
	v_mfma_f32_16x16x32_bf16 v[98:101], v[196:199], v[154:157], v[98:101]
	v_mfma_f32_16x16x32_bf16 v[86:89], v[188:191], v[162:165], v[86:89]
	v_mfma_f32_16x16x32_bf16 v[82:85], v[196:199], v[162:165], v[82:85]
	v_mfma_f32_16x16x32_bf16 v[70:73], v[188:191], v[170:173], v[70:73]
	v_mfma_f32_16x16x32_bf16 v[66:69], v[196:199], v[170:173], v[66:69]
	v_mfma_f32_16x16x32_bf16 v[118:121], v[192:195], v[150:153], v[118:121]
	v_mfma_f32_16x16x32_bf16 v[114:117], v[224:227], v[150:153], v[114:117]
	v_mfma_f32_16x16x32_bf16 v[102:105], v[192:195], v[158:161], v[102:105]
	v_mfma_f32_16x16x32_bf16 v[98:101], v[224:227], v[158:161], v[98:101]
	v_mfma_f32_16x16x32_bf16 v[86:89], v[192:195], v[166:169], v[86:89]
	v_mfma_f32_16x16x32_bf16 v[82:85], v[224:227], v[166:169], v[82:85]
	v_mfma_f32_16x16x32_bf16 v[70:73], v[192:195], v[174:177], v[70:73]
	v_mfma_f32_16x16x32_bf16 v[66:69], v[224:227], v[174:177], v[66:69]
	s_barrier
	s_mov_b32 m0, s69
	v_lshl_add_u64 v[232:233], s[44:45], 0, v[0:1]
	ds_read_b128 v[146:149], v223 offset:16384
	ds_read_b128 v[150:153], v223 offset:17408
	ds_read_b128 v[154:157], v223 offset:18432
	ds_read_b128 v[158:161], v223 offset:19456
	ds_read_b128 v[162:165], v223 offset:20480
	ds_read_b128 v[166:169], v223 offset:21504
	ds_read_b128 v[170:173], v223 offset:22528
	ds_read_b128 v[174:177], v223 offset:23552
	global_load_lds_dwordx4 v[232:233], off
	s_mov_b32 m0, s74
	v_lshl_add_u64 v[234:235], s[44:45], 0, v[182:183]
	global_load_lds_dwordx4 v[234:235], off
	s_barrier
	s_waitcnt lgkmcnt(0)
	v_mfma_f32_16x16x32_bf16 v[62:65], v[130:133], v[146:149], v[62:65]
	v_mfma_f32_16x16x32_bf16 v[58:61], v[138:141], v[146:149], v[58:61]
	v_mfma_f32_16x16x32_bf16 v[46:49], v[130:133], v[154:157], v[46:49]
	v_mfma_f32_16x16x32_bf16 v[42:45], v[138:141], v[154:157], v[42:45]
	v_mfma_f32_16x16x32_bf16 v[30:33], v[130:133], v[162:165], v[30:33]
	v_mfma_f32_16x16x32_bf16 v[26:29], v[138:141], v[162:165], v[26:29]
	v_mfma_f32_16x16x32_bf16 v[14:17], v[130:133], v[170:173], v[14:17]
	v_mfma_f32_16x16x32_bf16 v[10:13], v[138:141], v[170:173], v[10:13]
	v_mfma_f32_16x16x32_bf16 v[62:65], v[134:137], v[150:153], v[62:65]
	v_mfma_f32_16x16x32_bf16 v[58:61], v[142:145], v[150:153], v[58:61]
	v_mfma_f32_16x16x32_bf16 v[46:49], v[134:137], v[158:161], v[46:49]
	v_mfma_f32_16x16x32_bf16 v[42:45], v[142:145], v[158:161], v[42:45]
	v_mfma_f32_16x16x32_bf16 v[30:33], v[134:137], v[166:169], v[30:33]
	v_mfma_f32_16x16x32_bf16 v[26:29], v[142:145], v[166:169], v[26:29]
	v_mfma_f32_16x16x32_bf16 v[14:17], v[134:137], v[174:177], v[14:17]
	v_mfma_f32_16x16x32_bf16 v[10:13], v[142:145], v[174:177], v[10:13]
	s_barrier
; #define PG8_STAGE(bufoff, gbase, voff) do { _Pragma("unroll") for (int _i = 0; _i < 2; ++_i) \
;         __builtin_amdgcn_global_load_lds((const unsigned*)((const char*)(gbase) + (voff)[_i]), (LAS unsigned*)(lds + (bufoff) + ldsw + _i * 8192), 16, 0, 0); } while (0)
; #define PG8_LDA(dst, b, h) do { _Pragma("unroll") for (int m = 0; m < 4; ++m) _Pragma("unroll") for (int k = 0; k < 2; ++k) dst[m][k] = *(const LAS bf16x8*)(lds + PG8_SA(b, h) + aoff + m * 2048 + k * 1024); } while (0)
; #define PG8_LDB(dst, b, h) do { _Pragma("unroll") for (int n = 0; n < 2; ++n) _Pragma("unroll") for (int k = 0; k < 2; ++k) dst[n][k] = *(const LAS bf16x8*)(lds + PG8_SB(b, h) + boff + n * 2048 + k * 1024); } while (0)
; #define PG8_MMA(ai, bj, At, Bt) do { __builtin_amdgcn_s_setprio(1); _Pragma("unroll") for (int m = 0; m < 4; ++m) _Pragma("unroll") for (int n = 0; n < 2; ++n) _Pragma("unroll") for (int k = 0; k < 2; ++k) \
;         acc[ai][bj][m][n] = __builtin_amdgcn_mfma_f32_16x16x32_bf16(Bt[n][k], At[m][k], acc[ai][bj][m][n], 0, 0, 0); __builtin_amdgcn_s_setprio(0); } while (0)
; #define PG8_WAIT_V(n) asm volatile("s_waitcnt vmcnt(" #n ")" ::: "memory")
; #define PG8_WAIT_L(n) asm volatile("s_waitcnt lgkmcnt(" #n ")" ::: "memory")
; #define PG8_BAR __builtin_amdgcn_s_barrier()
; #define PG8_SCHED __builtin_amdgcn_sched_barrier(0)
; template <int MODE, class EpiT, class Sched>
; __device__ __forceinline__ void gemm_phase(LAS unsigned char* lds, const Gemm g, const Sched& S, const EpiT& E) {
;     ...
;             PG8_STAGE(PG8_SB(0, 1), b2 + hstep, voffB);
;             PG8_WAIT_V(6); PG8_BAR; PG8_MMA(1, 1, At, B1); PG8_BAR;
;             PG8_LDB(B0, 1, 0); PG8_SCHED; PG8_LDA(At, 1, 0); PG8_STAGE(PG8_SA(0, 1), a2 + hstep, voffA);
;             PG8_WAIT_L(8); PG8_BAR; PG8_WAIT_L(0); PG8_MMA(0, 0, At, B0); PG8_BAR; PG8_SCHED;
;             PG8_LDB(B1, 1, 1); PG8_STAGE(PG8_SB(1, 0), b3, voffB);
;             PG8_BAR; PG8_WAIT_L(0); PG8_MMA(0, 1, At, B1); PG8_BAR;
;             PG8_LDA(At, 1, 1); PG8_STAGE(PG8_SA(1, 0), a3, voffA);
;             PG8_BAR; PG8_WAIT_L(0); PG8_MMA(1, 0, At, B0); PG8_BAR; PG8_SCHED;
	s_add_u32 s52, s52, s38
	s_addc_u32 s53, s53, 0
	s_add_i32 s30, s30, s68
	v_lshl_add_u64 v[236:237], s[52:53], 0, v[0:1]
	s_mov_b32 m0, s30
	global_load_lds_dwordx4 v[236:237], off
	s_add_i32 m0, s30, 0x2000
	v_lshl_add_u64 v[238:239], s[52:53], 0, v[182:183]
	global_load_lds_dwordx4 v[238:239], off
	s_waitcnt vmcnt(6)
	s_barrier
	v_mfma_f32_16x16x32_bf16 v[54:57], v[188:191], v[146:149], v[54:57]
	v_mfma_f32_16x16x32_bf16 v[50:53], v[196:199], v[146:149], v[50:53]
	v_mfma_f32_16x16x32_bf16 v[38:41], v[188:191], v[154:157], v[38:41]
	v_mfma_f32_16x16x32_bf16 v[34:37], v[196:199], v[154:157], v[34:37]
	v_mfma_f32_16x16x32_bf16 v[22:25], v[188:191], v[162:165], v[22:25]
	v_mfma_f32_16x16x32_bf16 v[18:21], v[196:199], v[162:165], v[18:21]
	v_mfma_f32_16x16x32_bf16 v[6:9], v[188:191], v[170:173], v[6:9]
	v_mfma_f32_16x16x32_bf16 v[2:5], v[196:199], v[170:173], v[2:5]
	v_mfma_f32_16x16x32_bf16 v[54:57], v[192:195], v[150:153], v[54:57]
	v_mfma_f32_16x16x32_bf16 v[50:53], v[224:227], v[150:153], v[50:53]
	v_mfma_f32_16x16x32_bf16 v[38:41], v[192:195], v[158:161], v[38:41]
	v_mfma_f32_16x16x32_bf16 v[34:37], v[224:227], v[158:161], v[34:37]
	v_mfma_f32_16x16x32_bf16 v[22:25], v[192:195], v[166:169], v[22:25]
	v_mfma_f32_16x16x32_bf16 v[18:21], v[224:227], v[166:169], v[18:21]
	v_mfma_f32_16x16x32_bf16 v[6:9], v[192:195], v[174:177], v[6:9]
	v_mfma_f32_16x16x32_bf16 v[2:5], v[224:227], v[174:177], v[2:5]
	s_barrier
	s_add_i32 s30, 0, 0x18000
	v_add_u32_e32 v142, s30, v220
	ds_read_b128 v[130:133], v142
	ds_read_b128 v[134:137], v142 offset:1024
	ds_read_b128 v[138:141], v142 offset:2048
	ds_read_b128 v[142:145], v142 offset:3072
	s_add_u32 s44, s44, s38
	s_addc_u32 s45, s45, 0
	s_mov_b32 m0, s75
	v_lshl_add_u64 v[188:189], s[44:45], 0, v[0:1]
	ds_read_b128 v[146:149], v223 offset:32768
	ds_read_b128 v[150:153], v223 offset:33792
	ds_read_b128 v[154:157], v223 offset:34816
	ds_read_b128 v[158:161], v223 offset:35840
	ds_read_b128 v[162:165], v223 offset:36864
	ds_read_b128 v[166:169], v223 offset:37888
	ds_read_b128 v[170:173], v223 offset:38912
	ds_read_b128 v[174:177], v223 offset:39936
	global_load_lds_dwordx4 v[188:189], off
	s_mov_b32 m0, s9
	v_lshl_add_u64 v[188:189], s[44:45], 0, v[182:183]
	global_load_lds_dwordx4 v[188:189], off
	s_waitcnt lgkmcnt(8)
	s_barrier
	s_waitcnt lgkmcnt(0)
	v_mfma_f32_16x16x32_bf16 v[126:129], v[130:133], v[146:149], v[126:129]
	v_mfma_f32_16x16x32_bf16 v[122:125], v[138:141], v[146:149], v[122:125]
	v_mfma_f32_16x16x32_bf16 v[110:113], v[130:133], v[154:157], v[110:113]
	v_mfma_f32_16x16x32_bf16 v[106:109], v[138:141], v[154:157], v[106:109]
	v_mfma_f32_16x16x32_bf16 v[94:97], v[130:133], v[162:165], v[94:97]
	v_mfma_f32_16x16x32_bf16 v[90:93], v[138:141], v[162:165], v[90:93]
	v_mfma_f32_16x16x32_bf16 v[78:81], v[130:133], v[170:173], v[78:81]
	v_mfma_f32_16x16x32_bf16 v[74:77], v[138:141], v[170:173], v[74:77]
	v_mfma_f32_16x16x32_bf16 v[126:129], v[134:137], v[150:153], v[126:129]
	v_mfma_f32_16x16x32_bf16 v[122:125], v[142:145], v[150:153], v[122:125]
	v_mfma_f32_16x16x32_bf16 v[110:113], v[134:137], v[158:161], v[110:113]
	v_mfma_f32_16x16x32_bf16 v[106:109], v[142:145], v[158:161], v[106:109]
	v_mfma_f32_16x16x32_bf16 v[94:97], v[134:137], v[166:169], v[94:97]
	v_mfma_f32_16x16x32_bf16 v[90:93], v[142:145], v[166:169], v[90:93]
	v_mfma_f32_16x16x32_bf16 v[78:81], v[134:137], v[174:177], v[78:81]
	v_mfma_f32_16x16x32_bf16 v[74:77], v[142:145], v[174:177], v[74:77]
	s_barrier
	s_add_i32 s44, 0, 0x1c000
	s_add_i32 s30, s30, s68
	v_add_u32_e32 v200, s44, v220
	v_lshl_add_u64 v[228:229], v[228:229], 0, s[76:77]
	s_mov_b32 m0, s30
	ds_read_b128 v[188:191], v200
	ds_read_b128 v[192:195], v200 offset:1024
	ds_read_b128 v[196:199], v200 offset:2048
	ds_read_b128 v[224:227], v200 offset:3072
	global_load_lds_dwordx4 v[228:229], off
	s_add_i32 m0, s30, 0x2000
	v_lshl_add_u64 v[228:229], v[230:231], 0, s[76:77]
	global_load_lds_dwordx4 v[228:229], off
	s_barrier
	s_waitcnt lgkmcnt(0)
	v_mfma_f32_16x16x32_bf16 v[118:121], v[188:191], v[146:149], v[118:121]
	v_mfma_f32_16x16x32_bf16 v[114:117], v[196:199], v[146:149], v[114:117]
	v_mfma_f32_16x16x32_bf16 v[102:105], v[188:191], v[154:157], v[102:105]
	v_mfma_f32_16x16x32_bf16 v[98:101], v[196:199], v[154:157], v[98:101]
	v_mfma_f32_16x16x32_bf16 v[86:89], v[188:191], v[162:165], v[86:89]
	v_mfma_f32_16x16x32_bf16 v[82:85], v[196:199], v[162:165], v[82:85]
	v_mfma_f32_16x16x32_bf16 v[70:73], v[188:191], v[170:173], v[70:73]
	v_mfma_f32_16x16x32_bf16 v[66:69], v[196:199], v[170:173], v[66:69]
	v_mfma_f32_16x16x32_bf16 v[118:121], v[192:195], v[150:153], v[118:121]
	v_mfma_f32_16x16x32_bf16 v[114:117], v[224:227], v[150:153], v[114:117]
	v_mfma_f32_16x16x32_bf16 v[102:105], v[192:195], v[158:161], v[102:105]
	v_mfma_f32_16x16x32_bf16 v[98:101], v[224:227], v[158:161], v[98:101]
	v_mfma_f32_16x16x32_bf16 v[86:89], v[192:195], v[166:169], v[86:89]
	v_mfma_f32_16x16x32_bf16 v[82:85], v[224:227], v[166:169], v[82:85]
	v_mfma_f32_16x16x32_bf16 v[70:73], v[192:195], v[174:177], v[70:73]
	v_mfma_f32_16x16x32_bf16 v[66:69], v[224:227], v[174:177], v[66:69]
	s_barrier
	s_mov_b32 m0, s57
	v_lshl_add_u64 v[228:229], v[232:233], 0, s[76:77]
	ds_read_b128 v[146:149], v223 offset:49152
	ds_read_b128 v[150:153], v223 offset:50176
	ds_read_b128 v[154:157], v223 offset:51200
	ds_read_b128 v[158:161], v223 offset:52224
	ds_read_b128 v[162:165], v223 offset:53248
	ds_read_b128 v[166:169], v223 offset:54272
	ds_read_b128 v[170:173], v223 offset:55296
	ds_read_b128 v[174:177], v223 offset:56320
	global_load_lds_dwordx4 v[228:229], off
	s_mov_b32 m0, s60
	v_lshl_add_u64 v[228:229], v[234:235], 0, s[76:77]
	global_load_lds_dwordx4 v[228:229], off
	s_barrier
; #define PG8_STAGE(bufoff, gbase, voff) do { _Pragma("unroll") for (int _i = 0; _i < 2; ++_i) \
;         __builtin_amdgcn_global_load_lds((const unsigned*)((const char*)(gbase) + (voff)[_i]), (LAS unsigned*)(lds + (bufoff) + ldsw + _i * 8192), 16, 0, 0); } while (0)
; #define PG8_WAIT_V(n) asm volatile("s_waitcnt vmcnt(" #n ")" ::: "memory")
; #define PG8_WAIT_L(n) asm volatile("s_waitcnt lgkmcnt(" #n ")" ::: "memory")
;     __device__ __forceinline__ void scales2(const Unit& u, int wr, int fr, int fq, float& sA, float& sB) const {
;         const int rowA = u.pm * BM + wr * 64 + fq * 16 + fr;
;         const f32x4* pa = (const f32x4*)(ssq_in + (size_t)rowA * 16); const f32x4* pb = (const f32x4*)(ssq_in + (size_t)(rowA + HALF) * 16);
;         const f32x4 a0 = pa[0], a1 = pa[1], a2 = pa[2], a3 = pa[3], b0 = pb[0], b1 = pb[1], b2 = pb[2], b3 = pb[3];
;         const float ta = (((a0[0] + a0[1]) + (a0[2] + a0[3])) + ((a1[0] + a1[1]) + (a1[2] + a1[3]))) + (((a2[0] + a2[1]) + (a2[2] + a2[3])) + ((a3[0] + a3[1]) + (a3[2] + a3[3])));
;         const float tb = (((b0[0] + b0[1]) + (b0[2] + b0[3])) + ((b1[0] + b1[1]) + (b1[2] + b1[3]))) + (((b2[0] + b2[1]) + (b2[2] + b2[3])) + ((b3[0] + b3[1]) + (b3[2] + b3[3])));
;         sA = rsqrtf(ta * (1.0f / 1024.0f) + EPS); sB = rsqrtf(tb * (1.0f / 1024.0f) + EPS);
;     }
;     template <int mode> __device__ __forceinline__ void run(const f32x4 (&acc)[2][2][4][2], const Unit& u, int wr, int wc, int fr, int fq, const LAS float* sc) const {
;     ...
;                 const size_t off = (size_t)row0 * D + col0;
; #pragma unroll
;                 for (int bj = 0; bj < 2; ++bj) {
;                     const size_t o = off + bj * HALF;
;                     if (mode == 5) { xi[0][2 * bj] = *(const f32x4*)(xin + o); xi[0][2 * bj + 1] = *(const f32x4*)(xin + o + 4); }
;                     else { xh[0][bj] = *(const u32x4*)(hin + o); xl[0][bj] = *(const u32x4*)(lin + o); }
;                     if (mode == 4) pq[0][bj] = *(const u32x4*)(ob + o);
;                 }
; template <int MODE, class EpiT, class Sched>
; __device__ __forceinline__ void gemm_phase(LAS unsigned char* lds, const Gemm g, const Sched& S, const EpiT& E) {
;     ...
;             PG8_BAR; PG8_WAIT_L(0); PG8_MMA(1, 0, At, B0); PG8_BAR; PG8_SCHED;
;             PG8_STAGE(PG8_SB(1, 1), b3 + hstep, voffB);
;             PG8_WAIT_V(6); PG8_BAR; PG8_MMA(1, 1, At, B1); PG8_BAR;
	s_waitcnt lgkmcnt(0)
	v_mfma_f32_16x16x32_bf16 v[62:65], v[130:133], v[146:149], v[62:65]
	v_mfma_f32_16x16x32_bf16 v[58:61], v[138:141], v[146:149], v[58:61]
	v_mfma_f32_16x16x32_bf16 v[46:49], v[130:133], v[154:157], v[46:49]
	v_mfma_f32_16x16x32_bf16 v[42:45], v[138:141], v[154:157], v[42:45]
	v_mfma_f32_16x16x32_bf16 v[30:33], v[130:133], v[162:165], v[30:33]
	v_mfma_f32_16x16x32_bf16 v[26:29], v[138:141], v[162:165], v[26:29]
	v_mfma_f32_16x16x32_bf16 v[14:17], v[130:133], v[170:173], v[14:17]
	v_mfma_f32_16x16x32_bf16 v[10:13], v[138:141], v[170:173], v[10:13]
	v_mfma_f32_16x16x32_bf16 v[62:65], v[134:137], v[150:153], v[62:65]
	v_mfma_f32_16x16x32_bf16 v[58:61], v[142:145], v[150:153], v[58:61]
	v_mfma_f32_16x16x32_bf16 v[46:49], v[134:137], v[158:161], v[46:49]
	v_mfma_f32_16x16x32_bf16 v[42:45], v[142:145], v[158:161], v[42:45]
	v_mfma_f32_16x16x32_bf16 v[30:33], v[134:137], v[166:169], v[30:33]
	v_mfma_f32_16x16x32_bf16 v[26:29], v[142:145], v[166:169], v[26:29]
	v_mfma_f32_16x16x32_bf16 v[14:17], v[134:137], v[174:177], v[14:17]
	v_mfma_f32_16x16x32_bf16 v[10:13], v[142:145], v[174:177], v[10:13]
	s_barrier
	s_add_i32 s30, s44, s68
	s_mov_b32 m0, s30
	v_lshl_add_u64 v[130:131], v[236:237], 0, s[76:77]
	global_load_lds_dwordx4 v[130:131], off
	s_add_i32 m0, s30, 0x2000
	v_lshl_add_u64 v[130:131], v[238:239], 0, s[76:77]
	global_load_lds_dwordx4 v[130:131], off
	s_waitcnt vmcnt(6)
	s_barrier
	v_mfma_f32_16x16x32_bf16 v[54:57], v[188:191], v[146:149], v[54:57]
	v_mfma_f32_16x16x32_bf16 v[50:53], v[196:199], v[146:149], v[50:53]
	v_mfma_f32_16x16x32_bf16 v[38:41], v[188:191], v[154:157], v[38:41]
	v_mfma_f32_16x16x32_bf16 v[34:37], v[196:199], v[154:157], v[34:37]
	v_mfma_f32_16x16x32_bf16 v[22:25], v[188:191], v[162:165], v[22:25]
	v_mfma_f32_16x16x32_bf16 v[18:21], v[196:199], v[162:165], v[18:21]
	v_mfma_f32_16x16x32_bf16 v[6:9], v[188:191], v[170:173], v[6:9]
	v_mfma_f32_16x16x32_bf16 v[2:5], v[196:199], v[170:173], v[2:5]
	v_mfma_f32_16x16x32_bf16 v[54:57], v[192:195], v[150:153], v[54:57]
	v_mfma_f32_16x16x32_bf16 v[50:53], v[224:227], v[150:153], v[50:53]
	v_mfma_f32_16x16x32_bf16 v[38:41], v[192:195], v[158:161], v[38:41]
	v_mfma_f32_16x16x32_bf16 v[34:37], v[224:227], v[158:161], v[34:37]
	v_mfma_f32_16x16x32_bf16 v[22:25], v[192:195], v[166:169], v[22:25]
	v_mfma_f32_16x16x32_bf16 v[18:21], v[224:227], v[166:169], v[18:21]
	v_mfma_f32_16x16x32_bf16 v[6:9], v[192:195], v[174:177], v[6:9]
	v_mfma_f32_16x16x32_bf16 v[2:5], v[224:227], v[174:177], v[2:5]
	s_barrier
	s_add_u32 s4, s4, 0x100
	s_addc_u32 s5, s5, 0
	s_add_u32 s23, s23, 0x100
	s_addc_u32 s24, s24, 0
	s_cmp_ge_u32 s89, s21
	s_mov_b32 s30, s89
	s_cbranch_scc0 .LBB0_159
	s_lshl_b32 s4, s22, 8
	s_add_i32 s4, s4, s56
	v_or_b32_e32 v130, s4, v222
	v_ashrrev_i32_e32 v131, 31, v130
	v_lshlrev_b64 v[130:131], 6, v[130:131]
	v_lshl_add_u64 v[146:147], s[66:67], 0, v[130:131]
	global_load_dwordx4 v[130:133], v[146:147], off offset:16
	global_load_dwordx4 v[134:137], v[146:147], off offset:48
	global_load_dwordx4 v[138:141], v[146:147], off
	global_load_dwordx4 v[142:145], v[146:147], off offset:32
	v_or_b32_e32 v192, s4, v181
	s_mov_b64 s[4:5], 0x2000
	v_lshl_add_u64 v[158:159], v[146:147], 0, s[4:5]
	v_add_co_u32_e32 v146, vcc, 0x2000, v146
	s_mov_b32 s4, 0x3a800000
	s_nop 0
	v_addc_co_u32_e32 v147, vcc, 0, v147, vcc
	global_load_dwordx4 v[146:149], v[146:147], off
	s_nop 0
	global_load_dwordx4 v[150:153], v[158:159], off offset:16
	global_load_dwordx4 v[154:157], v[158:159], off offset:48
	s_nop 0
	global_load_dwordx4 v[158:161], v[158:159], off offset:32
	v_lshl_or_b32 v188, s2, 8, v221
	v_ashrrev_i32_e32 v193, 31, v192
	v_ashrrev_i32_e32 v189, 31, v188
	v_or_b32_e32 v194, 16, v192
	v_ashrrev_i32_e32 v195, 31, v194
	s_waitcnt vmcnt(0)
	v_mov_b32_e32 v162, v138
	v_mov_b32_e32 v163, v142
	v_mov_b32_e32 v142, v139
	v_pk_add_f32 v[138:139], v[162:163], v[142:143]
	v_mov_b32_e32 v142, v140
	v_mov_b32_e32 v143, v144
	v_mov_b32_e32 v144, v141
	v_pk_add_f32 v[140:141], v[142:143], v[144:145]
	s_nop 0
	v_pk_add_f32 v[138:139], v[138:139], v[140:141]
	v_mov_b32_e32 v140, v130
	v_mov_b32_e32 v141, v134
	v_mov_b32_e32 v134, v131
	v_pk_add_f32 v[130:131], v[140:141], v[134:135]
	v_mov_b32_e32 v134, v132
	v_mov_b32_e32 v135, v136
	v_mov_b32_e32 v136, v133
	v_pk_add_f32 v[132:133], v[134:135], v[136:137]
	v_mov_b32_e32 v134, v148
	v_pk_add_f32 v[130:131], v[130:131], v[132:133]
	v_mov_b32_e32 v132, v146
	v_mov_b32_e32 v133, v158
	v_mov_b32_e32 v158, v147
	v_mov_b32_e32 v135, v160
	v_mov_b32_e32 v160, v149
	v_pk_add_f32 v[132:133], v[132:133], v[158:159]
	v_pk_add_f32 v[134:135], v[134:135], v[160:161]
	v_mov_b32_e32 v136, v152
	v_pk_add_f32 v[132:133], v[132:133], v[134:135]
	v_mov_b32_e32 v134, v150
	v_mov_b32_e32 v135, v154
	v_mov_b32_e32 v154, v151
	v_mov_b32_e32 v137, v156
	v_mov_b32_e32 v156, v153
	v_pk_add_f32 v[134:135], v[134:135], v[154:155]
	v_pk_add_f32 v[136:137], v[136:137], v[156:157]
	v_pk_add_f32 v[130:131], v[138:139], v[130:131]
	v_pk_add_f32 v[134:135], v[134:135], v[136:137]
	s_nop 0
	v_pk_add_f32 v[132:133], v[132:133], v[134:135]
	v_mov_b32_e32 v135, v130
	v_mov_b32_e32 v134, v132
	v_mov_b32_e32 v130, v133
	v_pk_add_f32 v[130:131], v[134:135], v[130:131]
	s_nop 0
	v_pk_fma_f32 v[190:191], v[130:131], s[4:5], v[178:179] op_sel_hi:[1,0,0]
	s_mov_b32 s4, 0x800000
	v_mul_f32_e32 v130, 0x4b800000, v191
	v_cmp_gt_f32_e64 s[44:45], s4, v191
	v_cmp_gt_f32_e32 vcc, s4, v190
	s_nop 0
	v_cndmask_b32_e64 v130, v191, v130, s[44:45]
	v_rsq_f32_e32 v130, v130
	s_nop 0
	v_mul_f32_e32 v131, 0x45800000, v130
	v_cndmask_b32_e64 v226, v130, v131, s[44:45]
	v_lshlrev_b64 v[130:131], 10, v[192:193]
	v_lshl_add_u64 v[130:131], v[130:131], 0, v[188:189]
	v_lshlrev_b64 v[198:199], 1, v[130:131]
	v_lshl_add_u64 v[130:131], s[34:35], 0, v[198:199]
	v_lshl_add_u64 v[132:133], s[92:93], 0, v[198:199]
	global_load_dwordx4 v[170:173], v[130:131], off
	global_load_dwordx4 v[174:177], v[132:133], off
	v_lshl_add_u64 v[134:135], s[6:7], 0, v[198:199]
	global_load_dwordx4 v[166:169], v[134:135], off
	global_load_dwordx4 v[158:161], v[130:131], off offset:256
	global_load_dwordx4 v[162:165], v[132:133], off offset:256
	global_load_dwordx4 v[146:149], v[134:135], off offset:256
	v_and_b32_e32 v130, 64, v205
	v_or_b32_e32 v200, v130, v181
	v_lshlrev_b32_e32 v225, 2, v200
	ds_bpermute_b32 v200, v225, v226
	v_xor_b32_e32 v131, 16, v205
	v_add_u32_e32 v130, 64, v130
	v_cmp_lt_i32_e64 s[44:45], v131, v130
	s_waitcnt lgkmcnt(0)
; __device__ __forceinline__ float bf_lo(unsigned w) { return __uint_as_float(w << 16); }
; __device__ __forceinline__ float bf_hi(unsigned w) { return __uint_as_float(w & 0xffff0000u); }
;     template <int mode> __device__ __forceinline__ void run(const f32x4 (&acc)[2][2][4][2], const Unit& u, int wr, int wc, int fr, int fq, const LAS float* sc) const {
;     ...
;                 if (mode == 4) s = __shfl(ai ? sB : sA, m * 16 + fr);
;                 float ss = 0.f;
; #pragma unroll
;                 for (int bj = 0; bj < 2; ++bj) {
;                     u32x4 wh, wl;
; #pragma unroll
;                     for (int n = 0; n < 2; ++n) {
;                         const int q = 2 * bj + n;
;                         const unsigned h0 = n ? xh[cb][bj].z : xh[cb][bj].x, h1 = n ? xh[cb][bj].w : xh[cb][bj].y, l0 = n ? xl[cb][bj].z : xl[cb][bj].x, l1 = n ? xl[cb][bj].w : xl[cb][bj].y;
;                         f32x4 xo;
;                         if (mode == 5) xo = xi[cb][q];
;                         else { xo[0] = bf_lo(h0) + bf_lo(l0); xo[1] = bf_hi(h0) + bf_hi(l0); xo[2] = bf_lo(h1) + bf_lo(l1); xo[3] = bf_hi(h1) + bf_hi(l1); }
;                         f32x4 v;
;                         if (mode != 4) v = xo + acc[ai][bj][m][n] * alpha + bvv[q];
;                         else {
;                             const f32x4 a = acc[ai][bj][m][n] * s;
;                             const unsigned p0 = n ? pq[cb][bj].z : pq[cb][bj].x, p1 = n ? pq[cb][bj].w : pq[cb][bj].y;
;                             v[0] = xo[0] + sigmoidf_(a[0]) * bf_lo(p0); v[1] = xo[1] + sigmoidf_(a[1]) * bf_hi(p0);
;                             v[2] = xo[2] + sigmoidf_(a[2]) * bf_lo(p1); v[3] = xo[3] + sigmoidf_(a[3]) * bf_hi(p1);
;                         }
;                         const unsigned w0 = pk2(v[0], v[1]), w1 = pk2(v[2], v[3]);
;                         const unsigned m0 = pk2(v[0] - bf_lo(w0), v[1] - bf_hi(w0)), m1 = pk2(v[2] - bf_lo(w1), v[3] - bf_hi(w1));
;                         if (n == 0) { wh.x = w0; wh.y = w1; wl.x = m0; wl.y = m1; } else { wh.z = w0; wh.w = w1; wl.z = m0; wl.w = m1; }
;                         ss += (v[0] * v[0] + v[1] * v[1]) + (v[2] * v[2] + v[3] * v[3]);
;                     }
;                     *(u32x4*)(xb + off + bj * HALF) = wh;
;                     *(u32x4*)(lout + off + bj * HALF) = wl;
	v_pk_mul_f32 v[126:127], v[126:127], v[200:201] op_sel_hi:[1,0]
	v_cndmask_b32_e64 v131, v205, v131, s[44:45]
	v_lshlrev_b32_e32 v191, 2, v131
	v_xor_b32_e32 v131, 32, v205
	v_mul_f32_e32 v126, 0xbfb8aa3b, v126
	v_cmp_lt_i32_e64 s[44:45], v131, v130
	v_exp_f32_e32 v126, v126
	v_pk_mul_f32 v[128:129], v[128:129], v[200:201] op_sel_hi:[1,0]
	v_cndmask_b32_e64 v130, v205, v131, s[44:45]
	v_lshlrev_b32_e32 v224, 2, v130
	v_lshlrev_b64 v[130:131], 10, v[194:195]
	v_lshl_add_u64 v[130:131], v[130:131], 0, v[188:189]
	v_lshlrev_b64 v[196:197], 1, v[130:131]
	v_add_f32_e32 v126, 1.0, v126
	v_lshl_add_u64 v[130:131], s[34:35], 0, v[196:197]
	v_lshl_add_u64 v[132:133], s[92:93], 0, v[196:197]
	v_lshl_add_u64 v[228:229], s[6:7], 0, v[196:197]
	v_rcp_f32_e32 v126, v126
	global_load_dwordx4 v[150:153], v[130:131], off
	global_load_dwordx4 v[154:157], v[132:133], off
	global_load_dwordx4 v[142:145], v[228:229], off
	global_load_dwordx4 v[134:137], v[130:131], off offset:256
	global_load_dwordx4 v[138:141], v[132:133], off offset:256
	s_nop 0
	global_load_dwordx4 v[130:133], v[228:229], off offset:256
	v_pk_mul_f32 v[122:123], v[122:123], v[200:201] op_sel_hi:[1,0]
	v_pk_mul_f32 v[124:125], v[124:125], v[200:201] op_sel_hi:[1,0]
	v_mul_f32_e32 v122, 0xbfb8aa3b, v122
	v_exp_f32_e32 v122, v122
	v_pk_mul_f32 v[118:119], v[118:119], v[200:201] op_sel_hi:[1,0]
	v_pk_mul_f32 v[120:121], v[120:121], v[200:201] op_sel_hi:[1,0]
	v_mul_f32_e32 v118, 0xbfb8aa3b, v118
	v_add_f32_e32 v122, 1.0, v122
	v_rcp_f32_e32 v122, v122
	v_exp_f32_e32 v118, v118
	v_pk_mul_f32 v[114:115], v[114:115], v[200:201] op_sel_hi:[1,0]
	v_pk_mul_f32 v[116:117], v[116:117], v[200:201] op_sel_hi:[1,0]
	v_mul_f32_e32 v114, 0xbfb8aa3b, v114
	v_add_f32_e32 v118, 1.0, v118
	v_rcp_f32_e32 v118, v118
	v_exp_f32_e32 v114, v114
	s_lshl_b32 s44, s2, 2
	s_ashr_i32 s45, s44, 31
	v_add_f32_e32 v114, 1.0, v114
	v_rcp_f32_e32 v114, v114
	s_waitcnt vmcnt(11)
	v_lshlrev_b32_e32 v227, 16, v170
	s_waitcnt vmcnt(10)
	v_lshlrev_b32_e32 v228, 16, v174
	v_and_b32_e32 v174, 0xffff0000, v174
	v_and_b32_e32 v170, 0xffff0000, v170
	v_add_f32_e32 v227, v228, v227
	v_add_f32_e32 v170, v174, v170
	v_lshlrev_b32_e32 v174, 16, v171
	v_lshlrev_b32_e32 v228, 16, v175
	v_and_b32_e32 v175, 0xffff0000, v175
	v_and_b32_e32 v171, 0xffff0000, v171
	v_add_f32_e32 v171, v175, v171
	s_waitcnt vmcnt(9)
	v_lshlrev_b32_e32 v175, 16, v166
	v_fmac_f32_e32 v227, v126, v175
	v_mul_f32_e32 v126, 0xbfb8aa3b, v127
	v_exp_f32_e32 v126, v126
	v_and_b32_e32 v127, 0xffff0000, v166
	v_add_f32_e32 v174, v228, v174
	v_add_f32_e32 v126, 1.0, v126
	v_rcp_f32_e32 v126, v126
	s_nop 0
	v_fmac_f32_e32 v170, v126, v127
	v_mul_f32_e32 v126, 0xbfb8aa3b, v128
	v_exp_f32_e32 v126, v126
	v_lshlrev_b32_e32 v127, 16, v167
	v_add_f32_e32 v126, 1.0, v126
	v_rcp_f32_e32 v126, v126
	s_nop 0
	v_fmac_f32_e32 v174, v126, v127
	v_mul_f32_e32 v126, 0xbfb8aa3b, v129
	v_exp_f32_e32 v126, v126
	v_and_b32_e32 v127, 0xffff0000, v167
	v_add_f32_e32 v126, 1.0, v126
	v_rcp_f32_e32 v126, v126
	s_nop 0
	v_fmac_f32_e32 v171, v126, v127
	v_cvt_pk_bf16_f32 v126, v227, v170
	v_cvt_pk_bf16_f32 v127, v174, v171
	s_nop 0
	v_lshlrev_b32_e32 v128, 16, v126
	v_and_b32_e32 v129, 0xffff0000, v126
	v_sub_f32_e32 v128, v227, v128
	v_sub_f32_e32 v129, v170, v129
	v_cvt_pk_bf16_f32 v166, v128, v129
	v_lshlrev_b32_e32 v128, 16, v127
	v_and_b32_e32 v129, 0xffff0000, v127
	v_sub_f32_e32 v128, v174, v128
	v_sub_f32_e32 v129, v171, v129
	v_cvt_pk_bf16_f32 v167, v128, v129
	v_mul_f32_e32 v128, v170, v170
	v_mul_f32_e32 v129, v171, v171
	v_fmac_f32_e32 v128, v227, v227
	v_fmac_f32_e32 v129, v174, v174
	v_add_f32_e32 v170, v128, v129
	v_lshlrev_b32_e32 v128, 16, v172
	v_lshlrev_b32_e32 v129, 16, v176
	v_add_f32_e32 v171, v129, v128
	v_and_b32_e32 v128, 0xffff0000, v176
	v_and_b32_e32 v129, 0xffff0000, v172
	v_add_f32_e32 v172, v128, v129
	v_lshlrev_b32_e32 v128, 16, v173
	v_lshlrev_b32_e32 v129, 16, v177
	v_add_f32_e32 v174, v129, v128
	v_and_b32_e32 v128, 0xffff0000, v177
	v_and_b32_e32 v129, 0xffff0000, v173
	v_add_f32_e32 v173, v128, v129
	v_lshlrev_b32_e32 v128, 16, v168
	v_fmac_f32_e32 v171, v122, v128
	v_mul_f32_e32 v122, 0xbfb8aa3b, v123
	v_exp_f32_e32 v122, v122
	v_and_b32_e32 v123, 0xffff0000, v168
	v_add_f32_e32 v122, 1.0, v122
	v_rcp_f32_e32 v122, v122
	s_nop 0
	v_fmac_f32_e32 v172, v122, v123
	v_mul_f32_e32 v122, 0xbfb8aa3b, v124
	v_exp_f32_e32 v122, v122
	v_lshlrev_b32_e32 v123, 16, v169
	v_cvt_pk_bf16_f32 v128, v171, v172
	v_add_f32_e32 v122, 1.0, v122
	v_rcp_f32_e32 v122, v122
	s_nop 0
	v_fmac_f32_e32 v174, v122, v123
	v_mul_f32_e32 v122, 0xbfb8aa3b, v125
	v_exp_f32_e32 v122, v122
	v_and_b32_e32 v123, 0xffff0000, v169
	v_lshl_add_u64 v[124:125], s[28:29], 0, v[198:199]
	v_add_f32_e32 v122, 1.0, v122
	v_rcp_f32_e32 v122, v122
	s_nop 0
	v_fmac_f32_e32 v173, v122, v123
	v_lshlrev_b32_e32 v122, 16, v128
	v_and_b32_e32 v123, 0xffff0000, v128
	v_sub_f32_e32 v122, v171, v122
	v_sub_f32_e32 v123, v172, v123
	v_cvt_pk_bf16_f32 v129, v174, v173
	v_cvt_pk_bf16_f32 v168, v122, v123
	s_nop 0
	v_lshlrev_b32_e32 v122, 16, v129
	v_and_b32_e32 v123, 0xffff0000, v129
	v_sub_f32_e32 v122, v174, v122
	v_sub_f32_e32 v123, v173, v123
	v_cvt_pk_bf16_f32 v169, v122, v123
	v_mul_f32_e32 v122, v172, v172
	v_mul_f32_e32 v123, v173, v173
	v_fmac_f32_e32 v122, v171, v171
	v_fmac_f32_e32 v123, v174, v174
	v_add_f32_e32 v122, v122, v123
	v_add_f32_e32 v170, v170, v122
	v_lshl_add_u64 v[122:123], s[10:11], 0, v[198:199]
	global_store_dwordx4 v[122:123], v[126:129], off
	global_store_dwordx4 v[124:125], v[166:169], off
	s_waitcnt vmcnt(10)
; __device__ __forceinline__ float bf_lo(unsigned w) { return __uint_as_float(w << 16); }
; __device__ __forceinline__ float bf_hi(unsigned w) { return __uint_as_float(w & 0xffff0000u); }
;     template <int mode> __device__ __forceinline__ void run(const f32x4 (&acc)[2][2][4][2], const Unit& u, int wr, int wc, int fr, int fq, const LAS float* sc) const {
;     ...
;                 for (int bj = 0; bj < 2; ++bj) {
;                     u32x4 wh, wl;
; #pragma unroll
;                     for (int n = 0; n < 2; ++n) {
;                         const int q = 2 * bj + n;
;                         const unsigned h0 = n ? xh[cb][bj].z : xh[cb][bj].x, h1 = n ? xh[cb][bj].w : xh[cb][bj].y, l0 = n ? xl[cb][bj].z : xl[cb][bj].x, l1 = n ? xl[cb][bj].w : xl[cb][bj].y;
;                         f32x4 xo;
;                         if (mode == 5) xo = xi[cb][q];
;                         else { xo[0] = bf_lo(h0) + bf_lo(l0); xo[1] = bf_hi(h0) + bf_hi(l0); xo[2] = bf_lo(h1) + bf_lo(l1); xo[3] = bf_hi(h1) + bf_hi(l1); }
;                         f32x4 v;
;                         if (mode != 4) v = xo + acc[ai][bj][m][n] * alpha + bvv[q];
;                         else {
;                             const f32x4 a = acc[ai][bj][m][n] * s;
;                             const unsigned p0 = n ? pq[cb][bj].z : pq[cb][bj].x, p1 = n ? pq[cb][bj].w : pq[cb][bj].y;
;                             v[0] = xo[0] + sigmoidf_(a[0]) * bf_lo(p0); v[1] = xo[1] + sigmoidf_(a[1]) * bf_hi(p0);
;                             v[2] = xo[2] + sigmoidf_(a[2]) * bf_lo(p1); v[3] = xo[3] + sigmoidf_(a[3]) * bf_hi(p1);
;                         }
;                         const unsigned w0 = pk2(v[0], v[1]), w1 = pk2(v[2], v[3]);
;                         const unsigned m0 = pk2(v[0] - bf_lo(w0), v[1] - bf_hi(w0)), m1 = pk2(v[2] - bf_lo(w1), v[3] - bf_hi(w1));
;                         if (n == 0) { wh.x = w0; wh.y = w1; wl.x = m0; wl.y = m1; } else { wh.z = w0; wh.w = w1; wl.z = m0; wl.w = m1; }
;                         ss += (v[0] * v[0] + v[1] * v[1]) + (v[2] * v[2] + v[3] * v[3]);
;                     }
;                     *(u32x4*)(xb + off + bj * HALF) = wh;
;                     *(u32x4*)(lout + off + bj * HALF) = wl;
;                 }
;                 ss += __shfl_xor(ss, 16); ss += __shfl_xor(ss, 32);
;                 if (fq == 0) ssq_out[(size_t)row * 16 + u.pn * 4 + wc] = ss;
	v_lshlrev_b32_e32 v126, 16, v158
	s_waitcnt vmcnt(9)
	v_lshlrev_b32_e32 v127, 16, v162
	v_add_f32_e32 v128, v127, v126
	v_and_b32_e32 v126, 0xffff0000, v162
	v_and_b32_e32 v127, 0xffff0000, v158
	v_add_f32_e32 v129, v126, v127
	v_lshlrev_b32_e32 v126, 16, v159
	v_lshlrev_b32_e32 v127, 16, v163
	v_add_f32_e32 v158, v127, v126
	v_and_b32_e32 v126, 0xffff0000, v163
	v_and_b32_e32 v127, 0xffff0000, v159
	v_add_f32_e32 v159, v126, v127
	s_waitcnt vmcnt(8)
	v_lshlrev_b32_e32 v126, 16, v146
	v_fmac_f32_e32 v128, v118, v126
	v_mul_f32_e32 v118, 0xbfb8aa3b, v119
	v_exp_f32_e32 v118, v118
	v_and_b32_e32 v119, 0xffff0000, v146
	v_add_f32_e32 v118, 1.0, v118
	v_rcp_f32_e32 v118, v118
	s_nop 0
	v_fmac_f32_e32 v129, v118, v119
	v_mul_f32_e32 v118, 0xbfb8aa3b, v120
	v_exp_f32_e32 v118, v118
	v_lshlrev_b32_e32 v119, 16, v147
	v_add_f32_e32 v118, 1.0, v118
	v_rcp_f32_e32 v118, v118
	s_nop 0
	v_fmac_f32_e32 v158, v118, v119
	v_mul_f32_e32 v118, 0xbfb8aa3b, v121
	v_exp_f32_e32 v118, v118
	v_and_b32_e32 v119, 0xffff0000, v147
	v_add_f32_e32 v118, 1.0, v118
	v_rcp_f32_e32 v118, v118
	s_nop 0
	v_fmac_f32_e32 v159, v118, v119
	v_cvt_pk_bf16_f32 v118, v128, v129
	v_cvt_pk_bf16_f32 v119, v158, v159
	s_nop 0
	v_lshlrev_b32_e32 v120, 16, v118
	v_and_b32_e32 v121, 0xffff0000, v118
	v_sub_f32_e32 v120, v128, v120
	v_sub_f32_e32 v121, v129, v121
	v_cvt_pk_bf16_f32 v126, v120, v121
	v_lshlrev_b32_e32 v120, 16, v119
	v_and_b32_e32 v121, 0xffff0000, v119
	v_sub_f32_e32 v120, v158, v120
	v_sub_f32_e32 v121, v159, v121
	v_cvt_pk_bf16_f32 v127, v120, v121
	v_mul_f32_e32 v120, v129, v129
	v_mul_f32_e32 v121, v159, v159
	v_fmac_f32_e32 v120, v128, v128
	v_fmac_f32_e32 v121, v158, v158
	v_add_f32_e32 v120, v120, v121
	v_add_f32_e32 v146, v120, v170
	v_lshlrev_b32_e32 v120, 16, v160
	v_lshlrev_b32_e32 v121, 16, v164
	v_add_f32_e32 v147, v121, v120
	v_and_b32_e32 v120, 0xffff0000, v164
	v_and_b32_e32 v121, 0xffff0000, v160
	v_add_f32_e32 v158, v120, v121
	v_lshlrev_b32_e32 v120, 16, v161
	v_lshlrev_b32_e32 v121, 16, v165
	v_add_f32_e32 v159, v121, v120
	v_and_b32_e32 v120, 0xffff0000, v165
	v_and_b32_e32 v121, 0xffff0000, v161
	v_add_f32_e32 v160, v120, v121
	v_lshlrev_b32_e32 v120, 16, v148
	v_fmac_f32_e32 v147, v114, v120
	v_mul_f32_e32 v114, 0xbfb8aa3b, v115
	v_exp_f32_e32 v114, v114
	v_and_b32_e32 v115, 0xffff0000, v148
	v_add_f32_e32 v114, 1.0, v114
	v_rcp_f32_e32 v114, v114
	s_nop 0
	v_fmac_f32_e32 v158, v114, v115
	v_mul_f32_e32 v114, 0xbfb8aa3b, v116
	v_exp_f32_e32 v114, v114
	v_lshlrev_b32_e32 v115, 16, v149
	v_cvt_pk_bf16_f32 v120, v147, v158
	v_add_f32_e32 v114, 1.0, v114
	v_rcp_f32_e32 v114, v114
	s_nop 0
	v_fmac_f32_e32 v159, v114, v115
	v_mul_f32_e32 v114, 0xbfb8aa3b, v117
	v_exp_f32_e32 v114, v114
	v_and_b32_e32 v115, 0xffff0000, v149
	v_add_f32_e32 v114, 1.0, v114
	v_rcp_f32_e32 v114, v114
	s_nop 0
	v_fmac_f32_e32 v160, v114, v115
	v_lshlrev_b32_e32 v114, 16, v120
	v_and_b32_e32 v115, 0xffff0000, v120
	v_sub_f32_e32 v114, v147, v114
	v_sub_f32_e32 v115, v158, v115
	v_cvt_pk_bf16_f32 v121, v159, v160
	v_cvt_pk_bf16_f32 v128, v114, v115
	s_nop 0
	v_lshlrev_b32_e32 v114, 16, v121
	v_and_b32_e32 v115, 0xffff0000, v121
	v_sub_f32_e32 v114, v159, v114
	v_sub_f32_e32 v115, v160, v115
	v_cvt_pk_bf16_f32 v129, v114, v115
	v_mul_f32_e32 v114, v158, v158
	v_mul_f32_e32 v115, v160, v160
	v_fmac_f32_e32 v114, v147, v147
	v_fmac_f32_e32 v115, v159, v159
	v_add_f32_e32 v114, v114, v115
	v_add_f32_e32 v114, v114, v146
	ds_bpermute_b32 v115, v191, v114
	global_store_dwordx4 v[122:123], v[118:121], off offset:256
	global_store_dwordx4 v[124:125], v[126:129], off offset:256
	s_waitcnt lgkmcnt(0)
	v_add_f32_e32 v114, v114, v115
	ds_bpermute_b32 v115, v224, v114
	s_and_saveexec_b64 s[4:5], s[40:41]
	s_cbranch_execz .LBB0_162
	v_lshlrev_b64 v[116:117], 6, v[192:193]
	v_lshl_add_u64 v[116:117], s[62:63], 0, v[116:117]
	v_lshl_add_u64 v[116:117], s[44:45], 2, v[116:117]
	s_lshl_b32 s24, s20, 2
	v_lshl_add_u64 v[116:117], v[116:117], 0, s[24:25]
	s_waitcnt lgkmcnt(0)
	v_add_f32_e32 v114, v114, v115
	global_store_dword v[116:117], v114, off

; #define PG8_STAGE(bufoff, gbase, voff) do { _Pragma("unroll") for (int _i = 0; _i < 2; ++_i) \
;         __builtin_amdgcn_global_load_lds((const unsigned*)((const char*)(gbase) + (voff)[_i]), (LAS unsigned*)(lds + (bufoff) + ldsw + _i * 8192), 16, 0, 0); } while (0)
; #define PG8_LDA(dst, b, h) do { _Pragma("unroll") for (int m = 0; m < 4; ++m) _Pragma("unroll") for (int k = 0; k < 2; ++k) dst[m][k] = *(const LAS bf16x8*)(lds + PG8_SA(b, h) + aoff + m * 2048 + k * 1024); } while (0)
; #define PG8_LDB(dst, b, h) do { _Pragma("unroll") for (int n = 0; n < 2; ++n) _Pragma("unroll") for (int k = 0; k < 2; ++k) dst[n][k] = *(const LAS bf16x8*)(lds + PG8_SB(b, h) + boff + n * 2048 + k * 1024); } while (0)
; #define PG8_MMA(ai, bj, At, Bt) do { __builtin_amdgcn_s_setprio(1); _Pragma("unroll") for (int m = 0; m < 4; ++m) _Pragma("unroll") for (int n = 0; n < 2; ++n) _Pragma("unroll") for (int k = 0; k < 2; ++k) \
;         acc[ai][bj][m][n] = __builtin_amdgcn_mfma_f32_16x16x32_bf16(Bt[n][k], At[m][k], acc[ai][bj][m][n], 0, 0, 0); __builtin_amdgcn_s_setprio(0); } while (0)
; #define PG8_WAIT_L(n) asm volatile("s_waitcnt lgkmcnt(" #n ")" ::: "memory")
; #define PG8_BAR __builtin_amdgcn_s_barrier()
; #define PG8_SCHED __builtin_amdgcn_sched_barrier(0)
; template <int MODE, class EpiT, class Sched>
; __device__ __forceinline__ void gemm_phase(LAS unsigned char* lds, const Gemm g, const Sched& S, const EpiT& E) {
;     ...
;             PG8_LDB(B0, 0, 0); PG8_SCHED; PG8_LDA(At, 0, 0); PG8_STAGE(PG8_SA(1, 1), a1 + hstep, voffA);
;             PG8_WAIT_L(8); PG8_BAR; PG8_WAIT_L(0); PG8_MMA(0, 0, At, B0); PG8_BAR; PG8_SCHED;
;             PG8_LDB(B1, 0, 1); PG8_STAGE(PG8_SB(0, 0), b2, voffB);
;             PG8_BAR; PG8_WAIT_L(0); PG8_MMA(0, 1, At, B1); PG8_BAR;
;             PG8_LDA(At, 0, 1); PG8_STAGE(PG8_SA(0, 0), a2, voffA);
;             PG8_BAR; PG8_WAIT_L(0); PG8_MMA(1, 0, At, B0); PG8_BAR; PG8_SCHED;
.LBB0_195:
	s_add_i32 vcc_lo, s44, 2
	s_add_u32 s52, s4, 0x80
	s_addc_u32 s45, s5, 0
	s_add_i32 s58, 0, 0x10000
	v_add_u32_e32 v74, s58, v194
	ds_read_b128 v[58:61], v74
	ds_read_b128 v[62:65], v74 offset:1024
	ds_read_b128 v[70:73], v74 offset:2048
	ds_read_b128 v[74:77], v74 offset:3072
	s_cmp_eq_u32 s75, s44
	s_cselect_b32 s44, s68, s52
	s_cselect_b32 s45, s69, s45
	s_cselect_b32 s53, s47, s90
	s_cselect_b32 s52, s46, s89
	v_lshl_add_u64 v[188:189], s[4:5], 0, v[176:177]
	s_add_i32 m0, s21, 0xc000
	ds_read_b128 v[138:141], v196
	ds_read_b128 v[142:145], v196 offset:1024
	ds_read_b128 v[146:149], v196 offset:2048
	ds_read_b128 v[150:153], v196 offset:3072
	ds_read_b128 v[162:165], v196 offset:4096
	ds_read_b128 v[166:169], v196 offset:5120
	ds_read_b128 v[170:173], v196 offset:6144
	ds_read_b128 v[184:187], v196 offset:7168
	global_load_lds_dwordx4 v[188:189], off
	s_add_i32 m0, s21, 0xe000
	v_lshl_add_u64 v[188:189], s[4:5], 0, v[182:183]
	global_load_lds_dwordx4 v[188:189], off
	s_waitcnt lgkmcnt(8)
	s_barrier
	s_waitcnt lgkmcnt(0)
	v_mfma_f32_16x16x32_bf16 v[158:161], v[58:61], v[138:141], v[158:161]
	v_mfma_f32_16x16x32_bf16 v[154:157], v[70:73], v[138:141], v[154:157]
	v_mfma_f32_16x16x32_bf16 v[126:129], v[58:61], v[146:149], v[126:129]
	v_mfma_f32_16x16x32_bf16 v[122:125], v[70:73], v[146:149], v[122:125]
	v_mfma_f32_16x16x32_bf16 v[110:113], v[58:61], v[162:165], v[110:113]
	v_mfma_f32_16x16x32_bf16 v[106:109], v[70:73], v[162:165], v[106:109]
	v_mfma_f32_16x16x32_bf16 v[94:97], v[58:61], v[170:173], v[94:97]
	v_mfma_f32_16x16x32_bf16 v[90:93], v[70:73], v[170:173], v[90:93]
	v_mfma_f32_16x16x32_bf16 v[158:161], v[62:65], v[142:145], v[158:161]
	v_mfma_f32_16x16x32_bf16 v[154:157], v[74:77], v[142:145], v[154:157]
	v_mfma_f32_16x16x32_bf16 v[126:129], v[62:65], v[150:153], v[126:129]
	v_mfma_f32_16x16x32_bf16 v[122:125], v[74:77], v[150:153], v[122:125]
	v_mfma_f32_16x16x32_bf16 v[110:113], v[62:65], v[166:169], v[110:113]
	v_mfma_f32_16x16x32_bf16 v[106:109], v[74:77], v[166:169], v[106:109]
	v_mfma_f32_16x16x32_bf16 v[94:97], v[62:65], v[184:187], v[94:97]
	v_mfma_f32_16x16x32_bf16 v[90:93], v[74:77], v[184:187], v[90:93]
	s_barrier
	s_add_i32 s59, 0, 0x14000
	v_add_u32_e32 v192, s59, v194
	s_add_i32 s58, s58, s20
	ds_read_b128 v[188:191], v192
	ds_read_b128 v[220:223], v192 offset:1024
	ds_read_b128 v[224:227], v192 offset:2048
	ds_read_b128 v[228:231], v192 offset:3072
	v_lshl_add_u64 v[192:193], s[52:53], 0, v[0:1]
	s_mov_b32 m0, s58
	global_load_lds_dwordx4 v[192:193], off
	s_add_i32 m0, s58, 0x2000
	v_lshl_add_u64 v[198:199], s[52:53], 0, v[174:175]
	global_load_lds_dwordx4 v[198:199], off
	s_barrier
	s_waitcnt lgkmcnt(0)
	v_mfma_f32_16x16x32_bf16 v[134:137], v[188:191], v[138:141], v[134:137]
	v_mfma_f32_16x16x32_bf16 v[130:133], v[224:227], v[138:141], v[130:133]
	v_mfma_f32_16x16x32_bf16 v[118:121], v[188:191], v[146:149], v[118:121]
	v_mfma_f32_16x16x32_bf16 v[114:117], v[224:227], v[146:149], v[114:117]
	v_mfma_f32_16x16x32_bf16 v[102:105], v[188:191], v[162:165], v[102:105]
	v_mfma_f32_16x16x32_bf16 v[98:101], v[224:227], v[162:165], v[98:101]
	v_mfma_f32_16x16x32_bf16 v[86:89], v[188:191], v[170:173], v[86:89]
	v_mfma_f32_16x16x32_bf16 v[82:85], v[224:227], v[170:173], v[82:85]
	v_mfma_f32_16x16x32_bf16 v[134:137], v[220:223], v[142:145], v[134:137]
	v_mfma_f32_16x16x32_bf16 v[130:133], v[228:231], v[142:145], v[130:133]
	v_mfma_f32_16x16x32_bf16 v[118:121], v[220:223], v[150:153], v[118:121]
	v_mfma_f32_16x16x32_bf16 v[114:117], v[228:231], v[150:153], v[114:117]
	v_mfma_f32_16x16x32_bf16 v[102:105], v[220:223], v[166:169], v[102:105]
	v_mfma_f32_16x16x32_bf16 v[98:101], v[228:231], v[166:169], v[98:101]
	v_mfma_f32_16x16x32_bf16 v[86:89], v[220:223], v[184:187], v[86:89]
	v_mfma_f32_16x16x32_bf16 v[82:85], v[228:231], v[184:187], v[82:85]
	s_barrier
	s_mov_b32 m0, s21
	v_lshl_add_u64 v[232:233], s[44:45], 0, v[0:1]
	ds_read_b128 v[138:141], v196 offset:16384
	ds_read_b128 v[142:145], v196 offset:17408
	ds_read_b128 v[146:149], v196 offset:18432
	ds_read_b128 v[150:153], v196 offset:19456
	ds_read_b128 v[162:165], v196 offset:20480
	ds_read_b128 v[166:169], v196 offset:21504
	ds_read_b128 v[170:173], v196 offset:22528
	ds_read_b128 v[184:187], v196 offset:23552
	global_load_lds_dwordx4 v[232:233], off
	s_mov_b32 m0, s50
	v_lshl_add_u64 v[234:235], s[44:45], 0, v[174:175]
	global_load_lds_dwordx4 v[234:235], off
	s_barrier
	s_waitcnt lgkmcnt(0)
	v_mfma_f32_16x16x32_bf16 v[78:81], v[58:61], v[138:141], v[78:81]
	v_mfma_f32_16x16x32_bf16 v[66:69], v[70:73], v[138:141], v[66:69]
	v_mfma_f32_16x16x32_bf16 v[46:49], v[58:61], v[146:149], v[46:49]
	v_mfma_f32_16x16x32_bf16 v[42:45], v[70:73], v[146:149], v[42:45]
	v_mfma_f32_16x16x32_bf16 v[30:33], v[58:61], v[162:165], v[30:33]
	v_mfma_f32_16x16x32_bf16 v[26:29], v[70:73], v[162:165], v[26:29]
	v_mfma_f32_16x16x32_bf16 v[14:17], v[58:61], v[170:173], v[14:17]
	v_mfma_f32_16x16x32_bf16 v[10:13], v[70:73], v[170:173], v[10:13]
	v_mfma_f32_16x16x32_bf16 v[78:81], v[62:65], v[142:145], v[78:81]
	v_mfma_f32_16x16x32_bf16 v[66:69], v[74:77], v[142:145], v[66:69]
	v_mfma_f32_16x16x32_bf16 v[46:49], v[62:65], v[150:153], v[46:49]
	v_mfma_f32_16x16x32_bf16 v[42:45], v[74:77], v[150:153], v[42:45]
	v_mfma_f32_16x16x32_bf16 v[30:33], v[62:65], v[166:169], v[30:33]
	v_mfma_f32_16x16x32_bf16 v[26:29], v[74:77], v[166:169], v[26:29]
	v_mfma_f32_16x16x32_bf16 v[14:17], v[62:65], v[184:187], v[14:17]
	v_mfma_f32_16x16x32_bf16 v[10:13], v[74:77], v[184:187], v[10:13]
	s_barrier
; #define PG8_STAGE(bufoff, gbase, voff) do { _Pragma("unroll") for (int _i = 0; _i < 2; ++_i) \
;         __builtin_amdgcn_global_load_lds((const unsigned*)((const char*)(gbase) + (voff)[_i]), (LAS unsigned*)(lds + (bufoff) + ldsw + _i * 8192), 16, 0, 0); } while (0)
; #define PG8_LDA(dst, b, h) do { _Pragma("unroll") for (int m = 0; m < 4; ++m) _Pragma("unroll") for (int k = 0; k < 2; ++k) dst[m][k] = *(const LAS bf16x8*)(lds + PG8_SA(b, h) + aoff + m * 2048 + k * 1024); } while (0)
; #define PG8_LDB(dst, b, h) do { _Pragma("unroll") for (int n = 0; n < 2; ++n) _Pragma("unroll") for (int k = 0; k < 2; ++k) dst[n][k] = *(const LAS bf16x8*)(lds + PG8_SB(b, h) + boff + n * 2048 + k * 1024); } while (0)
; #define PG8_MMA(ai, bj, At, Bt) do { __builtin_amdgcn_s_setprio(1); _Pragma("unroll") for (int m = 0; m < 4; ++m) _Pragma("unroll") for (int n = 0; n < 2; ++n) _Pragma("unroll") for (int k = 0; k < 2; ++k) \
;         acc[ai][bj][m][n] = __builtin_amdgcn_mfma_f32_16x16x32_bf16(Bt[n][k], At[m][k], acc[ai][bj][m][n], 0, 0, 0); __builtin_amdgcn_s_setprio(0); } while (0)
; #define PG8_WAIT_V(n) asm volatile("s_waitcnt vmcnt(" #n ")" ::: "memory")
; #define PG8_WAIT_L(n) asm volatile("s_waitcnt lgkmcnt(" #n ")" ::: "memory")
; #define PG8_BAR __builtin_amdgcn_s_barrier()
; #define PG8_SCHED __builtin_amdgcn_sched_barrier(0)
; template <int MODE, class EpiT, class Sched>
; __device__ __forceinline__ void gemm_phase(LAS unsigned char* lds, const Gemm g, const Sched& S, const EpiT& E) {
;     ...
;             PG8_STAGE(PG8_SB(0, 1), b2 + hstep, voffB);
;             PG8_WAIT_V(6); PG8_BAR; PG8_MMA(1, 1, At, B1); PG8_BAR;
;             PG8_LDB(B0, 1, 0); PG8_SCHED; PG8_LDA(At, 1, 0); PG8_STAGE(PG8_SA(0, 1), a2 + hstep, voffA);
;             PG8_WAIT_L(8); PG8_BAR; PG8_WAIT_L(0); PG8_MMA(0, 0, At, B0); PG8_BAR; PG8_SCHED;
;             PG8_LDB(B1, 1, 1); PG8_STAGE(PG8_SB(1, 0), b3, voffB);
;             PG8_BAR; PG8_WAIT_L(0); PG8_MMA(0, 1, At, B1); PG8_BAR;
;             PG8_LDA(At, 1, 1); PG8_STAGE(PG8_SA(1, 0), a3, voffA);
;             PG8_BAR; PG8_WAIT_L(0); PG8_MMA(1, 0, At, B0); PG8_BAR; PG8_SCHED;
	s_add_u32 s52, s52, s38
	s_addc_u32 s53, s53, 0
	s_add_i32 s58, s59, s20
	v_lshl_add_u64 v[236:237], s[52:53], 0, v[0:1]
	s_mov_b32 m0, s58
	global_load_lds_dwordx4 v[236:237], off
	s_add_i32 m0, s58, 0x2000
	v_lshl_add_u64 v[238:239], s[52:53], 0, v[174:175]
	global_load_lds_dwordx4 v[238:239], off
	s_waitcnt vmcnt(6)
	s_barrier
	v_mfma_f32_16x16x32_bf16 v[54:57], v[188:191], v[138:141], v[54:57]
	v_mfma_f32_16x16x32_bf16 v[50:53], v[224:227], v[138:141], v[50:53]
	v_mfma_f32_16x16x32_bf16 v[38:41], v[188:191], v[146:149], v[38:41]
	v_mfma_f32_16x16x32_bf16 v[34:37], v[224:227], v[146:149], v[34:37]
	v_mfma_f32_16x16x32_bf16 v[22:25], v[188:191], v[162:165], v[22:25]
	v_mfma_f32_16x16x32_bf16 v[18:21], v[224:227], v[162:165], v[18:21]
	v_mfma_f32_16x16x32_bf16 v[6:9], v[188:191], v[170:173], v[6:9]
	v_mfma_f32_16x16x32_bf16 v[2:5], v[224:227], v[170:173], v[2:5]
	v_mfma_f32_16x16x32_bf16 v[54:57], v[220:223], v[142:145], v[54:57]
	v_mfma_f32_16x16x32_bf16 v[50:53], v[228:231], v[142:145], v[50:53]
	v_mfma_f32_16x16x32_bf16 v[38:41], v[220:223], v[150:153], v[38:41]
	v_mfma_f32_16x16x32_bf16 v[34:37], v[228:231], v[150:153], v[34:37]
	v_mfma_f32_16x16x32_bf16 v[22:25], v[220:223], v[166:169], v[22:25]
	v_mfma_f32_16x16x32_bf16 v[18:21], v[228:231], v[166:169], v[18:21]
	v_mfma_f32_16x16x32_bf16 v[6:9], v[220:223], v[184:187], v[6:9]
	v_mfma_f32_16x16x32_bf16 v[2:5], v[228:231], v[184:187], v[2:5]
	s_barrier
	s_add_i32 s52, 0, 0x18000
	v_add_u32_e32 v74, s52, v194
	ds_read_b128 v[58:61], v74
	ds_read_b128 v[62:65], v74 offset:1024
	ds_read_b128 v[70:73], v74 offset:2048
	ds_read_b128 v[74:77], v74 offset:3072
	s_add_u32 s44, s44, s38
	s_addc_u32 s45, s45, 0
	s_mov_b32 m0, s51
	v_lshl_add_u64 v[188:189], s[44:45], 0, v[0:1]
	ds_read_b128 v[138:141], v196 offset:32768
	ds_read_b128 v[142:145], v196 offset:33792
	ds_read_b128 v[146:149], v196 offset:34816
	ds_read_b128 v[150:153], v196 offset:35840
	ds_read_b128 v[162:165], v196 offset:36864
	ds_read_b128 v[166:169], v196 offset:37888
	ds_read_b128 v[170:173], v196 offset:38912
	ds_read_b128 v[184:187], v196 offset:39936
	global_load_lds_dwordx4 v[188:189], off
	s_mov_b32 m0, s56
	v_lshl_add_u64 v[188:189], s[44:45], 0, v[174:175]
	global_load_lds_dwordx4 v[188:189], off
	s_waitcnt lgkmcnt(8)
	s_barrier
	s_waitcnt lgkmcnt(0)
	v_mfma_f32_16x16x32_bf16 v[158:161], v[58:61], v[138:141], v[158:161]
	v_mfma_f32_16x16x32_bf16 v[154:157], v[70:73], v[138:141], v[154:157]
	v_mfma_f32_16x16x32_bf16 v[126:129], v[58:61], v[146:149], v[126:129]
	v_mfma_f32_16x16x32_bf16 v[122:125], v[70:73], v[146:149], v[122:125]
	v_mfma_f32_16x16x32_bf16 v[110:113], v[58:61], v[162:165], v[110:113]
	v_mfma_f32_16x16x32_bf16 v[106:109], v[70:73], v[162:165], v[106:109]
	v_mfma_f32_16x16x32_bf16 v[94:97], v[58:61], v[170:173], v[94:97]
	v_mfma_f32_16x16x32_bf16 v[90:93], v[70:73], v[170:173], v[90:93]
	v_mfma_f32_16x16x32_bf16 v[158:161], v[62:65], v[142:145], v[158:161]
	v_mfma_f32_16x16x32_bf16 v[154:157], v[74:77], v[142:145], v[154:157]
	v_mfma_f32_16x16x32_bf16 v[126:129], v[62:65], v[150:153], v[126:129]
	v_mfma_f32_16x16x32_bf16 v[122:125], v[74:77], v[150:153], v[122:125]
	v_mfma_f32_16x16x32_bf16 v[110:113], v[62:65], v[166:169], v[110:113]
	v_mfma_f32_16x16x32_bf16 v[106:109], v[74:77], v[166:169], v[106:109]
	v_mfma_f32_16x16x32_bf16 v[94:97], v[62:65], v[184:187], v[94:97]
	v_mfma_f32_16x16x32_bf16 v[90:93], v[74:77], v[184:187], v[90:93]
	s_barrier
	s_add_i32 s44, 0, 0x1c000
	s_add_i32 s45, s52, s20
	v_add_u32_e32 v197, s44, v194
	v_lshl_add_u64 v[192:193], v[192:193], 0, s[76:77]
	s_mov_b32 m0, s45
	ds_read_b128 v[188:191], v197
	ds_read_b128 v[220:223], v197 offset:1024
	ds_read_b128 v[224:227], v197 offset:2048
	ds_read_b128 v[228:231], v197 offset:3072
	global_load_lds_dwordx4 v[192:193], off
	s_add_i32 m0, s45, 0x2000
	v_lshl_add_u64 v[192:193], v[198:199], 0, s[76:77]
	global_load_lds_dwordx4 v[192:193], off
	s_barrier
; #define PG8_STAGE(bufoff, gbase, voff) do { _Pragma("unroll") for (int _i = 0; _i < 2; ++_i) \
;         __builtin_amdgcn_global_load_lds((const unsigned*)((const char*)(gbase) + (voff)[_i]), (LAS unsigned*)(lds + (bufoff) + ldsw + _i * 8192), 16, 0, 0); } while (0)
; #define PG8_LDA(dst, b, h) do { _Pragma("unroll") for (int m = 0; m < 4; ++m) _Pragma("unroll") for (int k = 0; k < 2; ++k) dst[m][k] = *(const LAS bf16x8*)(lds + PG8_SA(b, h) + aoff + m * 2048 + k * 1024); } while (0)
; #define PG8_MMA(ai, bj, At, Bt) do { __builtin_amdgcn_s_setprio(1); _Pragma("unroll") for (int m = 0; m < 4; ++m) _Pragma("unroll") for (int n = 0; n < 2; ++n) _Pragma("unroll") for (int k = 0; k < 2; ++k) \
;         acc[ai][bj][m][n] = __builtin_amdgcn_mfma_f32_16x16x32_bf16(Bt[n][k], At[m][k], acc[ai][bj][m][n], 0, 0, 0); __builtin_amdgcn_s_setprio(0); } while (0)
; #define PG8_WAIT_V(n) asm volatile("s_waitcnt vmcnt(" #n ")" ::: "memory")
; #define PG8_WAIT_L(n) asm volatile("s_waitcnt lgkmcnt(" #n ")" ::: "memory")
; #define PG8_BAR __builtin_amdgcn_s_barrier()
; #define PG8_SCHED __builtin_amdgcn_sched_barrier(0)
;     template <int mode> __device__ __forceinline__ void run(const f32x4 (&acc)[2][2][4][2], const Unit& u, int wr, int wc, int fr, int fq, const LAS float* sc) const {
;     ...
;             const int col0 = u.pn * BM + wc * 32 + 8 * fq;
;             f32x4 bv[2][2];
; #pragma unroll
;             for (int bj = 0; bj < 2; ++bj)
; #pragma unroll
;                 for (int n = 0; n < 2; ++n) bv[bj][n] = bias ? *(const f32x4*)(bias + col0 + bj * HALF + 4 * n) : (f32x4){0.f, 0.f, 0.f, 0.f};
; template <int MODE, class EpiT, class Sched>
; __device__ __forceinline__ void gemm_phase(LAS unsigned char* lds, const Gemm g, const Sched& S, const EpiT& E) {
;     ...
;             PG8_BAR; PG8_WAIT_L(0); PG8_MMA(0, 1, At, B1); PG8_BAR;
;             PG8_LDA(At, 1, 1); PG8_STAGE(PG8_SA(1, 0), a3, voffA);
;             PG8_BAR; PG8_WAIT_L(0); PG8_MMA(1, 0, At, B0); PG8_BAR; PG8_SCHED;
;             PG8_STAGE(PG8_SB(1, 1), b3 + hstep, voffB);
;             PG8_WAIT_V(6); PG8_BAR; PG8_MMA(1, 1, At, B1); PG8_BAR;
;         }
;         E.template run<MODE>(acc, cur, wr, wc, fr, fq, SC + ui * 256);
;         if (!has_next) break;
	s_waitcnt lgkmcnt(0)
	v_mfma_f32_16x16x32_bf16 v[134:137], v[188:191], v[138:141], v[134:137]
	v_mfma_f32_16x16x32_bf16 v[130:133], v[224:227], v[138:141], v[130:133]
	v_mfma_f32_16x16x32_bf16 v[118:121], v[188:191], v[146:149], v[118:121]
	v_mfma_f32_16x16x32_bf16 v[114:117], v[224:227], v[146:149], v[114:117]
	v_mfma_f32_16x16x32_bf16 v[102:105], v[188:191], v[162:165], v[102:105]
	v_mfma_f32_16x16x32_bf16 v[98:101], v[224:227], v[162:165], v[98:101]
	v_mfma_f32_16x16x32_bf16 v[86:89], v[188:191], v[170:173], v[86:89]
	v_mfma_f32_16x16x32_bf16 v[82:85], v[224:227], v[170:173], v[82:85]
	v_mfma_f32_16x16x32_bf16 v[134:137], v[220:223], v[142:145], v[134:137]
	v_mfma_f32_16x16x32_bf16 v[130:133], v[228:231], v[142:145], v[130:133]
	v_mfma_f32_16x16x32_bf16 v[118:121], v[220:223], v[150:153], v[118:121]
	v_mfma_f32_16x16x32_bf16 v[114:117], v[228:231], v[150:153], v[114:117]
	v_mfma_f32_16x16x32_bf16 v[102:105], v[220:223], v[166:169], v[102:105]
	v_mfma_f32_16x16x32_bf16 v[98:101], v[228:231], v[166:169], v[98:101]
	v_mfma_f32_16x16x32_bf16 v[86:89], v[220:223], v[184:187], v[86:89]
	v_mfma_f32_16x16x32_bf16 v[82:85], v[228:231], v[184:187], v[82:85]
	s_barrier
	s_mov_b32 m0, s61
	v_lshl_add_u64 v[192:193], v[232:233], 0, s[76:77]
	ds_read_b128 v[138:141], v196 offset:49152
	ds_read_b128 v[142:145], v196 offset:50176
	ds_read_b128 v[146:149], v196 offset:51200
	ds_read_b128 v[150:153], v196 offset:52224
	ds_read_b128 v[162:165], v196 offset:53248
	ds_read_b128 v[166:169], v196 offset:54272
	ds_read_b128 v[170:173], v196 offset:55296
	ds_read_b128 v[184:187], v196 offset:56320
	global_load_lds_dwordx4 v[192:193], off
	s_mov_b32 m0, s74
	v_lshl_add_u64 v[192:193], v[234:235], 0, s[76:77]
	global_load_lds_dwordx4 v[192:193], off
	s_barrier
	s_waitcnt lgkmcnt(0)
	v_mfma_f32_16x16x32_bf16 v[78:81], v[58:61], v[138:141], v[78:81]
	v_mfma_f32_16x16x32_bf16 v[66:69], v[70:73], v[138:141], v[66:69]
	v_mfma_f32_16x16x32_bf16 v[46:49], v[58:61], v[146:149], v[46:49]
	v_mfma_f32_16x16x32_bf16 v[42:45], v[70:73], v[146:149], v[42:45]
	v_mfma_f32_16x16x32_bf16 v[30:33], v[58:61], v[162:165], v[30:33]
	v_mfma_f32_16x16x32_bf16 v[26:29], v[70:73], v[162:165], v[26:29]
	v_mfma_f32_16x16x32_bf16 v[14:17], v[58:61], v[170:173], v[14:17]
	v_mfma_f32_16x16x32_bf16 v[10:13], v[70:73], v[170:173], v[10:13]
	v_mfma_f32_16x16x32_bf16 v[78:81], v[62:65], v[142:145], v[78:81]
	v_mfma_f32_16x16x32_bf16 v[66:69], v[74:77], v[142:145], v[66:69]
	v_mfma_f32_16x16x32_bf16 v[46:49], v[62:65], v[150:153], v[46:49]
	v_mfma_f32_16x16x32_bf16 v[42:45], v[74:77], v[150:153], v[42:45]
	v_mfma_f32_16x16x32_bf16 v[30:33], v[62:65], v[166:169], v[30:33]
	v_mfma_f32_16x16x32_bf16 v[26:29], v[74:77], v[166:169], v[26:29]
	v_mfma_f32_16x16x32_bf16 v[14:17], v[62:65], v[184:187], v[14:17]
	v_mfma_f32_16x16x32_bf16 v[10:13], v[74:77], v[184:187], v[10:13]
	s_barrier
	s_add_i32 s44, s44, s20
	s_mov_b32 m0, s44
	v_lshl_add_u64 v[58:59], v[236:237], 0, s[76:77]
	global_load_lds_dwordx4 v[58:59], off
	s_add_i32 m0, s44, 0x2000
	v_lshl_add_u64 v[58:59], v[238:239], 0, s[76:77]
	global_load_lds_dwordx4 v[58:59], off
	s_waitcnt vmcnt(6)
	s_barrier
	v_mfma_f32_16x16x32_bf16 v[54:57], v[188:191], v[138:141], v[54:57]
	v_mfma_f32_16x16x32_bf16 v[50:53], v[224:227], v[138:141], v[50:53]
	v_mfma_f32_16x16x32_bf16 v[38:41], v[188:191], v[146:149], v[38:41]
	v_mfma_f32_16x16x32_bf16 v[34:37], v[224:227], v[146:149], v[34:37]
	v_mfma_f32_16x16x32_bf16 v[22:25], v[188:191], v[162:165], v[22:25]
	v_mfma_f32_16x16x32_bf16 v[18:21], v[224:227], v[162:165], v[18:21]
	v_mfma_f32_16x16x32_bf16 v[6:9], v[188:191], v[170:173], v[6:9]
	v_mfma_f32_16x16x32_bf16 v[2:5], v[224:227], v[170:173], v[2:5]
	v_mfma_f32_16x16x32_bf16 v[54:57], v[220:223], v[142:145], v[54:57]
	v_mfma_f32_16x16x32_bf16 v[50:53], v[228:231], v[142:145], v[50:53]
	v_mfma_f32_16x16x32_bf16 v[38:41], v[220:223], v[150:153], v[38:41]
	v_mfma_f32_16x16x32_bf16 v[34:37], v[228:231], v[150:153], v[34:37]
	v_mfma_f32_16x16x32_bf16 v[22:25], v[220:223], v[166:169], v[22:25]
	v_mfma_f32_16x16x32_bf16 v[18:21], v[228:231], v[166:169], v[18:21]
	v_mfma_f32_16x16x32_bf16 v[6:9], v[220:223], v[184:187], v[6:9]
	v_mfma_f32_16x16x32_bf16 v[2:5], v[228:231], v[184:187], v[2:5]
	s_barrier
	s_add_u32 s4, s4, 0x100
	s_addc_u32 s5, s5, 0
	s_add_u32 s89, s89, 0x100
	s_addc_u32 s90, s90, 0
	s_cmp_ge_u32 vcc_lo, s60
	s_mov_b32 s44, vcc_lo
	s_cbranch_scc0 .LBB0_195
	v_lshl_or_b32 v186, s24, 8, v195
	v_ashrrev_i32_e32 v187, 31, v186
	v_mov_b32_e32 v70, 0
	v_cndmask_b32_e64 v58, 0, 1, s[78:79]
	v_lshl_add_u64 v[138:139], v[186:187], 2, s[12:13]
	v_cmp_ne_u32_e64 s[44:45], 1, v58
	s_andn2_b64 vcc, exec, s[78:79]
	v_mov_b32_e32 v74, 0
	v_mov_b32_e32 v75, v70
	v_mov_b32_e32 v184, 0
	v_mov_b32_e32 v185, v70
	s_cbranch_vccnz .LBB0_198
	global_load_dwordx4 v[74:77], v[138:139], off
	s_waitcnt vmcnt(0)
	v_mov_b32_e32 v184, v76
	v_mov_b32_e32 v185, v77

; #define PG8_STAGE(bufoff, gbase, voff) do { _Pragma("unroll") for (int _i = 0; _i < 2; ++_i) \
;         __builtin_amdgcn_global_load_lds((const unsigned*)((const char*)(gbase) + (voff)[_i]), (LAS unsigned*)(lds + (bufoff) + ldsw + _i * 8192), 16, 0, 0); } while (0)
; #define PG8_LDA(dst, b, h) do { _Pragma("unroll") for (int m = 0; m < 4; ++m) _Pragma("unroll") for (int k = 0; k < 2; ++k) dst[m][k] = *(const LAS bf16x8*)(lds + PG8_SA(b, h) + aoff + m * 2048 + k * 1024); } while (0)
; #define PG8_LDB(dst, b, h) do { _Pragma("unroll") for (int n = 0; n < 2; ++n) _Pragma("unroll") for (int k = 0; k < 2; ++k) dst[n][k] = *(const LAS bf16x8*)(lds + PG8_SB(b, h) + boff + n * 2048 + k * 1024); } while (0)
; #define PG8_MMA(ai, bj, At, Bt) do { __builtin_amdgcn_s_setprio(1); _Pragma("unroll") for (int m = 0; m < 4; ++m) _Pragma("unroll") for (int n = 0; n < 2; ++n) _Pragma("unroll") for (int k = 0; k < 2; ++k) \
;         acc[ai][bj][m][n] = __builtin_amdgcn_mfma_f32_16x16x32_bf16(Bt[n][k], At[m][k], acc[ai][bj][m][n], 0, 0, 0); __builtin_amdgcn_s_setprio(0); } while (0)
; #define PG8_WAIT_L(n) asm volatile("s_waitcnt lgkmcnt(" #n ")" ::: "memory")
; #define PG8_BAR __builtin_amdgcn_s_barrier()
; #define PG8_SCHED __builtin_amdgcn_sched_barrier(0)
; template <int MODE, class EpiT, class Sched>
; __device__ __forceinline__ void gemm_phase(LAS unsigned char* lds, const Gemm g, const Sched& S, const EpiT& E) {
;     ...
;             PG8_LDB(B0, 0, 0); PG8_SCHED; PG8_LDA(At, 0, 0); PG8_STAGE(PG8_SA(1, 1), a1 + hstep, voffA);
;             PG8_WAIT_L(8); PG8_BAR; PG8_WAIT_L(0); PG8_MMA(0, 0, At, B0); PG8_BAR; PG8_SCHED;
;             PG8_LDB(B1, 0, 1); PG8_STAGE(PG8_SB(0, 0), b2, voffB);
;             PG8_BAR; PG8_WAIT_L(0); PG8_MMA(0, 1, At, B1); PG8_BAR;
;             PG8_LDA(At, 0, 1); PG8_STAGE(PG8_SA(0, 0), a2, voffA);
;             PG8_BAR; PG8_WAIT_L(0); PG8_MMA(1, 0, At, B0); PG8_BAR; PG8_SCHED;
.LBB0_236:
	s_add_i32 s44, s34, 2
	s_add_u32 s38, s28, 0x80
	s_addc_u32 s35, s29, 0
	s_add_i32 s45, 0, 0x10000
	v_add_u32_e32 v136, s45, v139
	ds_read_b128 v[142:145], v136
	ds_read_b128 v[146:149], v136 offset:1024
	ds_read_b128 v[150:153], v136 offset:2048
	ds_read_b128 v[154:157], v136 offset:3072
	s_cmp_eq_u32 s52, s34
	s_cselect_b32 s34, s4, s38
	s_cselect_b32 s35, s5, s35
	s_cselect_b32 s39, s11, s43
	s_cselect_b32 s38, s10, s42
	v_lshl_add_u64 v[136:137], s[28:29], 0, v[132:133]
	s_add_i32 m0, s22, 0xc000
	ds_read_b128 v[158:161], v141
	ds_read_b128 v[162:165], v141 offset:1024
	ds_read_b128 v[166:169], v141 offset:2048
	ds_read_b128 v[170:173], v141 offset:3072
	ds_read_b128 v[174:177], v141 offset:4096
	ds_read_b128 v[182:185], v141 offset:5120
	ds_read_b128 v[186:189], v141 offset:6144
	ds_read_b128 v[190:193], v141 offset:7168
	global_load_lds_dwordx4 v[136:137], off
	s_add_i32 m0, s22, 0xe000
	v_lshl_add_u64 v[136:137], s[28:29], 0, v[134:135]
	global_load_lds_dwordx4 v[136:137], off
	s_waitcnt lgkmcnt(8)
	s_barrier
	s_waitcnt lgkmcnt(0)
	v_mfma_f32_16x16x32_bf16 v[126:129], v[142:145], v[158:161], v[126:129]
	v_mfma_f32_16x16x32_bf16 v[122:125], v[150:153], v[158:161], v[122:125]
	v_mfma_f32_16x16x32_bf16 v[118:121], v[142:145], v[166:169], v[118:121]
	v_mfma_f32_16x16x32_bf16 v[110:113], v[150:153], v[166:169], v[110:113]
	v_mfma_f32_16x16x32_bf16 v[102:105], v[142:145], v[174:177], v[102:105]
	v_mfma_f32_16x16x32_bf16 v[94:97], v[150:153], v[174:177], v[94:97]
	v_mfma_f32_16x16x32_bf16 v[86:89], v[142:145], v[186:189], v[86:89]
	v_mfma_f32_16x16x32_bf16 v[78:81], v[150:153], v[186:189], v[78:81]
	v_mfma_f32_16x16x32_bf16 v[126:129], v[146:149], v[162:165], v[126:129]
	v_mfma_f32_16x16x32_bf16 v[122:125], v[154:157], v[162:165], v[122:125]
	v_mfma_f32_16x16x32_bf16 v[118:121], v[146:149], v[170:173], v[118:121]
	v_mfma_f32_16x16x32_bf16 v[110:113], v[154:157], v[170:173], v[110:113]
	v_mfma_f32_16x16x32_bf16 v[102:105], v[146:149], v[182:185], v[102:105]
	v_mfma_f32_16x16x32_bf16 v[94:97], v[154:157], v[182:185], v[94:97]
	v_mfma_f32_16x16x32_bf16 v[86:89], v[146:149], v[190:193], v[86:89]
	v_mfma_f32_16x16x32_bf16 v[78:81], v[154:157], v[190:193], v[78:81]
	s_barrier
	s_add_i32 s58, 0, 0x14000
	v_add_u32_e32 v136, s58, v139
	s_add_i32 s45, s45, s9
	ds_read_b128 v[194:197], v136
	ds_read_b128 v[220:223], v136 offset:1024
	ds_read_b128 v[224:227], v136 offset:2048
	ds_read_b128 v[228:231], v136 offset:3072
	v_lshl_add_u64 v[136:137], s[38:39], 0, v[0:1]
	s_mov_b32 m0, s45
	global_load_lds_dwordx4 v[136:137], off
	s_add_i32 m0, s45, 0x2000
	v_lshl_add_u64 v[198:199], s[38:39], 0, v[130:131]
	global_load_lds_dwordx4 v[198:199], off
	s_barrier
	s_waitcnt lgkmcnt(0)
	v_mfma_f32_16x16x32_bf16 v[114:117], v[194:197], v[158:161], v[114:117]
	v_mfma_f32_16x16x32_bf16 v[106:109], v[224:227], v[158:161], v[106:109]
	v_mfma_f32_16x16x32_bf16 v[98:101], v[194:197], v[166:169], v[98:101]
	v_mfma_f32_16x16x32_bf16 v[90:93], v[224:227], v[166:169], v[90:93]
	v_mfma_f32_16x16x32_bf16 v[82:85], v[194:197], v[174:177], v[82:85]
	v_mfma_f32_16x16x32_bf16 v[74:77], v[224:227], v[174:177], v[74:77]
	v_mfma_f32_16x16x32_bf16 v[70:73], v[194:197], v[186:189], v[70:73]
	v_mfma_f32_16x16x32_bf16 v[66:69], v[224:227], v[186:189], v[66:69]
	v_mfma_f32_16x16x32_bf16 v[114:117], v[220:223], v[162:165], v[114:117]
	v_mfma_f32_16x16x32_bf16 v[106:109], v[228:231], v[162:165], v[106:109]
	v_mfma_f32_16x16x32_bf16 v[98:101], v[220:223], v[170:173], v[98:101]
	v_mfma_f32_16x16x32_bf16 v[90:93], v[228:231], v[170:173], v[90:93]
	v_mfma_f32_16x16x32_bf16 v[82:85], v[220:223], v[182:185], v[82:85]
	v_mfma_f32_16x16x32_bf16 v[74:77], v[228:231], v[182:185], v[74:77]
	v_mfma_f32_16x16x32_bf16 v[70:73], v[220:223], v[190:193], v[70:73]
	v_mfma_f32_16x16x32_bf16 v[66:69], v[228:231], v[190:193], v[66:69]
	s_barrier
	s_mov_b32 m0, s22
	v_lshl_add_u64 v[232:233], s[34:35], 0, v[0:1]
	ds_read_b128 v[158:161], v141 offset:16384
	ds_read_b128 v[162:165], v141 offset:17408
	ds_read_b128 v[166:169], v141 offset:18432
	ds_read_b128 v[170:173], v141 offset:19456
	ds_read_b128 v[174:177], v141 offset:20480
	ds_read_b128 v[182:185], v141 offset:21504
	ds_read_b128 v[186:189], v141 offset:22528
	ds_read_b128 v[190:193], v141 offset:23552
	global_load_lds_dwordx4 v[232:233], off
	s_mov_b32 m0, s23
	v_lshl_add_u64 v[234:235], s[34:35], 0, v[130:131]
	global_load_lds_dwordx4 v[234:235], off
	s_barrier
	s_waitcnt lgkmcnt(0)
	v_mfma_f32_16x16x32_bf16 v[62:65], v[142:145], v[158:161], v[62:65]
	v_mfma_f32_16x16x32_bf16 v[58:61], v[150:153], v[158:161], v[58:61]
	v_mfma_f32_16x16x32_bf16 v[54:57], v[142:145], v[166:169], v[54:57]
	v_mfma_f32_16x16x32_bf16 v[46:49], v[150:153], v[166:169], v[46:49]
	v_mfma_f32_16x16x32_bf16 v[38:41], v[142:145], v[174:177], v[38:41]
	v_mfma_f32_16x16x32_bf16 v[30:33], v[150:153], v[174:177], v[30:33]
	v_mfma_f32_16x16x32_bf16 v[22:25], v[142:145], v[186:189], v[22:25]
	v_mfma_f32_16x16x32_bf16 v[14:17], v[150:153], v[186:189], v[14:17]
	v_mfma_f32_16x16x32_bf16 v[62:65], v[146:149], v[162:165], v[62:65]
	v_mfma_f32_16x16x32_bf16 v[58:61], v[154:157], v[162:165], v[58:61]
	v_mfma_f32_16x16x32_bf16 v[54:57], v[146:149], v[170:173], v[54:57]
	v_mfma_f32_16x16x32_bf16 v[46:49], v[154:157], v[170:173], v[46:49]
	v_mfma_f32_16x16x32_bf16 v[38:41], v[146:149], v[182:185], v[38:41]
	v_mfma_f32_16x16x32_bf16 v[30:33], v[154:157], v[182:185], v[30:33]
	v_mfma_f32_16x16x32_bf16 v[22:25], v[146:149], v[190:193], v[22:25]
	v_mfma_f32_16x16x32_bf16 v[14:17], v[154:157], v[190:193], v[14:17]
	s_barrier
; #define PG8_STAGE(bufoff, gbase, voff) do { _Pragma("unroll") for (int _i = 0; _i < 2; ++_i) \
;         __builtin_amdgcn_global_load_lds((const unsigned*)((const char*)(gbase) + (voff)[_i]), (LAS unsigned*)(lds + (bufoff) + ldsw + _i * 8192), 16, 0, 0); } while (0)
; #define PG8_LDA(dst, b, h) do { _Pragma("unroll") for (int m = 0; m < 4; ++m) _Pragma("unroll") for (int k = 0; k < 2; ++k) dst[m][k] = *(const LAS bf16x8*)(lds + PG8_SA(b, h) + aoff + m * 2048 + k * 1024); } while (0)
; #define PG8_LDB(dst, b, h) do { _Pragma("unroll") for (int n = 0; n < 2; ++n) _Pragma("unroll") for (int k = 0; k < 2; ++k) dst[n][k] = *(const LAS bf16x8*)(lds + PG8_SB(b, h) + boff + n * 2048 + k * 1024); } while (0)
; #define PG8_MMA(ai, bj, At, Bt) do { __builtin_amdgcn_s_setprio(1); _Pragma("unroll") for (int m = 0; m < 4; ++m) _Pragma("unroll") for (int n = 0; n < 2; ++n) _Pragma("unroll") for (int k = 0; k < 2; ++k) \
;         acc[ai][bj][m][n] = __builtin_amdgcn_mfma_f32_16x16x32_bf16(Bt[n][k], At[m][k], acc[ai][bj][m][n], 0, 0, 0); __builtin_amdgcn_s_setprio(0); } while (0)
; #define PG8_WAIT_V(n) asm volatile("s_waitcnt vmcnt(" #n ")" ::: "memory")
; #define PG8_WAIT_L(n) asm volatile("s_waitcnt lgkmcnt(" #n ")" ::: "memory")
; #define PG8_BAR __builtin_amdgcn_s_barrier()
; #define PG8_SCHED __builtin_amdgcn_sched_barrier(0)
; template <int MODE, class EpiT, class Sched>
; __device__ __forceinline__ void gemm_phase(LAS unsigned char* lds, const Gemm g, const Sched& S, const EpiT& E) {
;     ...
;             PG8_STAGE(PG8_SB(0, 1), b2 + hstep, voffB);
;             PG8_WAIT_V(6); PG8_BAR; PG8_MMA(1, 1, At, B1); PG8_BAR;
;             PG8_LDB(B0, 1, 0); PG8_SCHED; PG8_LDA(At, 1, 0); PG8_STAGE(PG8_SA(0, 1), a2 + hstep, voffA);
;             PG8_WAIT_L(8); PG8_BAR; PG8_WAIT_L(0); PG8_MMA(0, 0, At, B0); PG8_BAR; PG8_SCHED;
;             PG8_LDB(B1, 1, 1); PG8_STAGE(PG8_SB(1, 0), b3, voffB);
;             PG8_BAR; PG8_WAIT_L(0); PG8_MMA(0, 1, At, B1); PG8_BAR;
;             PG8_LDA(At, 1, 1); PG8_STAGE(PG8_SA(1, 0), a3, voffA);
;             PG8_BAR; PG8_WAIT_L(0); PG8_MMA(1, 0, At, B0); PG8_BAR; PG8_SCHED;
	s_add_u32 s38, s38, s24
	s_addc_u32 s39, s39, 0
	s_add_i32 s45, s58, s9
	v_lshl_add_u64 v[236:237], s[38:39], 0, v[0:1]
	s_mov_b32 m0, s45
	global_load_lds_dwordx4 v[236:237], off
	s_add_i32 m0, s45, 0x2000
	v_lshl_add_u64 v[238:239], s[38:39], 0, v[130:131]
	global_load_lds_dwordx4 v[238:239], off
	s_waitcnt vmcnt(6)
	s_barrier
	v_mfma_f32_16x16x32_bf16 v[50:53], v[194:197], v[158:161], v[50:53]
	v_mfma_f32_16x16x32_bf16 v[42:45], v[224:227], v[158:161], v[42:45]
	v_mfma_f32_16x16x32_bf16 v[34:37], v[194:197], v[166:169], v[34:37]
	v_mfma_f32_16x16x32_bf16 v[26:29], v[224:227], v[166:169], v[26:29]
	v_mfma_f32_16x16x32_bf16 v[18:21], v[194:197], v[174:177], v[18:21]
	v_mfma_f32_16x16x32_bf16 v[10:13], v[224:227], v[174:177], v[10:13]
	v_mfma_f32_16x16x32_bf16 v[6:9], v[194:197], v[186:189], v[6:9]
	v_mfma_f32_16x16x32_bf16 v[2:5], v[224:227], v[186:189], v[2:5]
	v_mfma_f32_16x16x32_bf16 v[50:53], v[220:223], v[162:165], v[50:53]
	v_mfma_f32_16x16x32_bf16 v[42:45], v[228:231], v[162:165], v[42:45]
	v_mfma_f32_16x16x32_bf16 v[34:37], v[220:223], v[170:173], v[34:37]
	v_mfma_f32_16x16x32_bf16 v[26:29], v[228:231], v[170:173], v[26:29]
	v_mfma_f32_16x16x32_bf16 v[18:21], v[220:223], v[182:185], v[18:21]
	v_mfma_f32_16x16x32_bf16 v[10:13], v[228:231], v[182:185], v[10:13]
	v_mfma_f32_16x16x32_bf16 v[6:9], v[220:223], v[190:193], v[6:9]
	v_mfma_f32_16x16x32_bf16 v[2:5], v[228:231], v[190:193], v[2:5]
	s_barrier
	s_add_i32 s38, 0, 0x18000
	v_add_u32_e32 v154, s38, v139
	ds_read_b128 v[142:145], v154
	ds_read_b128 v[146:149], v154 offset:1024
	ds_read_b128 v[150:153], v154 offset:2048
	ds_read_b128 v[154:157], v154 offset:3072
	s_add_u32 s34, s34, s24
	s_addc_u32 s35, s35, 0
	s_mov_b32 m0, s30
	v_lshl_add_u64 v[194:195], s[34:35], 0, v[0:1]
	ds_read_b128 v[158:161], v141 offset:32768
	ds_read_b128 v[162:165], v141 offset:33792
	ds_read_b128 v[166:169], v141 offset:34816
	ds_read_b128 v[170:173], v141 offset:35840
	ds_read_b128 v[174:177], v141 offset:36864
	ds_read_b128 v[182:185], v141 offset:37888
	ds_read_b128 v[186:189], v141 offset:38912
	ds_read_b128 v[190:193], v141 offset:39936
	global_load_lds_dwordx4 v[194:195], off
	s_mov_b32 m0, s46
	v_lshl_add_u64 v[194:195], s[34:35], 0, v[130:131]
	global_load_lds_dwordx4 v[194:195], off
	s_waitcnt lgkmcnt(8)
	s_barrier
	s_waitcnt lgkmcnt(0)
	v_mfma_f32_16x16x32_bf16 v[126:129], v[142:145], v[158:161], v[126:129]
	v_mfma_f32_16x16x32_bf16 v[122:125], v[150:153], v[158:161], v[122:125]
	v_mfma_f32_16x16x32_bf16 v[118:121], v[142:145], v[166:169], v[118:121]
	v_mfma_f32_16x16x32_bf16 v[110:113], v[150:153], v[166:169], v[110:113]
	v_mfma_f32_16x16x32_bf16 v[102:105], v[142:145], v[174:177], v[102:105]
	v_mfma_f32_16x16x32_bf16 v[94:97], v[150:153], v[174:177], v[94:97]
	v_mfma_f32_16x16x32_bf16 v[86:89], v[142:145], v[186:189], v[86:89]
	v_mfma_f32_16x16x32_bf16 v[78:81], v[150:153], v[186:189], v[78:81]
	v_mfma_f32_16x16x32_bf16 v[126:129], v[146:149], v[162:165], v[126:129]
	v_mfma_f32_16x16x32_bf16 v[122:125], v[154:157], v[162:165], v[122:125]
	v_mfma_f32_16x16x32_bf16 v[118:121], v[146:149], v[170:173], v[118:121]
	v_mfma_f32_16x16x32_bf16 v[110:113], v[154:157], v[170:173], v[110:113]
	v_mfma_f32_16x16x32_bf16 v[102:105], v[146:149], v[182:185], v[102:105]
	v_mfma_f32_16x16x32_bf16 v[94:97], v[154:157], v[182:185], v[94:97]
	v_mfma_f32_16x16x32_bf16 v[86:89], v[146:149], v[190:193], v[86:89]
	v_mfma_f32_16x16x32_bf16 v[78:81], v[154:157], v[190:193], v[78:81]
	s_barrier
	s_add_i32 s34, 0, 0x1c000
	s_add_i32 s35, s38, s9
	v_add_u32_e32 v181, s34, v139
	v_lshl_add_u64 v[136:137], v[136:137], 0, s[76:77]
	s_mov_b32 m0, s35
	ds_read_b128 v[194:197], v181
	ds_read_b128 v[220:223], v181 offset:1024
	ds_read_b128 v[224:227], v181 offset:2048
	ds_read_b128 v[228:231], v181 offset:3072
	global_load_lds_dwordx4 v[136:137], off
	s_add_i32 m0, s35, 0x2000
	v_lshl_add_u64 v[136:137], v[198:199], 0, s[76:77]
	global_load_lds_dwordx4 v[136:137], off
	s_barrier
	s_waitcnt lgkmcnt(0)
	v_mfma_f32_16x16x32_bf16 v[114:117], v[194:197], v[158:161], v[114:117]
	v_mfma_f32_16x16x32_bf16 v[106:109], v[224:227], v[158:161], v[106:109]
	v_mfma_f32_16x16x32_bf16 v[98:101], v[194:197], v[166:169], v[98:101]
	v_mfma_f32_16x16x32_bf16 v[90:93], v[224:227], v[166:169], v[90:93]
	v_mfma_f32_16x16x32_bf16 v[82:85], v[194:197], v[174:177], v[82:85]
	v_mfma_f32_16x16x32_bf16 v[74:77], v[224:227], v[174:177], v[74:77]
	v_mfma_f32_16x16x32_bf16 v[70:73], v[194:197], v[186:189], v[70:73]
	v_mfma_f32_16x16x32_bf16 v[66:69], v[224:227], v[186:189], v[66:69]
	v_mfma_f32_16x16x32_bf16 v[114:117], v[220:223], v[162:165], v[114:117]
	v_mfma_f32_16x16x32_bf16 v[106:109], v[228:231], v[162:165], v[106:109]
	v_mfma_f32_16x16x32_bf16 v[98:101], v[220:223], v[170:173], v[98:101]
	v_mfma_f32_16x16x32_bf16 v[90:93], v[228:231], v[170:173], v[90:93]
	v_mfma_f32_16x16x32_bf16 v[82:85], v[220:223], v[182:185], v[82:85]
	v_mfma_f32_16x16x32_bf16 v[74:77], v[228:231], v[182:185], v[74:77]
	v_mfma_f32_16x16x32_bf16 v[70:73], v[220:223], v[190:193], v[70:73]
	v_mfma_f32_16x16x32_bf16 v[66:69], v[228:231], v[190:193], v[66:69]
	s_barrier
	s_mov_b32 m0, s50
	v_lshl_add_u64 v[136:137], v[232:233], 0, s[76:77]
	ds_read_b128 v[158:161], v141 offset:49152
	ds_read_b128 v[162:165], v141 offset:50176
	ds_read_b128 v[166:169], v141 offset:51200
	ds_read_b128 v[170:173], v141 offset:52224
	ds_read_b128 v[174:177], v141 offset:53248
	ds_read_b128 v[182:185], v141 offset:54272
	ds_read_b128 v[186:189], v141 offset:55296
	ds_read_b128 v[190:193], v141 offset:56320
	global_load_lds_dwordx4 v[136:137], off
	s_mov_b32 m0, s51
	v_lshl_add_u64 v[136:137], v[234:235], 0, s[76:77]
	global_load_lds_dwordx4 v[136:137], off
	s_barrier
; #define PG8_STAGE(bufoff, gbase, voff) do { _Pragma("unroll") for (int _i = 0; _i < 2; ++_i) \
;         __builtin_amdgcn_global_load_lds((const unsigned*)((const char*)(gbase) + (voff)[_i]), (LAS unsigned*)(lds + (bufoff) + ldsw + _i * 8192), 16, 0, 0); } while (0)
; #define PG8_MMA(ai, bj, At, Bt) do { __builtin_amdgcn_s_setprio(1); _Pragma("unroll") for (int m = 0; m < 4; ++m) _Pragma("unroll") for (int n = 0; n < 2; ++n) _Pragma("unroll") for (int k = 0; k < 2; ++k) \
;         acc[ai][bj][m][n] = __builtin_amdgcn_mfma_f32_16x16x32_bf16(Bt[n][k], At[m][k], acc[ai][bj][m][n], 0, 0, 0); __builtin_amdgcn_s_setprio(0); } while (0)
; #define PG8_WAIT_V(n) asm volatile("s_waitcnt vmcnt(" #n ")" ::: "memory")
; #define PG8_WAIT_L(n) asm volatile("s_waitcnt lgkmcnt(" #n ")" ::: "memory")
; #define PG8_BAR __builtin_amdgcn_s_barrier()
; #define PG8_SCHED __builtin_amdgcn_sched_barrier(0)
; template <int MODE, class EpiT, class Sched>
; __device__ __forceinline__ void gemm_phase(LAS unsigned char* lds, const Gemm g, const Sched& S, const EpiT& E) {
;     ...
;             PG8_BAR; PG8_WAIT_L(0); PG8_MMA(1, 0, At, B0); PG8_BAR; PG8_SCHED;
;             PG8_STAGE(PG8_SB(1, 1), b3 + hstep, voffB);
;             PG8_WAIT_V(6); PG8_BAR; PG8_MMA(1, 1, At, B1); PG8_BAR;
	s_waitcnt lgkmcnt(0)
	v_mfma_f32_16x16x32_bf16 v[62:65], v[142:145], v[158:161], v[62:65]
	v_mfma_f32_16x16x32_bf16 v[58:61], v[150:153], v[158:161], v[58:61]
	v_mfma_f32_16x16x32_bf16 v[54:57], v[142:145], v[166:169], v[54:57]
	v_mfma_f32_16x16x32_bf16 v[46:49], v[150:153], v[166:169], v[46:49]
	v_mfma_f32_16x16x32_bf16 v[38:41], v[142:145], v[174:177], v[38:41]
	v_mfma_f32_16x16x32_bf16 v[30:33], v[150:153], v[174:177], v[30:33]
	v_mfma_f32_16x16x32_bf16 v[22:25], v[142:145], v[186:189], v[22:25]
	v_mfma_f32_16x16x32_bf16 v[14:17], v[150:153], v[186:189], v[14:17]
	v_mfma_f32_16x16x32_bf16 v[62:65], v[146:149], v[162:165], v[62:65]
	v_mfma_f32_16x16x32_bf16 v[58:61], v[154:157], v[162:165], v[58:61]
	v_mfma_f32_16x16x32_bf16 v[54:57], v[146:149], v[170:173], v[54:57]
	v_mfma_f32_16x16x32_bf16 v[46:49], v[154:157], v[170:173], v[46:49]
	v_mfma_f32_16x16x32_bf16 v[38:41], v[146:149], v[182:185], v[38:41]
	v_mfma_f32_16x16x32_bf16 v[30:33], v[154:157], v[182:185], v[30:33]
	v_mfma_f32_16x16x32_bf16 v[22:25], v[146:149], v[190:193], v[22:25]
	v_mfma_f32_16x16x32_bf16 v[14:17], v[154:157], v[190:193], v[14:17]
	s_barrier
	s_add_i32 s34, s34, s9
	s_mov_b32 m0, s34
	v_lshl_add_u64 v[136:137], v[236:237], 0, s[76:77]
	global_load_lds_dwordx4 v[136:137], off
	s_add_i32 m0, s34, 0x2000
	v_lshl_add_u64 v[136:137], v[238:239], 0, s[76:77]
	global_load_lds_dwordx4 v[136:137], off
	s_waitcnt vmcnt(6)
	s_barrier
	v_mfma_f32_16x16x32_bf16 v[50:53], v[194:197], v[158:161], v[50:53]
	v_mfma_f32_16x16x32_bf16 v[42:45], v[224:227], v[158:161], v[42:45]
	v_mfma_f32_16x16x32_bf16 v[34:37], v[194:197], v[166:169], v[34:37]
	v_mfma_f32_16x16x32_bf16 v[26:29], v[224:227], v[166:169], v[26:29]
	v_mfma_f32_16x16x32_bf16 v[18:21], v[194:197], v[174:177], v[18:21]
	v_mfma_f32_16x16x32_bf16 v[10:13], v[224:227], v[174:177], v[10:13]
	v_mfma_f32_16x16x32_bf16 v[6:9], v[194:197], v[186:189], v[6:9]
	v_mfma_f32_16x16x32_bf16 v[2:5], v[224:227], v[186:189], v[2:5]
	v_mfma_f32_16x16x32_bf16 v[50:53], v[220:223], v[162:165], v[50:53]
	v_mfma_f32_16x16x32_bf16 v[42:45], v[228:231], v[162:165], v[42:45]
	v_mfma_f32_16x16x32_bf16 v[34:37], v[220:223], v[170:173], v[34:37]
	v_mfma_f32_16x16x32_bf16 v[26:29], v[228:231], v[170:173], v[26:29]
	v_mfma_f32_16x16x32_bf16 v[18:21], v[220:223], v[182:185], v[18:21]
	v_mfma_f32_16x16x32_bf16 v[10:13], v[228:231], v[182:185], v[10:13]
	v_mfma_f32_16x16x32_bf16 v[6:9], v[220:223], v[190:193], v[6:9]
	v_mfma_f32_16x16x32_bf16 v[2:5], v[228:231], v[190:193], v[2:5]
	s_barrier
	s_add_u32 s28, s28, 0x100
	s_addc_u32 s29, s29, 0
	s_add_u32 s42, s42, 0x100
	s_addc_u32 s43, s43, 0
	s_cmp_ge_u32 s44, s47
	s_mov_b32 s34, s44
	s_cbranch_scc0 .LBB0_236
; __device__ __forceinline__ unsigned pk2(float lo, float hi) { unsigned r; asm volatile("v_cvt_pk_bf16_f32 %0, %1, %2" : "=v"(r) : "v"(lo), "v"(hi)); return r; }
; #define PG8_WAIT_V(n) asm volatile("s_waitcnt vmcnt(" #n ")" ::: "memory")
; #define PG8_BAR __builtin_amdgcn_s_barrier()
;     template <int mode> __device__ __forceinline__ void run(const f32x4 (&acc)[2][2][4][2], const Unit& u, int wr, int wc, int fr, int fq, const LAS float* sc) const {
;     ...
;             const int col0 = u.pn * BM + wc * 32 + 8 * fq;
; #pragma unroll
;             for (int ai = 0; ai < 2; ++ai)
; #pragma unroll
;                 for (int m = 0; m < 4; ++m) {
;                     bf16_t* rowp = ob + (size_t)(row0 + ai * HALF + m * 16) * D + col0;
; #pragma unroll
;                     for (int bj = 0; bj < 2; ++bj) {
;                         const f32x4 v0 = acc[ai][bj][m][0], v1 = acc[ai][bj][m][1];
;                         u32x4 w; w.x = pk2(v0[0], v0[1]); w.y = pk2(v0[2], v0[3]); w.z = pk2(v1[0], v1[1]); w.w = pk2(v1[2], v1[3]);
;                         *(u32x4*)(rowp + bj * HALF) = w;
;                     }
;                 }
; template <int MODE, class EpiT, class Sched>
; __device__ __forceinline__ void gemm_phase(LAS unsigned char* lds, const Gemm g, const Sched& S, const EpiT& E) {
;     ...
;     PG8_WAIT_V(0);
;     if (wr == 0) PG8_BAR;
;     PG8_BAR;
	v_lshl_add_u32 v142, s56, 8, v138
	v_lshl_or_b32 v136, s61, 8, v140
	v_ashrrev_i32_e32 v143, 31, v142
	v_ashrrev_i32_e32 v137, 31, v136
	v_lshlrev_b64 v[144:145], 11, v[142:143]
	v_lshl_add_u64 v[144:145], s[6:7], 0, v[144:145]
	v_lshlrev_b64 v[146:147], 1, v[136:137]
	v_lshl_add_u64 v[136:137], v[144:145], 0, v[146:147]
	v_cvt_pk_bf16_f32 v126, v126, v127
	v_cvt_pk_bf16_f32 v127, v128, v129
	v_cvt_pk_bf16_f32 v128, v122, v123
	v_cvt_pk_bf16_f32 v129, v124, v125
	global_store_dwordx4 v[136:137], v[126:129], off
	v_cvt_pk_bf16_f32 v114, v114, v115
	v_cvt_pk_bf16_f32 v115, v116, v117
	v_cvt_pk_bf16_f32 v116, v106, v107
	v_or_b32_e32 v106, 16, v142
	v_ashrrev_i32_e32 v107, 31, v106
	v_lshlrev_b64 v[106:107], 11, v[106:107]
	v_lshl_add_u64 v[106:107], s[6:7], 0, v[106:107]
	v_cvt_pk_bf16_f32 v117, v108, v109
	global_store_dwordx4 v[136:137], v[114:117], off offset:256
	s_mov_b64 s[28:29], 0x40000
	s_mov_b32 s61, s57
	v_lshl_add_u64 v[114:115], v[106:107], 0, v[146:147]
	v_cvt_pk_bf16_f32 v106, v118, v119
	v_cvt_pk_bf16_f32 v107, v120, v121
	v_cvt_pk_bf16_f32 v108, v110, v111
	v_cvt_pk_bf16_f32 v109, v112, v113
	global_store_dwordx4 v[114:115], v[106:109], off
	v_cvt_pk_bf16_f32 v98, v98, v99
	v_cvt_pk_bf16_f32 v99, v100, v101
	v_cvt_pk_bf16_f32 v100, v90, v91
	v_or_b32_e32 v90, 32, v142
	v_ashrrev_i32_e32 v91, 31, v90
	v_lshlrev_b64 v[90:91], 11, v[90:91]
	v_lshl_add_u64 v[90:91], s[6:7], 0, v[90:91]
	v_cvt_pk_bf16_f32 v101, v92, v93
	global_store_dwordx4 v[114:115], v[98:101], off offset:256
	s_mov_b32 s56, s60
	s_mov_b64 s[34:35], s[10:11]
	v_lshl_add_u64 v[98:99], v[90:91], 0, v[146:147]
	v_cvt_pk_bf16_f32 v90, v102, v103
	v_cvt_pk_bf16_f32 v91, v104, v105
	v_cvt_pk_bf16_f32 v92, v94, v95
	v_cvt_pk_bf16_f32 v93, v96, v97
	global_store_dwordx4 v[98:99], v[90:93], off
	v_cvt_pk_bf16_f32 v82, v82, v83
	v_cvt_pk_bf16_f32 v83, v84, v85
	v_cvt_pk_bf16_f32 v84, v74, v75
	v_or_b32_e32 v74, 48, v142
	v_ashrrev_i32_e32 v75, 31, v74
	v_lshlrev_b64 v[74:75], 11, v[74:75]
	v_lshl_add_u64 v[74:75], s[6:7], 0, v[74:75]
	v_cvt_pk_bf16_f32 v85, v76, v77
	global_store_dwordx4 v[98:99], v[82:85], off offset:256
	s_nop 1
	v_lshl_add_u64 v[82:83], v[74:75], 0, v[146:147]
	v_cvt_pk_bf16_f32 v74, v86, v87
	v_cvt_pk_bf16_f32 v75, v88, v89
	v_cvt_pk_bf16_f32 v76, v78, v79
	v_cvt_pk_bf16_f32 v77, v80, v81
	global_store_dwordx4 v[82:83], v[74:77], off
	v_cvt_pk_bf16_f32 v70, v70, v71
	v_cvt_pk_bf16_f32 v71, v72, v73
	v_cvt_pk_bf16_f32 v72, v66, v67
	v_cvt_pk_bf16_f32 v73, v68, v69
	global_store_dwordx4 v[82:83], v[70:73], off offset:256
	v_cvt_pk_bf16_f32 v62, v62, v63
	v_cvt_pk_bf16_f32 v63, v64, v65
	v_cvt_pk_bf16_f32 v64, v58, v59
	v_add_co_u32_e32 v58, vcc, s91, v136
	v_lshl_add_u64 v[66:67], v[136:137], 0, s[28:29]
	s_nop 0
	v_addc_co_u32_e32 v59, vcc, 0, v137, vcc
	v_cvt_pk_bf16_f32 v65, v60, v61
	global_store_dwordx4 v[58:59], v[62:65], off
	v_cvt_pk_bf16_f32 v50, v50, v51
	v_cvt_pk_bf16_f32 v51, v52, v53
	s_mov_b64 s[28:29], 0x48000
	v_cvt_pk_bf16_f32 v52, v42, v43
	v_cvt_pk_bf16_f32 v53, v44, v45
	global_store_dwordx4 v[66:67], v[50:53], off offset:256
	v_cvt_pk_bf16_f32 v42, v54, v55
	v_cvt_pk_bf16_f32 v43, v56, v57
	v_cvt_pk_bf16_f32 v44, v46, v47
	v_cvt_pk_bf16_f32 v45, v48, v49
	s_nop 1
	v_lshl_add_u64 v[50:51], v[136:137], 0, s[28:29]
	s_mov_b32 s28, 0x48000
	v_add_co_u32_e32 v46, vcc, s28, v136
	s_mov_b64 s[28:29], 0x50000
	s_nop 0
	v_addc_co_u32_e32 v47, vcc, 0, v137, vcc
	global_store_dwordx4 v[46:47], v[42:45], off
	v_cvt_pk_bf16_f32 v34, v34, v35
	v_cvt_pk_bf16_f32 v35, v36, v37
	v_cvt_pk_bf16_f32 v36, v26, v27
	v_cvt_pk_bf16_f32 v37, v28, v29
	global_store_dwordx4 v[50:51], v[34:37], off offset:256
	v_cvt_pk_bf16_f32 v26, v38, v39
	v_cvt_pk_bf16_f32 v27, v40, v41
	v_cvt_pk_bf16_f32 v28, v30, v31
	v_cvt_pk_bf16_f32 v29, v32, v33
	s_nop 1
	v_lshl_add_u64 v[34:35], v[136:137], 0, s[28:29]
	s_mov_b32 s28, 0x50000
	v_add_co_u32_e32 v30, vcc, s28, v136
	s_mov_b64 s[28:29], 0x58000
	s_nop 0
	v_addc_co_u32_e32 v31, vcc, 0, v137, vcc
	global_store_dwordx4 v[30:31], v[26:29], off
	v_cvt_pk_bf16_f32 v18, v18, v19
	v_cvt_pk_bf16_f32 v19, v20, v21
	v_cvt_pk_bf16_f32 v20, v10, v11
	v_cvt_pk_bf16_f32 v21, v12, v13
	global_store_dwordx4 v[34:35], v[18:21], off offset:256
	v_cvt_pk_bf16_f32 v10, v22, v23
	v_cvt_pk_bf16_f32 v11, v24, v25
	v_cvt_pk_bf16_f32 v12, v14, v15
	v_cvt_pk_bf16_f32 v13, v16, v17
	s_nop 1
	v_lshl_add_u64 v[18:19], v[136:137], 0, s[28:29]
	s_mov_b32 s28, 0x58000
	v_add_co_u32_e32 v14, vcc, s28, v136
	s_mov_b64 s[28:29], s[4:5]
	s_nop 0
	v_addc_co_u32_e32 v15, vcc, 0, v137, vcc
	s_and_b64 vcc, exec, s[40:41]
	global_store_dwordx4 v[14:15], v[10:13], off
	v_cvt_pk_bf16_f32 v6, v6, v7
	v_cvt_pk_bf16_f32 v7, v8, v9
	v_cvt_pk_bf16_f32 v8, v2, v3
	v_cvt_pk_bf16_f32 v9, v4, v5
	global_store_dwordx4 v[18:19], v[6:9], off offset:256
	s_cbranch_vccz .LBB0_229
	s_waitcnt vmcnt(0)
	v_readlane_b32 s46, v247, 49
	v_readlane_b32 s50, v246, 29
	v_readlane_b32 s56, v246, 31
	v_readlane_b32 s58, v246, 33
	v_readlane_b32 s60, v246, 35
	s_cmpk_gt_u32 s2, 0xff
	s_mov_b32 s52, 0x800000
	s_movk_i32 s53, 0x1000
	s_movk_i32 s23, 0x2000
	s_movk_i32 s30, 0x2840
	s_movk_i32 s42, 0x3000
	s_mov_b64 s[44:45], 0x1800
	v_readlane_b32 s47, v247, 50
	v_readlane_b32 s43, v247, 51
	v_readlane_b32 s51, v246, 30
	v_readlane_b32 s57, v246, 32
	v_readlane_b32 s59, v246, 34
	v_readlane_b32 s61, v246, 36
	s_cbranch_scc1 .LBB0_240
	s_barrier

; #define PG8_STAGE(bufoff, gbase, voff) do { _Pragma("unroll") for (int _i = 0; _i < 2; ++_i) \
;         __builtin_amdgcn_global_load_lds((const unsigned*)((const char*)(gbase) + (voff)[_i]), (LAS unsigned*)(lds + (bufoff) + ldsw + _i * 8192), 16, 0, 0); } while (0)
; #define PG8_LDA(dst, b, h) do { _Pragma("unroll") for (int m = 0; m < 4; ++m) _Pragma("unroll") for (int k = 0; k < 2; ++k) dst[m][k] = *(const LAS bf16x8*)(lds + PG8_SA(b, h) + aoff + m * 2048 + k * 1024); } while (0)
; #define PG8_LDB(dst, b, h) do { _Pragma("unroll") for (int n = 0; n < 2; ++n) _Pragma("unroll") for (int k = 0; k < 2; ++k) dst[n][k] = *(const LAS bf16x8*)(lds + PG8_SB(b, h) + boff + n * 2048 + k * 1024); } while (0)
; #define PG8_MMA(ai, bj, At, Bt) do { __builtin_amdgcn_s_setprio(1); _Pragma("unroll") for (int m = 0; m < 4; ++m) _Pragma("unroll") for (int n = 0; n < 2; ++n) _Pragma("unroll") for (int k = 0; k < 2; ++k) \
;         acc[ai][bj][m][n] = __builtin_amdgcn_mfma_f32_16x16x32_bf16(Bt[n][k], At[m][k], acc[ai][bj][m][n], 0, 0, 0); __builtin_amdgcn_s_setprio(0); } while (0)
; #define PG8_WAIT_L(n) asm volatile("s_waitcnt lgkmcnt(" #n ")" ::: "memory")
; #define PG8_BAR __builtin_amdgcn_s_barrier()
; #define PG8_SCHED __builtin_amdgcn_sched_barrier(0)
; template <int MODE, class EpiT, class Sched>
; __device__ __forceinline__ void gemm_phase(LAS unsigned char* lds, const Gemm g, const Sched& S, const EpiT& E) {
;     ...
;             PG8_LDB(B0, 0, 0); PG8_SCHED; PG8_LDA(At, 0, 0); PG8_STAGE(PG8_SA(1, 1), a1 + hstep, voffA);
;             PG8_WAIT_L(8); PG8_BAR; PG8_WAIT_L(0); PG8_MMA(0, 0, At, B0); PG8_BAR; PG8_SCHED;
;             PG8_LDB(B1, 0, 1); PG8_STAGE(PG8_SB(0, 0), b2, voffB);
;             PG8_BAR; PG8_WAIT_L(0); PG8_MMA(0, 1, At, B1); PG8_BAR;
;             PG8_LDA(At, 0, 1); PG8_STAGE(PG8_SA(0, 0), a2, voffA);
;             PG8_BAR; PG8_WAIT_L(0); PG8_MMA(1, 0, At, B0); PG8_BAR; PG8_SCHED;
.LBB0_280:
	s_add_i32 s68, s46, 2
	s_add_u32 s52, s10, s44
	s_addc_u32 s47, s11, s45
	s_add_u32 s58, s4, s44
	s_addc_u32 s53, s5, s45
	s_add_i32 s59, 0, 0x10000
	v_add_u32_e32 v152, s59, v157
	ds_read_b128 v[134:137], v152
	ds_read_b128 v[138:141], v152 offset:1024
	ds_read_b128 v[142:145], v152 offset:2048
	ds_read_b128 v[152:155], v152 offset:3072
	s_cmp_eq_u32 s60, s46
	s_cselect_b32 s46, s34, s52
	s_cselect_b32 s47, s35, s47
	s_cselect_b32 s53, s39, s53
	s_cselect_b32 s52, s38, s58
	v_lshl_add_u64 v[198:199], s[10:11], 0, v[132:133]
	s_add_i32 m0, s30, 0xc000
	ds_read_b128 v[162:165], v160
	ds_read_b128 v[166:169], v160 offset:1024
	ds_read_b128 v[170:173], v160 offset:2048
	ds_read_b128 v[174:177], v160 offset:3072
	ds_read_b128 v[182:185], v160 offset:4096
	ds_read_b128 v[186:189], v160 offset:5120
	ds_read_b128 v[190:193], v160 offset:6144
	ds_read_b128 v[194:197], v160 offset:7168
	global_load_lds_dwordx4 v[198:199], off
	s_add_i32 m0, s30, 0xe000
	v_lshl_add_u64 v[198:199], s[10:11], 0, v[130:131]
	global_load_lds_dwordx4 v[198:199], off
	s_waitcnt lgkmcnt(8)
	s_barrier
	s_waitcnt lgkmcnt(0)
	v_mfma_f32_16x16x32_bf16 v[126:129], v[134:137], v[162:165], v[126:129]
	v_mfma_f32_16x16x32_bf16 v[122:125], v[142:145], v[162:165], v[122:125]
	v_mfma_f32_16x16x32_bf16 v[118:121], v[134:137], v[170:173], v[118:121]
	v_mfma_f32_16x16x32_bf16 v[114:117], v[142:145], v[170:173], v[114:117]
	v_mfma_f32_16x16x32_bf16 v[110:113], v[134:137], v[182:185], v[110:113]
	v_mfma_f32_16x16x32_bf16 v[106:109], v[142:145], v[182:185], v[106:109]
	v_mfma_f32_16x16x32_bf16 v[102:105], v[134:137], v[190:193], v[102:105]
	v_mfma_f32_16x16x32_bf16 v[98:101], v[142:145], v[190:193], v[98:101]
	v_mfma_f32_16x16x32_bf16 v[126:129], v[138:141], v[166:169], v[126:129]
	v_mfma_f32_16x16x32_bf16 v[122:125], v[152:155], v[166:169], v[122:125]
	v_mfma_f32_16x16x32_bf16 v[118:121], v[138:141], v[174:177], v[118:121]
	v_mfma_f32_16x16x32_bf16 v[114:117], v[152:155], v[174:177], v[114:117]
	v_mfma_f32_16x16x32_bf16 v[110:113], v[138:141], v[186:189], v[110:113]
	v_mfma_f32_16x16x32_bf16 v[106:109], v[152:155], v[186:189], v[106:109]
	v_mfma_f32_16x16x32_bf16 v[102:105], v[138:141], v[194:197], v[102:105]
	v_mfma_f32_16x16x32_bf16 v[98:101], v[152:155], v[194:197], v[98:101]
	s_barrier
	s_add_i32 s58, 0, 0x14000
	s_add_i32 s59, s59, s24
	v_add_u32_e32 v161, s58, v157
	v_lshl_add_u64 v[198:199], s[52:53], 0, v[0:1]
	s_mov_b32 m0, s59
	ds_read_b128 v[220:223], v161
	ds_read_b128 v[224:227], v161 offset:1024
	ds_read_b128 v[228:231], v161 offset:2048
	ds_read_b128 v[232:235], v161 offset:3072
	global_load_lds_dwordx4 v[198:199], off
	s_add_i32 m0, s59, 0x2000
	v_lshl_add_u64 v[236:237], s[52:53], 0, v[146:147]
	global_load_lds_dwordx4 v[236:237], off
	s_barrier
	s_waitcnt lgkmcnt(0)
	v_mfma_f32_16x16x32_bf16 v[94:97], v[220:223], v[162:165], v[94:97]
	v_mfma_f32_16x16x32_bf16 v[90:93], v[228:231], v[162:165], v[90:93]
	v_mfma_f32_16x16x32_bf16 v[86:89], v[220:223], v[170:173], v[86:89]
	v_mfma_f32_16x16x32_bf16 v[82:85], v[228:231], v[170:173], v[82:85]
	v_mfma_f32_16x16x32_bf16 v[78:81], v[220:223], v[182:185], v[78:81]
	v_mfma_f32_16x16x32_bf16 v[74:77], v[228:231], v[182:185], v[74:77]
	v_mfma_f32_16x16x32_bf16 v[70:73], v[220:223], v[190:193], v[70:73]
	v_mfma_f32_16x16x32_bf16 v[66:69], v[228:231], v[190:193], v[66:69]
	v_mfma_f32_16x16x32_bf16 v[94:97], v[224:227], v[166:169], v[94:97]
	v_mfma_f32_16x16x32_bf16 v[90:93], v[232:235], v[166:169], v[90:93]
	v_mfma_f32_16x16x32_bf16 v[86:89], v[224:227], v[174:177], v[86:89]
	v_mfma_f32_16x16x32_bf16 v[82:85], v[232:235], v[174:177], v[82:85]
	v_mfma_f32_16x16x32_bf16 v[78:81], v[224:227], v[186:189], v[78:81]
	v_mfma_f32_16x16x32_bf16 v[74:77], v[232:235], v[186:189], v[74:77]
	v_mfma_f32_16x16x32_bf16 v[70:73], v[224:227], v[194:197], v[70:73]
	v_mfma_f32_16x16x32_bf16 v[66:69], v[232:235], v[194:197], v[66:69]
	s_barrier
	s_mov_b32 m0, s30
	v_lshl_add_u64 v[238:239], s[46:47], 0, v[0:1]
	ds_read_b128 v[162:165], v160 offset:16384
	ds_read_b128 v[166:169], v160 offset:17408
	ds_read_b128 v[170:173], v160 offset:18432
	ds_read_b128 v[174:177], v160 offset:19456
	ds_read_b128 v[182:185], v160 offset:20480
	ds_read_b128 v[186:189], v160 offset:21504
	ds_read_b128 v[190:193], v160 offset:22528
	ds_read_b128 v[194:197], v160 offset:23552
	global_load_lds_dwordx4 v[238:239], off
	s_mov_b32 m0, s50
	v_lshl_add_u64 v[240:241], s[46:47], 0, v[146:147]
	global_load_lds_dwordx4 v[240:241], off
	s_barrier
	s_waitcnt lgkmcnt(0)
	v_mfma_f32_16x16x32_bf16 v[62:65], v[134:137], v[162:165], v[62:65]
	v_mfma_f32_16x16x32_bf16 v[58:61], v[142:145], v[162:165], v[58:61]
	v_mfma_f32_16x16x32_bf16 v[54:57], v[134:137], v[170:173], v[54:57]
	v_mfma_f32_16x16x32_bf16 v[50:53], v[142:145], v[170:173], v[50:53]
	v_mfma_f32_16x16x32_bf16 v[46:49], v[134:137], v[182:185], v[46:49]
	v_mfma_f32_16x16x32_bf16 v[42:45], v[142:145], v[182:185], v[42:45]
	v_mfma_f32_16x16x32_bf16 v[38:41], v[134:137], v[190:193], v[38:41]
	v_mfma_f32_16x16x32_bf16 v[34:37], v[142:145], v[190:193], v[34:37]
	v_mfma_f32_16x16x32_bf16 v[62:65], v[138:141], v[166:169], v[62:65]
	v_mfma_f32_16x16x32_bf16 v[58:61], v[152:155], v[166:169], v[58:61]
	v_mfma_f32_16x16x32_bf16 v[54:57], v[138:141], v[174:177], v[54:57]
	v_mfma_f32_16x16x32_bf16 v[50:53], v[152:155], v[174:177], v[50:53]
	v_mfma_f32_16x16x32_bf16 v[46:49], v[138:141], v[186:189], v[46:49]
	v_mfma_f32_16x16x32_bf16 v[42:45], v[152:155], v[186:189], v[42:45]
	v_mfma_f32_16x16x32_bf16 v[38:41], v[138:141], v[194:197], v[38:41]
	v_mfma_f32_16x16x32_bf16 v[34:37], v[152:155], v[194:197], v[34:37]
	s_barrier
; #define PG8_STAGE(bufoff, gbase, voff) do { _Pragma("unroll") for (int _i = 0; _i < 2; ++_i) \
;         __builtin_amdgcn_global_load_lds((const unsigned*)((const char*)(gbase) + (voff)[_i]), (LAS unsigned*)(lds + (bufoff) + ldsw + _i * 8192), 16, 0, 0); } while (0)
; #define PG8_LDA(dst, b, h) do { _Pragma("unroll") for (int m = 0; m < 4; ++m) _Pragma("unroll") for (int k = 0; k < 2; ++k) dst[m][k] = *(const LAS bf16x8*)(lds + PG8_SA(b, h) + aoff + m * 2048 + k * 1024); } while (0)
; #define PG8_LDB(dst, b, h) do { _Pragma("unroll") for (int n = 0; n < 2; ++n) _Pragma("unroll") for (int k = 0; k < 2; ++k) dst[n][k] = *(const LAS bf16x8*)(lds + PG8_SB(b, h) + boff + n * 2048 + k * 1024); } while (0)
; #define PG8_MMA(ai, bj, At, Bt) do { __builtin_amdgcn_s_setprio(1); _Pragma("unroll") for (int m = 0; m < 4; ++m) _Pragma("unroll") for (int n = 0; n < 2; ++n) _Pragma("unroll") for (int k = 0; k < 2; ++k) \
;         acc[ai][bj][m][n] = __builtin_amdgcn_mfma_f32_16x16x32_bf16(Bt[n][k], At[m][k], acc[ai][bj][m][n], 0, 0, 0); __builtin_amdgcn_s_setprio(0); } while (0)
; #define PG8_WAIT_V(n) asm volatile("s_waitcnt vmcnt(" #n ")" ::: "memory")
; #define PG8_WAIT_L(n) asm volatile("s_waitcnt lgkmcnt(" #n ")" ::: "memory")
; #define PG8_BAR __builtin_amdgcn_s_barrier()
; #define PG8_SCHED __builtin_amdgcn_sched_barrier(0)
; template <int MODE, class EpiT, class Sched>
; __device__ __forceinline__ void gemm_phase(LAS unsigned char* lds, const Gemm g, const Sched& S, const EpiT& E) {
;     ...
;             PG8_STAGE(PG8_SB(0, 1), b2 + hstep, voffB);
;             PG8_WAIT_V(6); PG8_BAR; PG8_MMA(1, 1, At, B1); PG8_BAR;
;             PG8_LDB(B0, 1, 0); PG8_SCHED; PG8_LDA(At, 1, 0); PG8_STAGE(PG8_SA(0, 1), a2 + hstep, voffA);
;             PG8_WAIT_L(8); PG8_BAR; PG8_WAIT_L(0); PG8_MMA(0, 0, At, B0); PG8_BAR; PG8_SCHED;
;             PG8_LDB(B1, 1, 1); PG8_STAGE(PG8_SB(1, 0), b3, voffB);
;             PG8_BAR; PG8_WAIT_L(0); PG8_MMA(0, 1, At, B1); PG8_BAR;
;             PG8_LDA(At, 1, 1); PG8_STAGE(PG8_SA(1, 0), a3, voffA);
;             PG8_BAR; PG8_WAIT_L(0); PG8_MMA(1, 0, At, B0); PG8_BAR; PG8_SCHED;
	s_add_u32 s52, s52, s22
	s_addc_u32 s53, s53, 0
	s_add_i32 s58, s58, s24
	v_lshl_add_u64 v[242:243], s[52:53], 0, v[0:1]
	s_mov_b32 m0, s58
	global_load_lds_dwordx4 v[242:243], off
	s_add_i32 m0, s58, 0x2000
	v_lshl_add_u64 v[244:245], s[52:53], 0, v[146:147]
	global_load_lds_dwordx4 v[244:245], off
	s_waitcnt vmcnt(6)
	s_barrier
	v_mfma_f32_16x16x32_bf16 v[30:33], v[220:223], v[162:165], v[30:33]
	v_mfma_f32_16x16x32_bf16 v[26:29], v[228:231], v[162:165], v[26:29]
	v_mfma_f32_16x16x32_bf16 v[22:25], v[220:223], v[170:173], v[22:25]
	v_mfma_f32_16x16x32_bf16 v[18:21], v[228:231], v[170:173], v[18:21]
	v_mfma_f32_16x16x32_bf16 v[14:17], v[220:223], v[182:185], v[14:17]
	v_mfma_f32_16x16x32_bf16 v[10:13], v[228:231], v[182:185], v[10:13]
	v_mfma_f32_16x16x32_bf16 v[6:9], v[220:223], v[190:193], v[6:9]
	v_mfma_f32_16x16x32_bf16 v[2:5], v[228:231], v[190:193], v[2:5]
	v_mfma_f32_16x16x32_bf16 v[30:33], v[224:227], v[166:169], v[30:33]
	v_mfma_f32_16x16x32_bf16 v[26:29], v[232:235], v[166:169], v[26:29]
	v_mfma_f32_16x16x32_bf16 v[22:25], v[224:227], v[174:177], v[22:25]
	v_mfma_f32_16x16x32_bf16 v[18:21], v[232:235], v[174:177], v[18:21]
	v_mfma_f32_16x16x32_bf16 v[14:17], v[224:227], v[186:189], v[14:17]
	v_mfma_f32_16x16x32_bf16 v[10:13], v[232:235], v[186:189], v[10:13]
	v_mfma_f32_16x16x32_bf16 v[6:9], v[224:227], v[194:197], v[6:9]
	v_mfma_f32_16x16x32_bf16 v[2:5], v[232:235], v[194:197], v[2:5]
	s_barrier
	s_add_i32 s52, 0, 0x18000
	v_add_u32_e32 v152, s52, v157
	ds_read_b128 v[134:137], v152
	ds_read_b128 v[138:141], v152 offset:1024
	ds_read_b128 v[142:145], v152 offset:2048
	ds_read_b128 v[152:155], v152 offset:3072
	s_add_u32 s46, s46, s22
	s_addc_u32 s47, s47, 0
	s_mov_b32 m0, s51
	v_lshl_add_u64 v[220:221], s[46:47], 0, v[0:1]
	ds_read_b128 v[162:165], v160 offset:32768
	ds_read_b128 v[166:169], v160 offset:33792
	ds_read_b128 v[170:173], v160 offset:34816
	ds_read_b128 v[174:177], v160 offset:35840
	ds_read_b128 v[182:185], v160 offset:36864
	ds_read_b128 v[186:189], v160 offset:37888
	ds_read_b128 v[190:193], v160 offset:38912
	ds_read_b128 v[194:197], v160 offset:39936
	global_load_lds_dwordx4 v[220:221], off
	s_mov_b32 m0, s54
	v_lshl_add_u64 v[220:221], s[46:47], 0, v[146:147]
	global_load_lds_dwordx4 v[220:221], off
	s_waitcnt lgkmcnt(8)
	s_barrier
	s_waitcnt lgkmcnt(0)
	v_mfma_f32_16x16x32_bf16 v[126:129], v[134:137], v[162:165], v[126:129]
	v_mfma_f32_16x16x32_bf16 v[122:125], v[142:145], v[162:165], v[122:125]
	v_mfma_f32_16x16x32_bf16 v[118:121], v[134:137], v[170:173], v[118:121]
	v_mfma_f32_16x16x32_bf16 v[114:117], v[142:145], v[170:173], v[114:117]
	v_mfma_f32_16x16x32_bf16 v[110:113], v[134:137], v[182:185], v[110:113]
	v_mfma_f32_16x16x32_bf16 v[106:109], v[142:145], v[182:185], v[106:109]
	v_mfma_f32_16x16x32_bf16 v[102:105], v[134:137], v[190:193], v[102:105]
	v_mfma_f32_16x16x32_bf16 v[98:101], v[142:145], v[190:193], v[98:101]
	v_mfma_f32_16x16x32_bf16 v[126:129], v[138:141], v[166:169], v[126:129]
	v_mfma_f32_16x16x32_bf16 v[122:125], v[152:155], v[166:169], v[122:125]
	v_mfma_f32_16x16x32_bf16 v[118:121], v[138:141], v[174:177], v[118:121]
	v_mfma_f32_16x16x32_bf16 v[114:117], v[152:155], v[174:177], v[114:117]
	v_mfma_f32_16x16x32_bf16 v[110:113], v[138:141], v[186:189], v[110:113]
	v_mfma_f32_16x16x32_bf16 v[106:109], v[152:155], v[186:189], v[106:109]
	v_mfma_f32_16x16x32_bf16 v[102:105], v[138:141], v[194:197], v[102:105]
	v_mfma_f32_16x16x32_bf16 v[98:101], v[152:155], v[194:197], v[98:101]
	s_barrier
	s_add_i32 s46, 0, 0x1c000
	s_add_i32 s47, s52, s24
	v_add_u32_e32 v161, s46, v157
	v_lshl_add_u64 v[198:199], v[198:199], 0, s[76:77]
	s_mov_b32 m0, s47
	ds_read_b128 v[220:223], v161
	ds_read_b128 v[224:227], v161 offset:1024
	ds_read_b128 v[228:231], v161 offset:2048
	ds_read_b128 v[232:235], v161 offset:3072
	global_load_lds_dwordx4 v[198:199], off
	s_add_i32 m0, s47, 0x2000
	v_lshl_add_u64 v[198:199], v[236:237], 0, s[76:77]
	global_load_lds_dwordx4 v[198:199], off
	s_barrier
; #define PG8_STAGE(bufoff, gbase, voff) do { _Pragma("unroll") for (int _i = 0; _i < 2; ++_i) \
;         __builtin_amdgcn_global_load_lds((const unsigned*)((const char*)(gbase) + (voff)[_i]), (LAS unsigned*)(lds + (bufoff) + ldsw + _i * 8192), 16, 0, 0); } while (0)
; #define PG8_LDA(dst, b, h) do { _Pragma("unroll") for (int m = 0; m < 4; ++m) _Pragma("unroll") for (int k = 0; k < 2; ++k) dst[m][k] = *(const LAS bf16x8*)(lds + PG8_SA(b, h) + aoff + m * 2048 + k * 1024); } while (0)
; #define PG8_MMA(ai, bj, At, Bt) do { __builtin_amdgcn_s_setprio(1); _Pragma("unroll") for (int m = 0; m < 4; ++m) _Pragma("unroll") for (int n = 0; n < 2; ++n) _Pragma("unroll") for (int k = 0; k < 2; ++k) \
;         acc[ai][bj][m][n] = __builtin_amdgcn_mfma_f32_16x16x32_bf16(Bt[n][k], At[m][k], acc[ai][bj][m][n], 0, 0, 0); __builtin_amdgcn_s_setprio(0); } while (0)
; #define PG8_WAIT_V(n) asm volatile("s_waitcnt vmcnt(" #n ")" ::: "memory")
; #define PG8_WAIT_L(n) asm volatile("s_waitcnt lgkmcnt(" #n ")" ::: "memory")
; #define PG8_BAR __builtin_amdgcn_s_barrier()
; #define PG8_SCHED __builtin_amdgcn_sched_barrier(0)
; template <int MODE, class EpiT, class Sched>
; __device__ __forceinline__ void gemm_phase(LAS unsigned char* lds, const Gemm g, const Sched& S, const EpiT& E) {
;     ...
;             PG8_BAR; PG8_WAIT_L(0); PG8_MMA(0, 1, At, B1); PG8_BAR;
;             PG8_LDA(At, 1, 1); PG8_STAGE(PG8_SA(1, 0), a3, voffA);
;             PG8_BAR; PG8_WAIT_L(0); PG8_MMA(1, 0, At, B0); PG8_BAR; PG8_SCHED;
;             PG8_STAGE(PG8_SB(1, 1), b3 + hstep, voffB);
;             PG8_WAIT_V(6); PG8_BAR; PG8_MMA(1, 1, At, B1); PG8_BAR;
;         }
;         E.template run<MODE>(acc, cur, wr, wc, fr, fq, SC + ui * 256);
;         if (!has_next) break;
	s_waitcnt lgkmcnt(0)
	v_mfma_f32_16x16x32_bf16 v[94:97], v[220:223], v[162:165], v[94:97]
	v_mfma_f32_16x16x32_bf16 v[90:93], v[228:231], v[162:165], v[90:93]
	v_mfma_f32_16x16x32_bf16 v[86:89], v[220:223], v[170:173], v[86:89]
	v_mfma_f32_16x16x32_bf16 v[82:85], v[228:231], v[170:173], v[82:85]
	v_mfma_f32_16x16x32_bf16 v[78:81], v[220:223], v[182:185], v[78:81]
	v_mfma_f32_16x16x32_bf16 v[74:77], v[228:231], v[182:185], v[74:77]
	v_mfma_f32_16x16x32_bf16 v[70:73], v[220:223], v[190:193], v[70:73]
	v_mfma_f32_16x16x32_bf16 v[66:69], v[228:231], v[190:193], v[66:69]
	v_mfma_f32_16x16x32_bf16 v[94:97], v[224:227], v[166:169], v[94:97]
	v_mfma_f32_16x16x32_bf16 v[90:93], v[232:235], v[166:169], v[90:93]
	v_mfma_f32_16x16x32_bf16 v[86:89], v[224:227], v[174:177], v[86:89]
	v_mfma_f32_16x16x32_bf16 v[82:85], v[232:235], v[174:177], v[82:85]
	v_mfma_f32_16x16x32_bf16 v[78:81], v[224:227], v[186:189], v[78:81]
	v_mfma_f32_16x16x32_bf16 v[74:77], v[232:235], v[186:189], v[74:77]
	v_mfma_f32_16x16x32_bf16 v[70:73], v[224:227], v[194:197], v[70:73]
	v_mfma_f32_16x16x32_bf16 v[66:69], v[232:235], v[194:197], v[66:69]
	s_barrier
	s_mov_b32 m0, s56
	v_lshl_add_u64 v[198:199], v[238:239], 0, s[76:77]
	ds_read_b128 v[162:165], v160 offset:49152
	ds_read_b128 v[166:169], v160 offset:50176
	ds_read_b128 v[170:173], v160 offset:51200
	ds_read_b128 v[174:177], v160 offset:52224
	ds_read_b128 v[182:185], v160 offset:53248
	ds_read_b128 v[186:189], v160 offset:54272
	ds_read_b128 v[190:193], v160 offset:55296
	ds_read_b128 v[194:197], v160 offset:56320
	global_load_lds_dwordx4 v[198:199], off
	s_mov_b32 m0, s57
	v_lshl_add_u64 v[198:199], v[240:241], 0, s[76:77]
	global_load_lds_dwordx4 v[198:199], off
	s_barrier
	s_waitcnt lgkmcnt(0)
	v_mfma_f32_16x16x32_bf16 v[62:65], v[134:137], v[162:165], v[62:65]
	v_mfma_f32_16x16x32_bf16 v[58:61], v[142:145], v[162:165], v[58:61]
	v_mfma_f32_16x16x32_bf16 v[54:57], v[134:137], v[170:173], v[54:57]
	v_mfma_f32_16x16x32_bf16 v[50:53], v[142:145], v[170:173], v[50:53]
	v_mfma_f32_16x16x32_bf16 v[46:49], v[134:137], v[182:185], v[46:49]
	v_mfma_f32_16x16x32_bf16 v[42:45], v[142:145], v[182:185], v[42:45]
	v_mfma_f32_16x16x32_bf16 v[38:41], v[134:137], v[190:193], v[38:41]
	v_mfma_f32_16x16x32_bf16 v[34:37], v[142:145], v[190:193], v[34:37]
	v_mfma_f32_16x16x32_bf16 v[62:65], v[138:141], v[166:169], v[62:65]
	v_mfma_f32_16x16x32_bf16 v[58:61], v[152:155], v[166:169], v[58:61]
	v_mfma_f32_16x16x32_bf16 v[54:57], v[138:141], v[174:177], v[54:57]
	v_mfma_f32_16x16x32_bf16 v[50:53], v[152:155], v[174:177], v[50:53]
	v_mfma_f32_16x16x32_bf16 v[46:49], v[138:141], v[186:189], v[46:49]
	v_mfma_f32_16x16x32_bf16 v[42:45], v[152:155], v[186:189], v[42:45]
	v_mfma_f32_16x16x32_bf16 v[38:41], v[138:141], v[194:197], v[38:41]
	v_mfma_f32_16x16x32_bf16 v[34:37], v[152:155], v[194:197], v[34:37]
	s_barrier
	s_add_i32 s46, s46, s24
	s_mov_b32 m0, s46
	v_lshl_add_u64 v[134:135], v[242:243], 0, s[76:77]
	global_load_lds_dwordx4 v[134:135], off
	s_add_i32 m0, s46, 0x2000
	v_lshl_add_u64 v[134:135], v[244:245], 0, s[76:77]
	global_load_lds_dwordx4 v[134:135], off
	s_waitcnt vmcnt(6)
	s_barrier
	v_mfma_f32_16x16x32_bf16 v[30:33], v[220:223], v[162:165], v[30:33]
	v_mfma_f32_16x16x32_bf16 v[26:29], v[228:231], v[162:165], v[26:29]
	v_mfma_f32_16x16x32_bf16 v[22:25], v[220:223], v[170:173], v[22:25]
	v_mfma_f32_16x16x32_bf16 v[18:21], v[228:231], v[170:173], v[18:21]
	v_mfma_f32_16x16x32_bf16 v[14:17], v[220:223], v[182:185], v[14:17]
	v_mfma_f32_16x16x32_bf16 v[10:13], v[228:231], v[182:185], v[10:13]
	v_mfma_f32_16x16x32_bf16 v[6:9], v[220:223], v[190:193], v[6:9]
	v_mfma_f32_16x16x32_bf16 v[2:5], v[228:231], v[190:193], v[2:5]
	v_mfma_f32_16x16x32_bf16 v[30:33], v[224:227], v[166:169], v[30:33]
	v_mfma_f32_16x16x32_bf16 v[26:29], v[232:235], v[166:169], v[26:29]
	v_mfma_f32_16x16x32_bf16 v[22:25], v[224:227], v[174:177], v[22:25]
	v_mfma_f32_16x16x32_bf16 v[18:21], v[232:235], v[174:177], v[18:21]
	v_mfma_f32_16x16x32_bf16 v[14:17], v[224:227], v[186:189], v[14:17]
	v_mfma_f32_16x16x32_bf16 v[10:13], v[232:235], v[186:189], v[10:13]
	v_mfma_f32_16x16x32_bf16 v[6:9], v[224:227], v[194:197], v[6:9]
	v_mfma_f32_16x16x32_bf16 v[2:5], v[232:235], v[194:197], v[2:5]
	s_barrier
	s_add_u32 s44, s44, 0x100
	s_addc_u32 s45, s45, 0
	v_lshl_add_u64 v[132:133], v[132:133], 0, s[80:81]
	v_lshl_add_u64 v[130:131], v[130:131], 0, s[80:81]
	s_cmp_ge_u32 s68, s55
	s_mov_b32 s46, s68
	s_cbranch_scc0 .LBB0_280
	v_lshl_or_b32 v152, s3, 8, v159
	v_ashrrev_i32_e32 v153, 31, v152
	v_cndmask_b32_e64 v131, 0, 1, s[28:29]
	v_lshl_add_u64 v[154:155], v[152:153], 2, s[12:13]
	v_mov_b32_e32 v130, 0
	v_cmp_ne_u32_e64 s[44:45], 1, v131
	s_andn2_b64 vcc, exec, s[28:29]
	v_mov_b32_e32 v134, 0
	v_mov_b32_e32 v135, 0
	v_mov_b32_e32 v136, 0
	v_mov_b32_e32 v137, 0
	s_cbranch_vccnz .LBB0_283
	global_load_dwordx4 v[134:137], v[154:155], off

; #define PG8_STAGE(bufoff, gbase, voff) do { _Pragma("unroll") for (int _i = 0; _i < 2; ++_i) \
;         __builtin_amdgcn_global_load_lds((const unsigned*)((const char*)(gbase) + (voff)[_i]), (LAS unsigned*)(lds + (bufoff) + ldsw + _i * 8192), 16, 0, 0); } while (0)
; #define PG8_LDA(dst, b, h) do { _Pragma("unroll") for (int m = 0; m < 4; ++m) _Pragma("unroll") for (int k = 0; k < 2; ++k) dst[m][k] = *(const LAS bf16x8*)(lds + PG8_SA(b, h) + aoff + m * 2048 + k * 1024); } while (0)
; #define PG8_LDB(dst, b, h) do { _Pragma("unroll") for (int n = 0; n < 2; ++n) _Pragma("unroll") for (int k = 0; k < 2; ++k) dst[n][k] = *(const LAS bf16x8*)(lds + PG8_SB(b, h) + boff + n * 2048 + k * 1024); } while (0)
; #define PG8_MMA(ai, bj, At, Bt) do { __builtin_amdgcn_s_setprio(1); _Pragma("unroll") for (int m = 0; m < 4; ++m) _Pragma("unroll") for (int n = 0; n < 2; ++n) _Pragma("unroll") for (int k = 0; k < 2; ++k) \
;         acc[ai][bj][m][n] = __builtin_amdgcn_mfma_f32_16x16x32_bf16(Bt[n][k], At[m][k], acc[ai][bj][m][n], 0, 0, 0); __builtin_amdgcn_s_setprio(0); } while (0)
; #define PG8_WAIT_L(n) asm volatile("s_waitcnt lgkmcnt(" #n ")" ::: "memory")
; #define PG8_BAR __builtin_amdgcn_s_barrier()
; #define PG8_SCHED __builtin_amdgcn_sched_barrier(0)
; template <int MODE, class EpiT, class Sched>
; __device__ __forceinline__ void gemm_phase(LAS unsigned char* lds, const Gemm g, const Sched& S, const EpiT& E) {
;     ...
;             PG8_LDB(B0, 0, 0); PG8_SCHED; PG8_LDA(At, 0, 0); PG8_STAGE(PG8_SA(1, 1), a1 + hstep, voffA);
;             PG8_WAIT_L(8); PG8_BAR; PG8_WAIT_L(0); PG8_MMA(0, 0, At, B0); PG8_BAR; PG8_SCHED;
;             PG8_LDB(B1, 0, 1); PG8_STAGE(PG8_SB(0, 0), b2, voffB);
;             PG8_BAR; PG8_WAIT_L(0); PG8_MMA(0, 1, At, B1); PG8_BAR;
;             PG8_LDA(At, 0, 1); PG8_STAGE(PG8_SA(0, 0), a2, voffA);
;             PG8_BAR; PG8_WAIT_L(0); PG8_MMA(1, 0, At, B0); PG8_BAR; PG8_SCHED;
.LBB0_332:
	s_add_i32 s23, s22, 2
	s_add_u32 s30, s12, s4
	s_addc_u32 s38, s13, s5
	s_add_u32 s44, s10, s4
	s_addc_u32 s45, s11, s5
	s_add_i32 s58, 0, 0x10000
	v_add_u32_e32 v145, s58, v141
	ds_read_b128 v[146:149], v145
	ds_read_b128 v[150:153], v145 offset:1024
	ds_read_b128 v[154:157], v145 offset:2048
	ds_read_b128 v[158:161], v145 offset:3072
	s_cmp_eq_u32 s55, s22
	s_cselect_b32 s39, s29, s38
	s_cselect_b32 s38, s28, s30
	s_cselect_b32 s45, s35, s45
	s_cselect_b32 s44, s34, s44
	v_lshl_add_u64 v[198:199], s[12:13], 0, v[138:139]
	s_add_i32 m0, s47, 0xc000
	ds_read_b128 v[162:165], v144
	ds_read_b128 v[166:169], v144 offset:1024
	ds_read_b128 v[170:173], v144 offset:2048
	ds_read_b128 v[174:177], v144 offset:3072
	ds_read_b128 v[182:185], v144 offset:4096
	ds_read_b128 v[186:189], v144 offset:5120
	ds_read_b128 v[190:193], v144 offset:6144
	ds_read_b128 v[194:197], v144 offset:7168
	global_load_lds_dwordx4 v[198:199], off
	s_add_i32 m0, s47, 0xe000
	v_lshl_add_u64 v[198:199], s[12:13], 0, v[136:137]
	global_load_lds_dwordx4 v[198:199], off
	s_waitcnt lgkmcnt(8)
	s_barrier
	s_waitcnt lgkmcnt(0)
	v_mfma_f32_16x16x32_bf16 v[126:129], v[146:149], v[162:165], v[126:129]
	v_mfma_f32_16x16x32_bf16 v[122:125], v[154:157], v[162:165], v[122:125]
	v_mfma_f32_16x16x32_bf16 v[118:121], v[146:149], v[170:173], v[118:121]
	v_mfma_f32_16x16x32_bf16 v[114:117], v[154:157], v[170:173], v[114:117]
	v_mfma_f32_16x16x32_bf16 v[110:113], v[146:149], v[182:185], v[110:113]
	v_mfma_f32_16x16x32_bf16 v[106:109], v[154:157], v[182:185], v[106:109]
	v_mfma_f32_16x16x32_bf16 v[102:105], v[146:149], v[190:193], v[102:105]
	v_mfma_f32_16x16x32_bf16 v[98:101], v[154:157], v[190:193], v[98:101]
	v_mfma_f32_16x16x32_bf16 v[126:129], v[150:153], v[166:169], v[126:129]
	v_mfma_f32_16x16x32_bf16 v[122:125], v[158:161], v[166:169], v[122:125]
	v_mfma_f32_16x16x32_bf16 v[118:121], v[150:153], v[174:177], v[118:121]
	v_mfma_f32_16x16x32_bf16 v[114:117], v[158:161], v[174:177], v[114:117]
	v_mfma_f32_16x16x32_bf16 v[110:113], v[150:153], v[186:189], v[110:113]
	v_mfma_f32_16x16x32_bf16 v[106:109], v[158:161], v[186:189], v[106:109]
	v_mfma_f32_16x16x32_bf16 v[102:105], v[150:153], v[194:197], v[102:105]
	v_mfma_f32_16x16x32_bf16 v[98:101], v[158:161], v[194:197], v[98:101]
	s_barrier
	s_add_i32 s22, 0, 0x14000
	s_add_i32 s30, s58, s46
	v_add_u32_e32 v145, s22, v141
	v_lshl_add_u64 v[198:199], s[44:45], 0, v[0:1]
	s_mov_b32 m0, s30
	ds_read_b128 v[220:223], v145
	ds_read_b128 v[224:227], v145 offset:1024
	ds_read_b128 v[228:231], v145 offset:2048
	ds_read_b128 v[232:235], v145 offset:3072
	global_load_lds_dwordx4 v[198:199], off
	s_add_i32 m0, s30, 0x2000
	v_lshl_add_u64 v[236:237], s[44:45], 0, v[130:131]
	global_load_lds_dwordx4 v[236:237], off
	s_barrier
	s_waitcnt lgkmcnt(0)
	v_mfma_f32_16x16x32_bf16 v[94:97], v[220:223], v[162:165], v[94:97]
	v_mfma_f32_16x16x32_bf16 v[90:93], v[228:231], v[162:165], v[90:93]
	v_mfma_f32_16x16x32_bf16 v[86:89], v[220:223], v[170:173], v[86:89]
	v_mfma_f32_16x16x32_bf16 v[82:85], v[228:231], v[170:173], v[82:85]
	v_mfma_f32_16x16x32_bf16 v[78:81], v[220:223], v[182:185], v[78:81]
	v_mfma_f32_16x16x32_bf16 v[74:77], v[228:231], v[182:185], v[74:77]
	v_mfma_f32_16x16x32_bf16 v[70:73], v[220:223], v[190:193], v[70:73]
	v_mfma_f32_16x16x32_bf16 v[66:69], v[228:231], v[190:193], v[66:69]
	v_mfma_f32_16x16x32_bf16 v[94:97], v[224:227], v[166:169], v[94:97]
	v_mfma_f32_16x16x32_bf16 v[90:93], v[232:235], v[166:169], v[90:93]
	v_mfma_f32_16x16x32_bf16 v[86:89], v[224:227], v[174:177], v[86:89]
	v_mfma_f32_16x16x32_bf16 v[82:85], v[232:235], v[174:177], v[82:85]
	v_mfma_f32_16x16x32_bf16 v[78:81], v[224:227], v[186:189], v[78:81]
	v_mfma_f32_16x16x32_bf16 v[74:77], v[232:235], v[186:189], v[74:77]
	v_mfma_f32_16x16x32_bf16 v[70:73], v[224:227], v[194:197], v[70:73]
	v_mfma_f32_16x16x32_bf16 v[66:69], v[232:235], v[194:197], v[66:69]
	s_barrier
	s_mov_b32 m0, s47
	v_lshl_add_u64 v[238:239], s[38:39], 0, v[0:1]
	ds_read_b128 v[162:165], v144 offset:16384
	ds_read_b128 v[166:169], v144 offset:17408
	ds_read_b128 v[170:173], v144 offset:18432
	ds_read_b128 v[174:177], v144 offset:19456
	ds_read_b128 v[182:185], v144 offset:20480
	ds_read_b128 v[186:189], v144 offset:21504
	ds_read_b128 v[190:193], v144 offset:22528
	ds_read_b128 v[194:197], v144 offset:23552
	global_load_lds_dwordx4 v[238:239], off
	s_mov_b32 m0, s50
	v_lshl_add_u64 v[240:241], s[38:39], 0, v[130:131]
	global_load_lds_dwordx4 v[240:241], off
	s_barrier
	s_waitcnt lgkmcnt(0)
	v_mfma_f32_16x16x32_bf16 v[62:65], v[146:149], v[162:165], v[62:65]
	v_mfma_f32_16x16x32_bf16 v[58:61], v[154:157], v[162:165], v[58:61]
	v_mfma_f32_16x16x32_bf16 v[54:57], v[146:149], v[170:173], v[54:57]
	v_mfma_f32_16x16x32_bf16 v[50:53], v[154:157], v[170:173], v[50:53]
	v_mfma_f32_16x16x32_bf16 v[46:49], v[146:149], v[182:185], v[46:49]
	v_mfma_f32_16x16x32_bf16 v[42:45], v[154:157], v[182:185], v[42:45]
	v_mfma_f32_16x16x32_bf16 v[38:41], v[146:149], v[190:193], v[38:41]
	v_mfma_f32_16x16x32_bf16 v[34:37], v[154:157], v[190:193], v[34:37]
	v_mfma_f32_16x16x32_bf16 v[62:65], v[150:153], v[166:169], v[62:65]
	v_mfma_f32_16x16x32_bf16 v[58:61], v[158:161], v[166:169], v[58:61]
	v_mfma_f32_16x16x32_bf16 v[54:57], v[150:153], v[174:177], v[54:57]
	v_mfma_f32_16x16x32_bf16 v[50:53], v[158:161], v[174:177], v[50:53]
	v_mfma_f32_16x16x32_bf16 v[46:49], v[150:153], v[186:189], v[46:49]
	v_mfma_f32_16x16x32_bf16 v[42:45], v[158:161], v[186:189], v[42:45]
	v_mfma_f32_16x16x32_bf16 v[38:41], v[150:153], v[194:197], v[38:41]
	v_mfma_f32_16x16x32_bf16 v[34:37], v[158:161], v[194:197], v[34:37]
	s_barrier
; #define PG8_STAGE(bufoff, gbase, voff) do { _Pragma("unroll") for (int _i = 0; _i < 2; ++_i) \
;         __builtin_amdgcn_global_load_lds((const unsigned*)((const char*)(gbase) + (voff)[_i]), (LAS unsigned*)(lds + (bufoff) + ldsw + _i * 8192), 16, 0, 0); } while (0)
; #define PG8_LDA(dst, b, h) do { _Pragma("unroll") for (int m = 0; m < 4; ++m) _Pragma("unroll") for (int k = 0; k < 2; ++k) dst[m][k] = *(const LAS bf16x8*)(lds + PG8_SA(b, h) + aoff + m * 2048 + k * 1024); } while (0)
; #define PG8_LDB(dst, b, h) do { _Pragma("unroll") for (int n = 0; n < 2; ++n) _Pragma("unroll") for (int k = 0; k < 2; ++k) dst[n][k] = *(const LAS bf16x8*)(lds + PG8_SB(b, h) + boff + n * 2048 + k * 1024); } while (0)
; #define PG8_MMA(ai, bj, At, Bt) do { __builtin_amdgcn_s_setprio(1); _Pragma("unroll") for (int m = 0; m < 4; ++m) _Pragma("unroll") for (int n = 0; n < 2; ++n) _Pragma("unroll") for (int k = 0; k < 2; ++k) \
;         acc[ai][bj][m][n] = __builtin_amdgcn_mfma_f32_16x16x32_bf16(Bt[n][k], At[m][k], acc[ai][bj][m][n], 0, 0, 0); __builtin_amdgcn_s_setprio(0); } while (0)
; #define PG8_WAIT_V(n) asm volatile("s_waitcnt vmcnt(" #n ")" ::: "memory")
; #define PG8_WAIT_L(n) asm volatile("s_waitcnt lgkmcnt(" #n ")" ::: "memory")
; #define PG8_BAR __builtin_amdgcn_s_barrier()
; #define PG8_SCHED __builtin_amdgcn_sched_barrier(0)
; template <int MODE, class EpiT, class Sched>
; __device__ __forceinline__ void gemm_phase(LAS unsigned char* lds, const Gemm g, const Sched& S, const EpiT& E) {
;     ...
;             PG8_STAGE(PG8_SB(0, 1), b2 + hstep, voffB);
;             PG8_WAIT_V(6); PG8_BAR; PG8_MMA(1, 1, At, B1); PG8_BAR;
;             PG8_LDB(B0, 1, 0); PG8_SCHED; PG8_LDA(At, 1, 0); PG8_STAGE(PG8_SA(0, 1), a2 + hstep, voffA);
;             PG8_WAIT_L(8); PG8_BAR; PG8_WAIT_L(0); PG8_MMA(0, 0, At, B0); PG8_BAR; PG8_SCHED;
;             PG8_LDB(B1, 1, 1); PG8_STAGE(PG8_SB(1, 0), b3, voffB);
;             PG8_BAR; PG8_WAIT_L(0); PG8_MMA(0, 1, At, B1); PG8_BAR;
;             PG8_LDA(At, 1, 1); PG8_STAGE(PG8_SA(1, 0), a3, voffA);
;             PG8_BAR; PG8_WAIT_L(0); PG8_MMA(1, 0, At, B0); PG8_BAR; PG8_SCHED;
	s_add_u32 s44, s44, s21
	s_addc_u32 s45, s45, 0
	s_add_i32 s22, s22, s46
	v_lshl_add_u64 v[242:243], s[44:45], 0, v[0:1]
	s_mov_b32 m0, s22
	global_load_lds_dwordx4 v[242:243], off
	s_add_i32 m0, s22, 0x2000
	v_lshl_add_u64 v[244:245], s[44:45], 0, v[130:131]
	global_load_lds_dwordx4 v[244:245], off
	s_waitcnt vmcnt(6)
	s_barrier
	v_mfma_f32_16x16x32_bf16 v[30:33], v[220:223], v[162:165], v[30:33]
	v_mfma_f32_16x16x32_bf16 v[26:29], v[228:231], v[162:165], v[26:29]
	v_mfma_f32_16x16x32_bf16 v[22:25], v[220:223], v[170:173], v[22:25]
	v_mfma_f32_16x16x32_bf16 v[18:21], v[228:231], v[170:173], v[18:21]
	v_mfma_f32_16x16x32_bf16 v[14:17], v[220:223], v[182:185], v[14:17]
	v_mfma_f32_16x16x32_bf16 v[10:13], v[228:231], v[182:185], v[10:13]
	v_mfma_f32_16x16x32_bf16 v[6:9], v[220:223], v[190:193], v[6:9]
	v_mfma_f32_16x16x32_bf16 v[2:5], v[228:231], v[190:193], v[2:5]
	v_mfma_f32_16x16x32_bf16 v[30:33], v[224:227], v[166:169], v[30:33]
	v_mfma_f32_16x16x32_bf16 v[26:29], v[232:235], v[166:169], v[26:29]
	v_mfma_f32_16x16x32_bf16 v[22:25], v[224:227], v[174:177], v[22:25]
	v_mfma_f32_16x16x32_bf16 v[18:21], v[232:235], v[174:177], v[18:21]
	v_mfma_f32_16x16x32_bf16 v[14:17], v[224:227], v[186:189], v[14:17]
	v_mfma_f32_16x16x32_bf16 v[10:13], v[232:235], v[186:189], v[10:13]
	v_mfma_f32_16x16x32_bf16 v[6:9], v[224:227], v[194:197], v[6:9]
	v_mfma_f32_16x16x32_bf16 v[2:5], v[232:235], v[194:197], v[2:5]
	s_barrier
	s_add_i32 s22, 0, 0x18000
	v_add_u32_e32 v145, s22, v141
	ds_read_b128 v[146:149], v145
	ds_read_b128 v[150:153], v145 offset:1024
	ds_read_b128 v[154:157], v145 offset:2048
	ds_read_b128 v[158:161], v145 offset:3072
	s_add_u32 s38, s38, s21
	s_addc_u32 s39, s39, 0
	s_mov_b32 m0, s51
	v_lshl_add_u64 v[220:221], s[38:39], 0, v[0:1]
	ds_read_b128 v[162:165], v144 offset:32768
	ds_read_b128 v[166:169], v144 offset:33792
	ds_read_b128 v[170:173], v144 offset:34816
	ds_read_b128 v[174:177], v144 offset:35840
	ds_read_b128 v[182:185], v144 offset:36864
	ds_read_b128 v[186:189], v144 offset:37888
	ds_read_b128 v[190:193], v144 offset:38912
	ds_read_b128 v[194:197], v144 offset:39936
	global_load_lds_dwordx4 v[220:221], off
	s_mov_b32 m0, s52
	v_lshl_add_u64 v[220:221], s[38:39], 0, v[130:131]
	global_load_lds_dwordx4 v[220:221], off
	s_waitcnt lgkmcnt(8)
	s_barrier
	s_waitcnt lgkmcnt(0)
	v_mfma_f32_16x16x32_bf16 v[126:129], v[146:149], v[162:165], v[126:129]
	v_mfma_f32_16x16x32_bf16 v[122:125], v[154:157], v[162:165], v[122:125]
	v_mfma_f32_16x16x32_bf16 v[118:121], v[146:149], v[170:173], v[118:121]
	v_mfma_f32_16x16x32_bf16 v[114:117], v[154:157], v[170:173], v[114:117]
	v_mfma_f32_16x16x32_bf16 v[110:113], v[146:149], v[182:185], v[110:113]
	v_mfma_f32_16x16x32_bf16 v[106:109], v[154:157], v[182:185], v[106:109]
	v_mfma_f32_16x16x32_bf16 v[102:105], v[146:149], v[190:193], v[102:105]
	v_mfma_f32_16x16x32_bf16 v[98:101], v[154:157], v[190:193], v[98:101]
	v_mfma_f32_16x16x32_bf16 v[126:129], v[150:153], v[166:169], v[126:129]
	v_mfma_f32_16x16x32_bf16 v[122:125], v[158:161], v[166:169], v[122:125]
	v_mfma_f32_16x16x32_bf16 v[118:121], v[150:153], v[174:177], v[118:121]
	v_mfma_f32_16x16x32_bf16 v[114:117], v[158:161], v[174:177], v[114:117]
	v_mfma_f32_16x16x32_bf16 v[110:113], v[150:153], v[186:189], v[110:113]
	v_mfma_f32_16x16x32_bf16 v[106:109], v[158:161], v[186:189], v[106:109]
	v_mfma_f32_16x16x32_bf16 v[102:105], v[150:153], v[194:197], v[102:105]
	v_mfma_f32_16x16x32_bf16 v[98:101], v[158:161], v[194:197], v[98:101]
	s_barrier
	s_add_i32 s30, 0, 0x1c000
	s_add_i32 s22, s22, s46
	v_add_u32_e32 v145, s30, v141
	v_lshl_add_u64 v[198:199], v[198:199], 0, s[76:77]
	s_mov_b32 m0, s22
	ds_read_b128 v[220:223], v145
	ds_read_b128 v[224:227], v145 offset:1024
	ds_read_b128 v[228:231], v145 offset:2048
	ds_read_b128 v[232:235], v145 offset:3072
	global_load_lds_dwordx4 v[198:199], off
	s_add_i32 m0, s22, 0x2000
	v_lshl_add_u64 v[198:199], v[236:237], 0, s[76:77]
	global_load_lds_dwordx4 v[198:199], off
	s_barrier
	s_waitcnt lgkmcnt(0)
	v_mfma_f32_16x16x32_bf16 v[94:97], v[220:223], v[162:165], v[94:97]
	v_mfma_f32_16x16x32_bf16 v[90:93], v[228:231], v[162:165], v[90:93]
	v_mfma_f32_16x16x32_bf16 v[86:89], v[220:223], v[170:173], v[86:89]
	v_mfma_f32_16x16x32_bf16 v[82:85], v[228:231], v[170:173], v[82:85]
	v_mfma_f32_16x16x32_bf16 v[78:81], v[220:223], v[182:185], v[78:81]
	v_mfma_f32_16x16x32_bf16 v[74:77], v[228:231], v[182:185], v[74:77]
	v_mfma_f32_16x16x32_bf16 v[70:73], v[220:223], v[190:193], v[70:73]
	v_mfma_f32_16x16x32_bf16 v[66:69], v[228:231], v[190:193], v[66:69]
	v_mfma_f32_16x16x32_bf16 v[94:97], v[224:227], v[166:169], v[94:97]
	v_mfma_f32_16x16x32_bf16 v[90:93], v[232:235], v[166:169], v[90:93]
	v_mfma_f32_16x16x32_bf16 v[86:89], v[224:227], v[174:177], v[86:89]
	v_mfma_f32_16x16x32_bf16 v[82:85], v[232:235], v[174:177], v[82:85]
	v_mfma_f32_16x16x32_bf16 v[78:81], v[224:227], v[186:189], v[78:81]
	v_mfma_f32_16x16x32_bf16 v[74:77], v[232:235], v[186:189], v[74:77]
	v_mfma_f32_16x16x32_bf16 v[70:73], v[224:227], v[194:197], v[70:73]
	v_mfma_f32_16x16x32_bf16 v[66:69], v[232:235], v[194:197], v[66:69]
	s_barrier
	s_mov_b32 m0, s53
	v_lshl_add_u64 v[198:199], v[238:239], 0, s[76:77]
	ds_read_b128 v[162:165], v144 offset:49152
	ds_read_b128 v[166:169], v144 offset:50176
	ds_read_b128 v[170:173], v144 offset:51200
	ds_read_b128 v[174:177], v144 offset:52224
	ds_read_b128 v[182:185], v144 offset:53248
	ds_read_b128 v[186:189], v144 offset:54272
	ds_read_b128 v[190:193], v144 offset:55296
	ds_read_b128 v[194:197], v144 offset:56320
	global_load_lds_dwordx4 v[198:199], off
	s_mov_b32 m0, s54
	v_lshl_add_u64 v[198:199], v[240:241], 0, s[76:77]
	global_load_lds_dwordx4 v[198:199], off
	s_barrier
; __device__ __forceinline__ unsigned pk2(float lo, float hi) { unsigned r; asm volatile("v_cvt_pk_bf16_f32 %0, %1, %2" : "=v"(r) : "v"(lo), "v"(hi)); return r; }
; __device__ __forceinline__ float siluf_(float x) { return x * __builtin_amdgcn_rcpf(1.0f + __expf(-x)); }
; #define PG8_STAGE(bufoff, gbase, voff) do { _Pragma("unroll") for (int _i = 0; _i < 2; ++_i) \
;         __builtin_amdgcn_global_load_lds((const unsigned*)((const char*)(gbase) + (voff)[_i]), (LAS unsigned*)(lds + (bufoff) + ldsw + _i * 8192), 16, 0, 0); } while (0)
; #define PG8_MMA(ai, bj, At, Bt) do { __builtin_amdgcn_s_setprio(1); _Pragma("unroll") for (int m = 0; m < 4; ++m) _Pragma("unroll") for (int n = 0; n < 2; ++n) _Pragma("unroll") for (int k = 0; k < 2; ++k) \
;         acc[ai][bj][m][n] = __builtin_amdgcn_mfma_f32_16x16x32_bf16(Bt[n][k], At[m][k], acc[ai][bj][m][n], 0, 0, 0); __builtin_amdgcn_s_setprio(0); } while (0)
; #define PG8_BAR __builtin_amdgcn_s_barrier()
;     template <int mode> __device__ __forceinline__ void run(const f32x4 (&acc)[2][2][4][2], const Unit& u, int wr, int wc, int fr, int fq, const LAS float* sc) const {
;     ...
;         if (mode == 0) {
;             const int col0 = u.pn * HALF + wc * 32 + 8 * fq;
; #pragma unroll
;             for (int ai = 0; ai < 2; ++ai)
; #pragma unroll
;                 for (int m = 0; m < 4; ++m) {
;                     const int row = row0 + ai * HALF + m * 16;
;                     const float s = sc[ai * HALF + wr * 64 + m * 16 + fr];
;                     const f32x4 g0 = acc[ai][0][m][0] * s, u0 = acc[ai][1][m][0] * s, g1 = acc[ai][0][m][1] * s, u1 = acc[ai][1][m][1] * s;
;                     u32x4 w;
;                     w.x = pk2(siluf_(g0[0]) * u0[0], siluf_(g0[1]) * u0[1]); w.y = pk2(siluf_(g0[2]) * u0[2], siluf_(g0[3]) * u0[3]);
;                     w.z = pk2(siluf_(g1[0]) * u1[0], siluf_(g1[1]) * u1[1]); w.w = pk2(siluf_(g1[2]) * u1[2], siluf_(g1[3]) * u1[3]);
;                     *(u32x4*)(ob + (size_t)row * FF + col0) = w;
;                 }
; template <int MODE, class EpiT, class Sched>
; __device__ __forceinline__ void gemm_phase(LAS unsigned char* lds, const Gemm g, const Sched& S, const EpiT& E) {
;     ...
;             PG8_BAR; PG8_WAIT_L(0); PG8_MMA(1, 0, At, B0); PG8_BAR; PG8_SCHED;
;             PG8_STAGE(PG8_SB(1, 1), b3 + hstep, voffB);
;             PG8_WAIT_V(6); PG8_BAR; PG8_MMA(1, 1, At, B1); PG8_BAR;
	s_waitcnt lgkmcnt(0)
	v_mfma_f32_16x16x32_bf16 v[62:65], v[146:149], v[162:165], v[62:65]
	v_mfma_f32_16x16x32_bf16 v[58:61], v[154:157], v[162:165], v[58:61]
	v_mfma_f32_16x16x32_bf16 v[54:57], v[146:149], v[170:173], v[54:57]
	v_mfma_f32_16x16x32_bf16 v[50:53], v[154:157], v[170:173], v[50:53]
	v_mfma_f32_16x16x32_bf16 v[46:49], v[146:149], v[182:185], v[46:49]
	v_mfma_f32_16x16x32_bf16 v[42:45], v[154:157], v[182:185], v[42:45]
	v_mfma_f32_16x16x32_bf16 v[38:41], v[146:149], v[190:193], v[38:41]
	v_mfma_f32_16x16x32_bf16 v[34:37], v[154:157], v[190:193], v[34:37]
	v_mfma_f32_16x16x32_bf16 v[62:65], v[150:153], v[166:169], v[62:65]
	v_mfma_f32_16x16x32_bf16 v[58:61], v[158:161], v[166:169], v[58:61]
	v_mfma_f32_16x16x32_bf16 v[54:57], v[150:153], v[174:177], v[54:57]
	v_mfma_f32_16x16x32_bf16 v[50:53], v[158:161], v[174:177], v[50:53]
	v_mfma_f32_16x16x32_bf16 v[46:49], v[150:153], v[186:189], v[46:49]
	v_mfma_f32_16x16x32_bf16 v[42:45], v[158:161], v[186:189], v[42:45]
	v_mfma_f32_16x16x32_bf16 v[38:41], v[150:153], v[194:197], v[38:41]
	v_mfma_f32_16x16x32_bf16 v[34:37], v[158:161], v[194:197], v[34:37]
	s_barrier
	s_add_i32 s22, s30, s46
	s_mov_b32 m0, s22
	v_lshl_add_u64 v[146:147], v[242:243], 0, s[76:77]
	global_load_lds_dwordx4 v[146:147], off
	s_add_i32 m0, s22, 0x2000
	v_lshl_add_u64 v[146:147], v[244:245], 0, s[76:77]
	global_load_lds_dwordx4 v[146:147], off
	s_waitcnt vmcnt(6)
	s_barrier
	v_mfma_f32_16x16x32_bf16 v[30:33], v[220:223], v[162:165], v[30:33]
	v_mfma_f32_16x16x32_bf16 v[26:29], v[228:231], v[162:165], v[26:29]
	v_mfma_f32_16x16x32_bf16 v[22:25], v[220:223], v[170:173], v[22:25]
	v_mfma_f32_16x16x32_bf16 v[18:21], v[228:231], v[170:173], v[18:21]
	v_mfma_f32_16x16x32_bf16 v[14:17], v[220:223], v[182:185], v[14:17]
	v_mfma_f32_16x16x32_bf16 v[10:13], v[228:231], v[182:185], v[10:13]
	v_mfma_f32_16x16x32_bf16 v[6:9], v[220:223], v[190:193], v[6:9]
	v_mfma_f32_16x16x32_bf16 v[2:5], v[228:231], v[190:193], v[2:5]
	v_mfma_f32_16x16x32_bf16 v[30:33], v[224:227], v[166:169], v[30:33]
	v_mfma_f32_16x16x32_bf16 v[26:29], v[232:235], v[166:169], v[26:29]
	v_mfma_f32_16x16x32_bf16 v[22:25], v[224:227], v[174:177], v[22:25]
	v_mfma_f32_16x16x32_bf16 v[18:21], v[232:235], v[174:177], v[18:21]
	v_mfma_f32_16x16x32_bf16 v[14:17], v[224:227], v[186:189], v[14:17]
	v_mfma_f32_16x16x32_bf16 v[10:13], v[232:235], v[186:189], v[10:13]
	v_mfma_f32_16x16x32_bf16 v[6:9], v[224:227], v[194:197], v[6:9]
	v_mfma_f32_16x16x32_bf16 v[2:5], v[232:235], v[194:197], v[2:5]
	s_barrier
	s_add_u32 s4, s4, 0x100
	s_addc_u32 s5, s5, 0
	v_lshl_add_u64 v[138:139], v[138:139], 0, s[80:81]
	v_lshl_add_u64 v[136:137], v[136:137], 0, s[80:81]
	s_cmp_ge_u32 s23, s16
	s_mov_b32 s22, s23
	s_cbranch_scc0 .LBB0_332
	v_lshl_add_u32 v145, s57, 10, v142
	ds_read_b32 v136, v145
	v_lshl_or_b32 v138, s8, 7, v143
	v_lshl_add_u32 v146, s9, 8, v140
	v_ashrrev_i32_e32 v139, 31, v138
	v_lshlrev_b64 v[138:139], 1, v[138:139]
	s_waitcnt lgkmcnt(0)
	v_pk_mul_f32 v[148:149], v[126:127], v[136:137] op_sel_hi:[1,0]
	v_pk_mul_f32 v[154:155], v[94:95], v[136:137] op_sel_hi:[1,0]
	v_mul_f32_e32 v147, 0xbfb8aa3b, v148
	v_exp_f32_e32 v147, v147
	v_pk_mul_f32 v[150:151], v[128:129], v[136:137] op_sel_hi:[1,0]
	v_pk_mul_f32 v[152:153], v[96:97], v[136:137] op_sel_hi:[1,0]
	v_pk_mul_f32 v[158:159], v[122:123], v[136:137] op_sel_hi:[1,0]
	v_add_f32_e32 v147, 1.0, v147
	v_rcp_f32_e32 v147, v147
	v_pk_mul_f32 v[156:157], v[124:125], v[136:137] op_sel_hi:[1,0]
	v_pk_mul_f32 v[160:161], v[92:93], v[136:137] op_sel_hi:[1,0]
	v_pk_mul_f32 v[136:137], v[90:91], v[136:137] op_sel_hi:[1,0]
	v_mul_f32_e32 v147, v148, v147
	v_mul_f32_e32 v148, 0xbfb8aa3b, v149
	v_exp_f32_e32 v148, v148
	v_mul_f32_e32 v147, v154, v147
	s_and_b64 vcc, exec, s[42:43]
	v_add_f32_e32 v148, 1.0, v148
	v_rcp_f32_e32 v148, v148
	s_nop 0
	v_mul_f32_e32 v148, v149, v148
	v_mul_f32_e32 v148, v155, v148
	v_cvt_pk_bf16_f32 v148, v147, v148
	v_mul_f32_e32 v147, 0xbfb8aa3b, v150
	v_mul_f32_e32 v149, 0xbfb8aa3b, v151
	v_exp_f32_e32 v147, v147
	v_exp_f32_e32 v149, v149
	v_add_f32_e32 v147, 1.0, v147
	v_add_f32_e32 v149, 1.0, v149
	v_rcp_f32_e32 v147, v147
	v_rcp_f32_e32 v149, v149
	v_mul_f32_e32 v147, v150, v147
	v_mul_f32_e32 v149, v151, v149
	v_mul_f32_e32 v147, v152, v147
	v_mul_f32_e32 v149, v153, v149
	v_cvt_pk_bf16_f32 v149, v147, v149
	v_mul_f32_e32 v147, 0xbfb8aa3b, v158
	v_exp_f32_e32 v147, v147
	s_nop 0
	v_add_f32_e32 v147, 1.0, v147
	v_rcp_f32_e32 v147, v147
	s_nop 0
	v_mul_f32_e32 v147, v158, v147
	v_mul_f32_e32 v136, v136, v147
	v_mul_f32_e32 v147, 0xbfb8aa3b, v159
	v_exp_f32_e32 v147, v147
	s_nop 0
	v_add_f32_e32 v147, 1.0, v147
	v_rcp_f32_e32 v147, v147
	s_nop 0
	v_mul_f32_e32 v147, v159, v147
	v_mul_f32_e32 v137, v137, v147
	v_cvt_pk_bf16_f32 v150, v136, v137
	v_mul_f32_e32 v136, 0xbfb8aa3b, v156
	v_mul_f32_e32 v137, 0xbfb8aa3b, v157
	v_exp_f32_e32 v136, v136
	v_exp_f32_e32 v137, v137
	v_or_b32_e32 v147, 16, v146
	v_add_f32_e32 v136, 1.0, v136
	v_add_f32_e32 v137, 1.0, v137
	v_rcp_f32_e32 v136, v136
	v_rcp_f32_e32 v137, v137
	v_mul_f32_e32 v136, v156, v136
	v_mul_f32_e32 v137, v157, v137
	v_mul_f32_e32 v136, v160, v136
	v_mul_f32_e32 v137, v161, v137
	v_cvt_pk_bf16_f32 v151, v136, v137
	v_mov_b64_e32 v[136:137], s[6:7]
	v_mad_i64_i32 v[152:153], s[4:5], v146, s33, v[136:137]
	v_lshl_add_u64 v[152:153], v[152:153], 0, v[138:139]
	global_store_dwordx4 v[152:153], v[148:151], off
	ds_read_b32 v148, v145 offset:64
	s_waitcnt lgkmcnt(0)
; __device__ __forceinline__ unsigned pk2(float lo, float hi) { unsigned r; asm volatile("v_cvt_pk_bf16_f32 %0, %1, %2" : "=v"(r) : "v"(lo), "v"(hi)); return r; }
; __device__ __forceinline__ float siluf_(float x) { return x * __builtin_amdgcn_rcpf(1.0f + __expf(-x)); }
;     template <int mode> __device__ __forceinline__ void run(const f32x4 (&acc)[2][2][4][2], const Unit& u, int wr, int wc, int fr, int fq, const LAS float* sc) const {
;     ...
;         if (mode == 0) {
;             const int col0 = u.pn * HALF + wc * 32 + 8 * fq;
; #pragma unroll
;             for (int ai = 0; ai < 2; ++ai)
; #pragma unroll
;                 for (int m = 0; m < 4; ++m) {
;                     const int row = row0 + ai * HALF + m * 16;
;                     const float s = sc[ai * HALF + wr * 64 + m * 16 + fr];
;                     const f32x4 g0 = acc[ai][0][m][0] * s, u0 = acc[ai][1][m][0] * s, g1 = acc[ai][0][m][1] * s, u1 = acc[ai][1][m][1] * s;
;                     u32x4 w;
;                     w.x = pk2(siluf_(g0[0]) * u0[0], siluf_(g0[1]) * u0[1]); w.y = pk2(siluf_(g0[2]) * u0[2], siluf_(g0[3]) * u0[3]);
;                     w.z = pk2(siluf_(g1[0]) * u1[0], siluf_(g1[1]) * u1[1]); w.w = pk2(siluf_(g1[2]) * u1[2], siluf_(g1[3]) * u1[3]);
;                     *(u32x4*)(ob + (size_t)row * FF + col0) = w;
;                 }
	v_pk_mul_f32 v[152:153], v[118:119], v[148:149] op_sel_hi:[1,0]
	v_pk_mul_f32 v[150:151], v[120:121], v[148:149] op_sel_hi:[1,0]
	v_pk_mul_f32 v[154:155], v[88:89], v[148:149] op_sel_hi:[1,0]
	v_pk_mul_f32 v[156:157], v[86:87], v[148:149] op_sel_hi:[1,0]
	v_pk_mul_f32 v[158:159], v[116:117], v[148:149] op_sel_hi:[1,0]
	v_pk_mul_f32 v[160:161], v[114:115], v[148:149] op_sel_hi:[1,0]
	v_pk_mul_f32 v[162:163], v[84:85], v[148:149] op_sel_hi:[1,0]
	v_pk_mul_f32 v[164:165], v[82:83], v[148:149] op_sel_hi:[1,0]
	v_mul_f32_e32 v148, 0xbfb8aa3b, v152
	v_mul_f32_e32 v149, 0xbfb8aa3b, v153
	v_exp_f32_e32 v148, v148
	v_exp_f32_e32 v149, v149
	v_add_f32_e32 v148, 1.0, v148
	v_add_f32_e32 v149, 1.0, v149
	v_rcp_f32_e32 v148, v148
	v_rcp_f32_e32 v149, v149
	v_mul_f32_e32 v148, v152, v148
	v_mul_f32_e32 v149, v153, v149
	v_mul_f32_e32 v148, v156, v148
	v_mul_f32_e32 v149, v157, v149
	v_cvt_pk_bf16_f32 v148, v148, v149
	v_mul_f32_e32 v149, 0xbfb8aa3b, v150
	v_exp_f32_e32 v149, v149
	v_mul_f32_e32 v152, 0xbfb8aa3b, v159
	v_exp_f32_e32 v152, v152
	v_add_f32_e32 v149, 1.0, v149
	v_rcp_f32_e32 v149, v149
	v_add_f32_e32 v152, 1.0, v152
	v_rcp_f32_e32 v152, v152
	v_mul_f32_e32 v149, v150, v149
	v_mul_f32_e32 v150, 0xbfb8aa3b, v151
	v_exp_f32_e32 v150, v150
	v_mul_f32_e32 v149, v154, v149
	v_mul_f32_e32 v152, v159, v152
	v_mul_f32_e32 v152, v163, v152
	v_add_f32_e32 v150, 1.0, v150
	v_rcp_f32_e32 v150, v150
	s_nop 0
	v_mul_f32_e32 v150, v151, v150
	v_mul_f32_e32 v150, v155, v150
	v_cvt_pk_bf16_f32 v149, v149, v150
	v_mul_f32_e32 v150, 0xbfb8aa3b, v160
	v_mul_f32_e32 v151, 0xbfb8aa3b, v161
	v_exp_f32_e32 v150, v150
	v_exp_f32_e32 v151, v151
	v_add_f32_e32 v150, 1.0, v150
	v_add_f32_e32 v151, 1.0, v151
	v_rcp_f32_e32 v150, v150
	v_rcp_f32_e32 v151, v151
	v_mul_f32_e32 v150, v160, v150
	v_mul_f32_e32 v151, v161, v151
	v_mul_f32_e32 v150, v164, v150
	v_mul_f32_e32 v151, v165, v151
	v_cvt_pk_bf16_f32 v150, v150, v151
	v_mul_f32_e32 v151, 0xbfb8aa3b, v158
	v_exp_f32_e32 v151, v151
	s_nop 0
	v_add_f32_e32 v151, 1.0, v151
	v_rcp_f32_e32 v151, v151
	s_nop 0
	v_mul_f32_e32 v151, v158, v151
	v_mul_f32_e32 v151, v162, v151
	v_cvt_pk_bf16_f32 v151, v151, v152
	v_mad_i64_i32 v[152:153], s[4:5], v147, s33, v[136:137]
	v_lshl_add_u64 v[152:153], v[152:153], 0, v[138:139]
	global_store_dwordx4 v[152:153], v[148:151], off
	ds_read_b32 v148, v145 offset:128
	v_or_b32_e32 v147, 32, v146
	s_waitcnt lgkmcnt(0)
	v_pk_mul_f32 v[152:153], v[110:111], v[148:149] op_sel_hi:[1,0]
	v_pk_mul_f32 v[150:151], v[112:113], v[148:149] op_sel_hi:[1,0]
	v_pk_mul_f32 v[154:155], v[80:81], v[148:149] op_sel_hi:[1,0]
	v_pk_mul_f32 v[156:157], v[78:79], v[148:149] op_sel_hi:[1,0]
	v_pk_mul_f32 v[158:159], v[108:109], v[148:149] op_sel_hi:[1,0]
	v_pk_mul_f32 v[160:161], v[106:107], v[148:149] op_sel_hi:[1,0]
	v_pk_mul_f32 v[162:163], v[76:77], v[148:149] op_sel_hi:[1,0]
	v_pk_mul_f32 v[164:165], v[74:75], v[148:149] op_sel_hi:[1,0]
	v_mul_f32_e32 v148, 0xbfb8aa3b, v152
	v_mul_f32_e32 v149, 0xbfb8aa3b, v153
	v_exp_f32_e32 v148, v148
	v_exp_f32_e32 v149, v149
	v_add_f32_e32 v148, 1.0, v148
	v_add_f32_e32 v149, 1.0, v149
	v_rcp_f32_e32 v148, v148
	v_rcp_f32_e32 v149, v149
	v_mul_f32_e32 v148, v152, v148
	v_mul_f32_e32 v149, v153, v149
	v_mul_f32_e32 v148, v156, v148
	v_mul_f32_e32 v149, v157, v149
	v_cvt_pk_bf16_f32 v148, v148, v149
	v_mul_f32_e32 v149, 0xbfb8aa3b, v150
	v_exp_f32_e32 v149, v149
	v_mul_f32_e32 v152, 0xbfb8aa3b, v159
	v_exp_f32_e32 v152, v152
	v_add_f32_e32 v149, 1.0, v149
	v_rcp_f32_e32 v149, v149
	v_add_f32_e32 v152, 1.0, v152
	v_rcp_f32_e32 v152, v152
	v_mul_f32_e32 v149, v150, v149
	v_mul_f32_e32 v150, 0xbfb8aa3b, v151
	v_exp_f32_e32 v150, v150
	v_mul_f32_e32 v149, v154, v149
	v_mul_f32_e32 v152, v159, v152
	v_mul_f32_e32 v152, v163, v152
	v_add_f32_e32 v150, 1.0, v150
	v_rcp_f32_e32 v150, v150
	s_nop 0
	v_mul_f32_e32 v150, v151, v150
	v_mul_f32_e32 v150, v155, v150
	v_cvt_pk_bf16_f32 v149, v149, v150
	v_mul_f32_e32 v150, 0xbfb8aa3b, v160
	v_mul_f32_e32 v151, 0xbfb8aa3b, v161
	v_exp_f32_e32 v150, v150
	v_exp_f32_e32 v151, v151
	v_add_f32_e32 v150, 1.0, v150
	v_add_f32_e32 v151, 1.0, v151
	v_rcp_f32_e32 v150, v150
	v_rcp_f32_e32 v151, v151
	v_mul_f32_e32 v150, v160, v150
	v_mul_f32_e32 v151, v161, v151
	v_mul_f32_e32 v150, v164, v150
	v_mul_f32_e32 v151, v165, v151
	v_cvt_pk_bf16_f32 v150, v150, v151
	v_mul_f32_e32 v151, 0xbfb8aa3b, v158
	v_exp_f32_e32 v151, v151
	s_nop 0
	v_add_f32_e32 v151, 1.0, v151
	v_rcp_f32_e32 v151, v151
	s_nop 0
	v_mul_f32_e32 v151, v158, v151
	v_mul_f32_e32 v151, v162, v151
	v_cvt_pk_bf16_f32 v151, v151, v152
	v_mad_i64_i32 v[152:153], s[4:5], v147, s33, v[136:137]
	v_lshl_add_u64 v[152:153], v[152:153], 0, v[138:139]
	global_store_dwordx4 v[152:153], v[148:151], off
	ds_read_b32 v148, v145 offset:192
	v_or_b32_e32 v147, 48, v146
	s_waitcnt lgkmcnt(0)
; __device__ __forceinline__ unsigned pk2(float lo, float hi) { unsigned r; asm volatile("v_cvt_pk_bf16_f32 %0, %1, %2" : "=v"(r) : "v"(lo), "v"(hi)); return r; }
; __device__ __forceinline__ float siluf_(float x) { return x * __builtin_amdgcn_rcpf(1.0f + __expf(-x)); }
;     template <int mode> __device__ __forceinline__ void run(const f32x4 (&acc)[2][2][4][2], const Unit& u, int wr, int wc, int fr, int fq, const LAS float* sc) const {
;     ...
;         if (mode == 0) {
;             const int col0 = u.pn * HALF + wc * 32 + 8 * fq;
; #pragma unroll
;             for (int ai = 0; ai < 2; ++ai)
; #pragma unroll
;                 for (int m = 0; m < 4; ++m) {
;                     const int row = row0 + ai * HALF + m * 16;
;                     const float s = sc[ai * HALF + wr * 64 + m * 16 + fr];
;                     const f32x4 g0 = acc[ai][0][m][0] * s, u0 = acc[ai][1][m][0] * s, g1 = acc[ai][0][m][1] * s, u1 = acc[ai][1][m][1] * s;
;                     u32x4 w;
;                     w.x = pk2(siluf_(g0[0]) * u0[0], siluf_(g0[1]) * u0[1]); w.y = pk2(siluf_(g0[2]) * u0[2], siluf_(g0[3]) * u0[3]);
;                     w.z = pk2(siluf_(g1[0]) * u1[0], siluf_(g1[1]) * u1[1]); w.w = pk2(siluf_(g1[2]) * u1[2], siluf_(g1[3]) * u1[3]);
;                     *(u32x4*)(ob + (size_t)row * FF + col0) = w;
;                 }
	v_pk_mul_f32 v[152:153], v[102:103], v[148:149] op_sel_hi:[1,0]
	v_pk_mul_f32 v[150:151], v[104:105], v[148:149] op_sel_hi:[1,0]
	v_pk_mul_f32 v[154:155], v[72:73], v[148:149] op_sel_hi:[1,0]
	v_pk_mul_f32 v[156:157], v[70:71], v[148:149] op_sel_hi:[1,0]
	v_pk_mul_f32 v[158:159], v[100:101], v[148:149] op_sel_hi:[1,0]
	v_pk_mul_f32 v[160:161], v[98:99], v[148:149] op_sel_hi:[1,0]
	v_pk_mul_f32 v[162:163], v[68:69], v[148:149] op_sel_hi:[1,0]
	v_pk_mul_f32 v[164:165], v[66:67], v[148:149] op_sel_hi:[1,0]
	v_mul_f32_e32 v148, 0xbfb8aa3b, v152
	v_mul_f32_e32 v149, 0xbfb8aa3b, v153
	v_exp_f32_e32 v148, v148
	v_exp_f32_e32 v149, v149
	v_add_f32_e32 v148, 1.0, v148
	v_add_f32_e32 v149, 1.0, v149
	v_rcp_f32_e32 v148, v148
	v_rcp_f32_e32 v149, v149
	v_mul_f32_e32 v148, v152, v148
	v_mul_f32_e32 v149, v153, v149
	v_mul_f32_e32 v148, v156, v148
	v_mul_f32_e32 v149, v157, v149
	v_cvt_pk_bf16_f32 v148, v148, v149
	v_mul_f32_e32 v149, 0xbfb8aa3b, v150
	v_exp_f32_e32 v149, v149
	v_mul_f32_e32 v152, 0xbfb8aa3b, v159
	v_exp_f32_e32 v152, v152
	v_add_f32_e32 v149, 1.0, v149
	v_rcp_f32_e32 v149, v149
	v_add_f32_e32 v152, 1.0, v152
	v_rcp_f32_e32 v152, v152
	v_mul_f32_e32 v149, v150, v149
	v_mul_f32_e32 v150, 0xbfb8aa3b, v151
	v_exp_f32_e32 v150, v150
	v_mul_f32_e32 v149, v154, v149
	v_mul_f32_e32 v152, v159, v152
	v_mul_f32_e32 v152, v163, v152
	v_add_f32_e32 v150, 1.0, v150
	v_rcp_f32_e32 v150, v150
	s_nop 0
	v_mul_f32_e32 v150, v151, v150
	v_mul_f32_e32 v150, v155, v150
	v_cvt_pk_bf16_f32 v149, v149, v150
	v_mul_f32_e32 v150, 0xbfb8aa3b, v160
	v_mul_f32_e32 v151, 0xbfb8aa3b, v161
	v_exp_f32_e32 v150, v150
	v_exp_f32_e32 v151, v151
	v_add_f32_e32 v150, 1.0, v150
	v_add_f32_e32 v151, 1.0, v151
	v_rcp_f32_e32 v150, v150
	v_rcp_f32_e32 v151, v151
	v_mul_f32_e32 v150, v160, v150
	v_mul_f32_e32 v151, v161, v151
	v_mul_f32_e32 v150, v164, v150
	v_mul_f32_e32 v151, v165, v151
	v_cvt_pk_bf16_f32 v150, v150, v151
	v_mul_f32_e32 v151, 0xbfb8aa3b, v158
	v_exp_f32_e32 v151, v151
	s_nop 0
	v_add_f32_e32 v151, 1.0, v151
	v_rcp_f32_e32 v151, v151
	s_nop 0
	v_mul_f32_e32 v151, v158, v151
	v_mul_f32_e32 v151, v162, v151
	v_cvt_pk_bf16_f32 v151, v151, v152
	v_mad_i64_i32 v[152:153], s[4:5], v147, s33, v[136:137]
	v_lshl_add_u64 v[152:153], v[152:153], 0, v[138:139]
	global_store_dwordx4 v[152:153], v[148:151], off
	ds_read_b32 v148, v145 offset:512
	v_add_u32_e32 v147, 0x80, v146
	s_waitcnt lgkmcnt(0)
	v_pk_mul_f32 v[152:153], v[62:63], v[148:149] op_sel_hi:[1,0]
	v_pk_mul_f32 v[150:151], v[64:65], v[148:149] op_sel_hi:[1,0]
	v_pk_mul_f32 v[154:155], v[32:33], v[148:149] op_sel_hi:[1,0]
	v_pk_mul_f32 v[156:157], v[30:31], v[148:149] op_sel_hi:[1,0]
	v_pk_mul_f32 v[158:159], v[60:61], v[148:149] op_sel_hi:[1,0]
	v_pk_mul_f32 v[160:161], v[58:59], v[148:149] op_sel_hi:[1,0]
	v_pk_mul_f32 v[162:163], v[28:29], v[148:149] op_sel_hi:[1,0]
	v_pk_mul_f32 v[164:165], v[26:27], v[148:149] op_sel_hi:[1,0]
	v_mul_f32_e32 v148, 0xbfb8aa3b, v152
	v_mul_f32_e32 v149, 0xbfb8aa3b, v153
	v_exp_f32_e32 v148, v148
	v_exp_f32_e32 v149, v149
	v_add_f32_e32 v148, 1.0, v148
	v_add_f32_e32 v149, 1.0, v149
	v_rcp_f32_e32 v148, v148
	v_rcp_f32_e32 v149, v149
	v_mul_f32_e32 v148, v152, v148
	v_mul_f32_e32 v149, v153, v149
	v_mul_f32_e32 v148, v156, v148
	v_mul_f32_e32 v149, v157, v149
	v_cvt_pk_bf16_f32 v148, v148, v149
	v_mul_f32_e32 v149, 0xbfb8aa3b, v150
	v_exp_f32_e32 v149, v149
	v_mul_f32_e32 v152, 0xbfb8aa3b, v159
	v_exp_f32_e32 v152, v152
	v_add_f32_e32 v149, 1.0, v149
	v_rcp_f32_e32 v149, v149
	v_add_f32_e32 v152, 1.0, v152
	v_rcp_f32_e32 v152, v152
	v_mul_f32_e32 v149, v150, v149
	v_mul_f32_e32 v150, 0xbfb8aa3b, v151
	v_exp_f32_e32 v150, v150
	v_mul_f32_e32 v149, v154, v149
	v_mul_f32_e32 v152, v159, v152
	v_mul_f32_e32 v152, v163, v152
	v_add_f32_e32 v150, 1.0, v150
	v_rcp_f32_e32 v150, v150
	s_nop 0
	v_mul_f32_e32 v150, v151, v150
	v_mul_f32_e32 v150, v155, v150
	v_cvt_pk_bf16_f32 v149, v149, v150
	v_mul_f32_e32 v150, 0xbfb8aa3b, v160
	v_mul_f32_e32 v151, 0xbfb8aa3b, v161
	v_exp_f32_e32 v150, v150
	v_exp_f32_e32 v151, v151
	v_add_f32_e32 v150, 1.0, v150
	v_add_f32_e32 v151, 1.0, v151
	v_rcp_f32_e32 v150, v150
	v_rcp_f32_e32 v151, v151
	v_mul_f32_e32 v150, v160, v150
	v_mul_f32_e32 v151, v161, v151
	v_mul_f32_e32 v150, v164, v150
	v_mul_f32_e32 v151, v165, v151
	v_cvt_pk_bf16_f32 v150, v150, v151
	v_mul_f32_e32 v151, 0xbfb8aa3b, v158
	v_exp_f32_e32 v151, v151
	s_nop 0
	v_add_f32_e32 v151, 1.0, v151
	v_rcp_f32_e32 v151, v151
	s_nop 0
	v_mul_f32_e32 v151, v158, v151
	v_mul_f32_e32 v151, v162, v151
	v_cvt_pk_bf16_f32 v151, v151, v152
	v_mad_i64_i32 v[152:153], s[4:5], v147, s33, v[136:137]
	v_lshl_add_u64 v[152:153], v[152:153], 0, v[138:139]
	global_store_dwordx4 v[152:153], v[148:151], off
	ds_read_b32 v148, v145 offset:576
	v_add_u32_e32 v147, 0x90, v146
	s_waitcnt lgkmcnt(0)
; __device__ __forceinline__ unsigned pk2(float lo, float hi) { unsigned r; asm volatile("v_cvt_pk_bf16_f32 %0, %1, %2" : "=v"(r) : "v"(lo), "v"(hi)); return r; }
; __device__ __forceinline__ float siluf_(float x) { return x * __builtin_amdgcn_rcpf(1.0f + __expf(-x)); }
;     template <int mode> __device__ __forceinline__ void run(const f32x4 (&acc)[2][2][4][2], const Unit& u, int wr, int wc, int fr, int fq, const LAS float* sc) const {
;     ...
;         if (mode == 0) {
;             const int col0 = u.pn * HALF + wc * 32 + 8 * fq;
; #pragma unroll
;             for (int ai = 0; ai < 2; ++ai)
; #pragma unroll
;                 for (int m = 0; m < 4; ++m) {
;                     const int row = row0 + ai * HALF + m * 16;
;                     const float s = sc[ai * HALF + wr * 64 + m * 16 + fr];
;                     const f32x4 g0 = acc[ai][0][m][0] * s, u0 = acc[ai][1][m][0] * s, g1 = acc[ai][0][m][1] * s, u1 = acc[ai][1][m][1] * s;
;                     u32x4 w;
;                     w.x = pk2(siluf_(g0[0]) * u0[0], siluf_(g0[1]) * u0[1]); w.y = pk2(siluf_(g0[2]) * u0[2], siluf_(g0[3]) * u0[3]);
;                     w.z = pk2(siluf_(g1[0]) * u1[0], siluf_(g1[1]) * u1[1]); w.w = pk2(siluf_(g1[2]) * u1[2], siluf_(g1[3]) * u1[3]);
;                     *(u32x4*)(ob + (size_t)row * FF + col0) = w;
;                 }
	v_pk_mul_f32 v[152:153], v[54:55], v[148:149] op_sel_hi:[1,0]
	v_pk_mul_f32 v[150:151], v[56:57], v[148:149] op_sel_hi:[1,0]
	v_pk_mul_f32 v[154:155], v[24:25], v[148:149] op_sel_hi:[1,0]
	v_pk_mul_f32 v[156:157], v[22:23], v[148:149] op_sel_hi:[1,0]
	v_pk_mul_f32 v[158:159], v[52:53], v[148:149] op_sel_hi:[1,0]
	v_pk_mul_f32 v[160:161], v[50:51], v[148:149] op_sel_hi:[1,0]
	v_pk_mul_f32 v[162:163], v[20:21], v[148:149] op_sel_hi:[1,0]
	v_pk_mul_f32 v[164:165], v[18:19], v[148:149] op_sel_hi:[1,0]
	v_mul_f32_e32 v148, 0xbfb8aa3b, v152
	v_mul_f32_e32 v149, 0xbfb8aa3b, v153
	v_exp_f32_e32 v148, v148
	v_exp_f32_e32 v149, v149
	v_add_f32_e32 v148, 1.0, v148
	v_add_f32_e32 v149, 1.0, v149
	v_rcp_f32_e32 v148, v148
	v_rcp_f32_e32 v149, v149
	v_mul_f32_e32 v148, v152, v148
	v_mul_f32_e32 v149, v153, v149
	v_mul_f32_e32 v148, v156, v148
	v_mul_f32_e32 v149, v157, v149
	v_cvt_pk_bf16_f32 v148, v148, v149
	v_mul_f32_e32 v149, 0xbfb8aa3b, v150
	v_exp_f32_e32 v149, v149
	v_mul_f32_e32 v152, 0xbfb8aa3b, v159
	v_exp_f32_e32 v152, v152
	v_add_f32_e32 v149, 1.0, v149
	v_rcp_f32_e32 v149, v149
	v_add_f32_e32 v152, 1.0, v152
	v_rcp_f32_e32 v152, v152
	v_mul_f32_e32 v149, v150, v149
	v_mul_f32_e32 v150, 0xbfb8aa3b, v151
	v_exp_f32_e32 v150, v150
	v_mul_f32_e32 v149, v154, v149
	v_mul_f32_e32 v152, v159, v152
	v_mul_f32_e32 v152, v163, v152
	v_add_f32_e32 v150, 1.0, v150
	v_rcp_f32_e32 v150, v150
	s_nop 0
	v_mul_f32_e32 v150, v151, v150
	v_mul_f32_e32 v150, v155, v150
	v_cvt_pk_bf16_f32 v149, v149, v150
	v_mul_f32_e32 v150, 0xbfb8aa3b, v160
	v_mul_f32_e32 v151, 0xbfb8aa3b, v161
	v_exp_f32_e32 v150, v150
	v_exp_f32_e32 v151, v151
	v_add_f32_e32 v150, 1.0, v150
	v_add_f32_e32 v151, 1.0, v151
	v_rcp_f32_e32 v150, v150
	v_rcp_f32_e32 v151, v151
	v_mul_f32_e32 v150, v160, v150
	v_mul_f32_e32 v151, v161, v151
	v_mul_f32_e32 v150, v164, v150
	v_mul_f32_e32 v151, v165, v151
	v_cvt_pk_bf16_f32 v150, v150, v151
	v_mul_f32_e32 v151, 0xbfb8aa3b, v158
	v_exp_f32_e32 v151, v151
	s_nop 0
	v_add_f32_e32 v151, 1.0, v151
	v_rcp_f32_e32 v151, v151
	s_nop 0
	v_mul_f32_e32 v151, v158, v151
	v_mul_f32_e32 v151, v162, v151
	v_cvt_pk_bf16_f32 v151, v151, v152
	v_mad_i64_i32 v[152:153], s[4:5], v147, s33, v[136:137]
	v_lshl_add_u64 v[152:153], v[152:153], 0, v[138:139]
	global_store_dwordx4 v[152:153], v[148:151], off
	ds_read_b32 v148, v145 offset:640
	v_add_u32_e32 v147, 0xa0, v146
	s_waitcnt lgkmcnt(0)
	v_pk_mul_f32 v[152:153], v[46:47], v[148:149] op_sel_hi:[1,0]
	v_pk_mul_f32 v[150:151], v[48:49], v[148:149] op_sel_hi:[1,0]
	v_pk_mul_f32 v[154:155], v[16:17], v[148:149] op_sel_hi:[1,0]
	v_pk_mul_f32 v[156:157], v[14:15], v[148:149] op_sel_hi:[1,0]
	v_pk_mul_f32 v[158:159], v[44:45], v[148:149] op_sel_hi:[1,0]
	v_pk_mul_f32 v[160:161], v[42:43], v[148:149] op_sel_hi:[1,0]
	v_pk_mul_f32 v[162:163], v[12:13], v[148:149] op_sel_hi:[1,0]
	v_pk_mul_f32 v[164:165], v[10:11], v[148:149] op_sel_hi:[1,0]
	v_mul_f32_e32 v148, 0xbfb8aa3b, v152
	v_mul_f32_e32 v149, 0xbfb8aa3b, v153
	v_exp_f32_e32 v148, v148
	v_exp_f32_e32 v149, v149
	v_add_f32_e32 v148, 1.0, v148
	v_add_f32_e32 v149, 1.0, v149
	v_rcp_f32_e32 v148, v148
	v_rcp_f32_e32 v149, v149
	v_mul_f32_e32 v148, v152, v148
	v_mul_f32_e32 v149, v153, v149
	v_mul_f32_e32 v148, v156, v148
	v_mul_f32_e32 v149, v157, v149
	v_cvt_pk_bf16_f32 v148, v148, v149
	v_mul_f32_e32 v149, 0xbfb8aa3b, v150
	v_exp_f32_e32 v149, v149
	v_mul_f32_e32 v152, 0xbfb8aa3b, v159
	v_exp_f32_e32 v152, v152
	v_add_f32_e32 v149, 1.0, v149
	v_rcp_f32_e32 v149, v149
	v_add_f32_e32 v152, 1.0, v152
	v_rcp_f32_e32 v152, v152
	v_mul_f32_e32 v149, v150, v149
	v_mul_f32_e32 v150, 0xbfb8aa3b, v151
	v_exp_f32_e32 v150, v150
	v_mul_f32_e32 v149, v154, v149
	v_mul_f32_e32 v152, v159, v152
	v_mul_f32_e32 v152, v163, v152
	v_add_f32_e32 v150, 1.0, v150
	v_rcp_f32_e32 v150, v150
	s_nop 0
	v_mul_f32_e32 v150, v151, v150
	v_mul_f32_e32 v150, v155, v150
	v_cvt_pk_bf16_f32 v149, v149, v150
	v_mul_f32_e32 v150, 0xbfb8aa3b, v160
	v_mul_f32_e32 v151, 0xbfb8aa3b, v161
	v_exp_f32_e32 v150, v150
	v_exp_f32_e32 v151, v151
	v_add_f32_e32 v150, 1.0, v150
	v_add_f32_e32 v151, 1.0, v151
	v_rcp_f32_e32 v150, v150
	v_rcp_f32_e32 v151, v151
	v_mul_f32_e32 v150, v160, v150
	v_mul_f32_e32 v151, v161, v151
	v_mul_f32_e32 v150, v164, v150
	v_mul_f32_e32 v151, v165, v151
	v_cvt_pk_bf16_f32 v150, v150, v151
	v_mul_f32_e32 v151, 0xbfb8aa3b, v158
	v_exp_f32_e32 v151, v151
	v_add_u32_e32 v164, 0xb0, v146
	v_add_f32_e32 v151, 1.0, v151
	v_rcp_f32_e32 v151, v151
	s_nop 0
	v_mul_f32_e32 v151, v158, v151
	v_mul_f32_e32 v151, v162, v151
	v_cvt_pk_bf16_f32 v151, v151, v152
	ds_read_b32 v146, v145 offset:704
	v_mad_i64_i32 v[152:153], s[4:5], v147, s33, v[136:137]
	v_lshl_add_u64 v[152:153], v[152:153], 0, v[138:139]
	global_store_dwordx4 v[152:153], v[148:151], off
	s_waitcnt lgkmcnt(0)
; __device__ __forceinline__ unsigned pk2(float lo, float hi) { unsigned r; asm volatile("v_cvt_pk_bf16_f32 %0, %1, %2" : "=v"(r) : "v"(lo), "v"(hi)); return r; }
; __device__ __forceinline__ float siluf_(float x) { return x * __builtin_amdgcn_rcpf(1.0f + __expf(-x)); }
;     template <int mode> __device__ __forceinline__ void run(const f32x4 (&acc)[2][2][4][2], const Unit& u, int wr, int wc, int fr, int fq, const LAS float* sc) const {
;     ...
;                     const int row = row0 + ai * HALF + m * 16;
;                     const float s = sc[ai * HALF + wr * 64 + m * 16 + fr];
;                     const f32x4 g0 = acc[ai][0][m][0] * s, u0 = acc[ai][1][m][0] * s, g1 = acc[ai][0][m][1] * s, u1 = acc[ai][1][m][1] * s;
;                     u32x4 w;
;                     w.x = pk2(siluf_(g0[0]) * u0[0], siluf_(g0[1]) * u0[1]); w.y = pk2(siluf_(g0[2]) * u0[2], siluf_(g0[3]) * u0[3]);
;                     w.z = pk2(siluf_(g1[0]) * u1[0], siluf_(g1[1]) * u1[1]); w.w = pk2(siluf_(g1[2]) * u1[2], siluf_(g1[3]) * u1[3]);
;                     *(u32x4*)(ob + (size_t)row * FF + col0) = w;
; template <int MODE, class EpiT, class Sched>
; __device__ __forceinline__ void gemm_phase(LAS unsigned char* lds, const Gemm g, const Sched& S, const EpiT& E) {
;     ...
;         if (!has_next) break;
; #pragma unroll
;         for (int a = 0; a < 2; ++a)
; #pragma unroll
;             for (int b = 0; b < 2; ++b)
; #pragma unroll
;                 for (int m = 0; m < 4; ++m)
; #pragma unroll
;                     for (int n = 0; n < 2; ++n) acc[a][b][m][n] = (f32x4){0.f, 0.f, 0.f, 0.f};
;         cur = nxt; cA = nA; cB = nB; ++ui;
	v_pk_mul_f32 v[152:153], v[8:9], v[146:147] op_sel_hi:[1,0]
	v_pk_mul_f32 v[154:155], v[6:7], v[146:147] op_sel_hi:[1,0]
	v_pk_mul_f32 v[150:151], v[38:39], v[146:147] op_sel_hi:[1,0]
	v_pk_mul_f32 v[148:149], v[40:41], v[146:147] op_sel_hi:[1,0]
	v_pk_mul_f32 v[156:157], v[36:37], v[146:147] op_sel_hi:[1,0]
	v_pk_mul_f32 v[158:159], v[34:35], v[146:147] op_sel_hi:[1,0]
	v_pk_mul_f32 v[160:161], v[4:5], v[146:147] op_sel_hi:[1,0]
	v_pk_mul_f32 v[162:163], v[2:3], v[146:147] op_sel_hi:[1,0]
	v_mul_f32_e32 v145, 0xbfb8aa3b, v150
	v_mul_f32_e32 v146, 0xbfb8aa3b, v151
	v_exp_f32_e32 v145, v145
	v_exp_f32_e32 v146, v146
	v_mul_f32_e32 v147, 0xbfb8aa3b, v149
	v_exp_f32_e32 v147, v147
	v_add_f32_e32 v145, 1.0, v145
	v_add_f32_e32 v146, 1.0, v146
	v_rcp_f32_e32 v145, v145
	v_rcp_f32_e32 v146, v146
	v_add_f32_e32 v147, 1.0, v147
	v_rcp_f32_e32 v147, v147
	v_mul_f32_e32 v145, v150, v145
	v_mul_f32_e32 v146, v151, v146
	v_mul_f32_e32 v145, v154, v145
	v_mul_f32_e32 v146, v155, v146
	v_cvt_pk_bf16_f32 v146, v145, v146
	v_mul_f32_e32 v145, 0xbfb8aa3b, v148
	v_exp_f32_e32 v145, v145
	v_mul_f32_e32 v147, v149, v147
	v_mul_f32_e32 v147, v153, v147
	v_mul_f32_e32 v149, 0xbfb8aa3b, v157
	v_add_f32_e32 v145, 1.0, v145
	v_rcp_f32_e32 v145, v145
	v_exp_f32_e32 v149, v149
	v_mad_i64_i32 v[136:137], s[4:5], v164, s33, v[136:137]
	v_mul_f32_e32 v145, v148, v145
	v_mul_f32_e32 v145, v152, v145
	v_cvt_pk_bf16_f32 v147, v145, v147
	v_mul_f32_e32 v145, 0xbfb8aa3b, v158
	v_mul_f32_e32 v148, 0xbfb8aa3b, v159
	v_exp_f32_e32 v145, v145
	v_exp_f32_e32 v148, v148
	v_add_f32_e32 v149, 1.0, v149
	v_rcp_f32_e32 v149, v149
	v_add_f32_e32 v145, 1.0, v145
	v_add_f32_e32 v148, 1.0, v148
	v_rcp_f32_e32 v145, v145
	v_rcp_f32_e32 v148, v148
	v_mul_f32_e32 v149, v157, v149
	v_mul_f32_e32 v149, v161, v149
	v_mul_f32_e32 v145, v158, v145
	v_mul_f32_e32 v148, v159, v148
	v_mul_f32_e32 v145, v162, v145
	v_mul_f32_e32 v148, v163, v148
	v_cvt_pk_bf16_f32 v148, v145, v148
	v_mul_f32_e32 v145, 0xbfb8aa3b, v156
	v_exp_f32_e32 v145, v145
	v_lshl_add_u64 v[136:137], v[136:137], 0, v[138:139]
	v_add_f32_e32 v145, 1.0, v145
	v_rcp_f32_e32 v145, v145
	s_nop 0
	v_mul_f32_e32 v145, v156, v145
	v_mul_f32_e32 v145, v160, v145
	v_cvt_pk_bf16_f32 v149, v145, v149
	global_store_dwordx4 v[136:137], v[146:149], off
	s_cbranch_vccnz .LBB0_324
	v_mov_b32_e32 v2, 0
	s_mov_b32 s9, s61
	s_mov_b32 s8, s60
	s_mov_b64 s[12:13], s[28:29]
	s_mov_b64 s[10:11], s[34:35]
	s_mov_b32 s57, s2
	v_mov_b32_e32 v3, v2
	v_mov_b32_e32 v4, v2
	v_mov_b32_e32 v5, v2
	v_mov_b32_e32 v6, v2
	v_mov_b32_e32 v7, v2
	v_mov_b32_e32 v8, v2
	v_mov_b32_e32 v9, v2
	v_mov_b32_e32 v10, v2
	v_mov_b32_e32 v11, v2
	v_mov_b32_e32 v12, v2
	v_mov_b32_e32 v13, v2
	v_mov_b32_e32 v14, v2
	v_mov_b32_e32 v15, v2
	v_mov_b32_e32 v16, v2
	v_mov_b32_e32 v17, v2
	v_mov_b32_e32 v18, v2
	v_mov_b32_e32 v19, v2
	v_mov_b32_e32 v20, v2
	v_mov_b32_e32 v21, v2
	v_mov_b32_e32 v22, v2
	v_mov_b32_e32 v23, v2
	v_mov_b32_e32 v24, v2
	v_mov_b32_e32 v25, v2
	v_mov_b32_e32 v26, v2
	v_mov_b32_e32 v27, v2
	v_mov_b32_e32 v28, v2
	v_mov_b32_e32 v29, v2
	v_mov_b32_e32 v30, v2
	v_mov_b32_e32 v31, v2
	v_mov_b32_e32 v32, v2
	v_mov_b32_e32 v33, v2
	v_mov_b32_e32 v34, v2
	v_mov_b32_e32 v35, v2
	v_mov_b32_e32 v36, v2
	v_mov_b32_e32 v37, v2
	v_mov_b32_e32 v38, v2
	v_mov_b32_e32 v39, v2
	v_mov_b32_e32 v40, v2
	v_mov_b32_e32 v41, v2
	v_mov_b32_e32 v42, v2
	v_mov_b32_e32 v43, v2
	v_mov_b32_e32 v44, v2
	v_mov_b32_e32 v45, v2
	v_mov_b32_e32 v46, v2
	v_mov_b32_e32 v47, v2
	v_mov_b32_e32 v48, v2
	v_mov_b32_e32 v49, v2
	v_mov_b32_e32 v50, v2
	v_mov_b32_e32 v51, v2
	v_mov_b32_e32 v52, v2
	v_mov_b32_e32 v53, v2
	v_mov_b32_e32 v54, v2
	v_mov_b32_e32 v55, v2
	v_mov_b32_e32 v56, v2
	v_mov_b32_e32 v57, v2
	v_mov_b32_e32 v58, v2
	v_mov_b32_e32 v59, v2
	v_mov_b32_e32 v60, v2
	v_mov_b32_e32 v61, v2
	v_mov_b32_e32 v62, v2
	v_mov_b32_e32 v63, v2
	v_mov_b32_e32 v64, v2
	v_mov_b32_e32 v65, v2
	v_mov_b32_e32 v66, v2
	v_mov_b32_e32 v67, v2
	v_mov_b32_e32 v68, v2
	v_mov_b32_e32 v69, v2
	v_mov_b32_e32 v70, v2
	v_mov_b32_e32 v71, v2
	v_mov_b32_e32 v72, v2
	v_mov_b32_e32 v73, v2
	v_mov_b32_e32 v74, v2
	v_mov_b32_e32 v75, v2
	v_mov_b32_e32 v76, v2
	v_mov_b32_e32 v77, v2
	v_mov_b32_e32 v78, v2
	v_mov_b32_e32 v79, v2
	v_mov_b32_e32 v80, v2
	v_mov_b32_e32 v81, v2
	v_mov_b32_e32 v82, v2
	v_mov_b32_e32 v83, v2
	v_mov_b32_e32 v84, v2
	v_mov_b32_e32 v85, v2
	v_mov_b32_e32 v86, v2
	v_mov_b32_e32 v87, v2
	v_mov_b32_e32 v88, v2
	v_mov_b32_e32 v89, v2
	v_mov_b32_e32 v90, v2
	v_mov_b32_e32 v91, v2
	v_mov_b32_e32 v92, v2
	v_mov_b32_e32 v93, v2
	v_mov_b32_e32 v94, v2
	v_mov_b32_e32 v95, v2
	v_mov_b32_e32 v96, v2
	v_mov_b32_e32 v97, v2
	v_mov_b32_e32 v98, v2
	v_mov_b32_e32 v99, v2
	v_mov_b32_e32 v100, v2
	v_mov_b32_e32 v101, v2
	v_mov_b32_e32 v102, v2
	v_mov_b32_e32 v103, v2
	v_mov_b32_e32 v104, v2
	v_mov_b32_e32 v105, v2
	v_mov_b32_e32 v106, v2
	v_mov_b32_e32 v107, v2
	v_mov_b32_e32 v108, v2
	v_mov_b32_e32 v109, v2
	v_mov_b32_e32 v110, v2
	v_mov_b32_e32 v111, v2
	v_mov_b32_e32 v112, v2
	v_mov_b32_e32 v113, v2
	v_mov_b32_e32 v114, v2
	v_mov_b32_e32 v115, v2
	v_mov_b32_e32 v116, v2
	v_mov_b32_e32 v117, v2
	v_mov_b32_e32 v118, v2
	v_mov_b32_e32 v119, v2
	v_mov_b32_e32 v120, v2
	v_mov_b32_e32 v121, v2
	v_mov_b32_e32 v122, v2
	v_mov_b32_e32 v123, v2
	v_mov_b32_e32 v124, v2
	v_mov_b32_e32 v125, v2
	v_mov_b32_e32 v126, v2
	v_mov_b32_e32 v127, v2
	v_mov_b32_e32 v128, v2
	v_mov_b32_e32 v129, v2
	s_branch .LBB0_324
